# x20 + removed the redundant s_waitcnt lgkmcnt(0) after s_setprio 1 in every K-loop MFMA segment (already drained before the barrier)
# speedup vs baseline: 1.0042x; 1.0007x over previous
; #define PG8_STAGE(bufoff, gbase, voff) do { _Pragma("unroll") for (int _i = 0; _i < 2; ++_i) \
;         __builtin_amdgcn_global_load_lds((const unsigned*)((const char*)(gbase) + (voff)[_i]), (PG8_LAS unsigned*)(lds + (bufoff) + ldsw + _i * 8192), 16, 0, 0); } while (0)
; #define PG8_LDA(dst, b, h) do { _Pragma("unroll") for (int m = 0; m < 4; ++m) _Pragma("unroll") for (int k = 0; k < 2; ++k) dst[m][k] = *(const PG8_LAS bf16x8*)(lds + PG8_SA(b, h) + aoff + m * 2048 + k * 1024); } while (0)
; #define PG8_LDB(dst, b, h) do { _Pragma("unroll") for (int n = 0; n < 2; ++n) _Pragma("unroll") for (int k = 0; k < 2; ++k) dst[n][k] = *(const PG8_LAS bf16x8*)(lds + PG8_SB(b, h) + boff + n * 2048 + k * 1024); } while (0)
; #define PG8_MMA(ai, bj, At, Bt) do { __builtin_amdgcn_s_setprio(1); _Pragma("unroll") for (int m = 0; m < 4; ++m) _Pragma("unroll") for (int n = 0; n < 2; ++n) _Pragma("unroll") for (int k = 0; k < 2; ++k) \
;         acc[ai][bj][m][n] = __builtin_amdgcn_mfma_f32_16x16x32_bf16(Bt[n][k], At[m][k], acc[ai][bj][m][n], 0, 0, 0); __builtin_amdgcn_s_setprio(0); } while (0)
; #define PG8_BAR __builtin_amdgcn_s_barrier()
; template <class Epi, class Sched, bool ALIGN_EPI = true, bool SP2 = true>
; __device__ __forceinline__ void gemm_phase(PG8_LAS unsigned char* lds, const Gemm g, const Sched& S, const Epi& E, const int tid) {
;     ...
;             PG8_LDB(B0, 0, 0); PG8_LDB(B1, 0, 1); PG8_SCHED; PG8_LDA(At, 0, 0); PG8_STAGE(PG8_SA(1, 1), a1 + hstepA, voffA);
;             PG8_WAIT_V(8); PG8_WAIT_L(0); PG8_BAR; PG8_MMA(0, 0, At, B0); PG8_MMA(0, 1, At, B1); PG8_BAR; PG8_SCHED;
;             PG8_LDA(At, 0, 1); PG8_STAGE(PG8_SB(0, 0), b2, voffB); PG8_STAGE(PG8_SB(0, 1), b2 + hstepB, voffB); PG8_STAGE(PG8_SA(0, 0), a2, voffA);
;             PG8_WAIT_V(8); PG8_WAIT_L(0); PG8_BAR; PG8_MMA(1, 0, At, B0); PG8_MMA(1, 1, At, B1); PG8_BAR; PG8_SCHED;
;             PG8_LDB(B0, 1, 0); PG8_LDB(B1, 1, 1); PG8_SCHED; PG8_LDA(At, 1, 0); PG8_STAGE(PG8_SA(0, 1), a2 + hstepA, voffA);
;             PG8_WAIT_V(8); PG8_WAIT_L(0); PG8_BAR; PG8_MMA(0, 0, At, B0); PG8_MMA(0, 1, At, B1); PG8_BAR; PG8_SCHED;
;             PG8_LDA(At, 1, 1); PG8_STAGE(PG8_SB(1, 0), b3, voffB); PG8_STAGE(PG8_SB(1, 1), b3 + hstepB, voffB); PG8_STAGE(PG8_SA(1, 0), a3, voffA);
;             PG8_WAIT_V(8); PG8_WAIT_L(0); PG8_BAR; PG8_MMA(1, 0, At, B0); PG8_MMA(1, 1, At, B1); PG8_BAR; PG8_SCHED;
.LBB0_381:
	s_add_u32 s25, s62, 0xfff80080
	s_addc_u32 s26, s63, -1
	s_add_i32 s27, 0, 0x10000
	s_cmp_eq_u32 s24, 28
	s_cselect_b32 s69, s18, s26
	s_cselect_b32 s68, s19, s25
	s_cselect_b32 s67, s20, s23
	s_cselect_b32 s66, s21, s22
	s_add_i32 s25, 0, 0x14000
	v_add_u32_e32 v158, s27, v163
	v_add_u32_e32 v165, s25, v163
	ds_read_b128 v[146:149], v158
	ds_read_b128 v[150:153], v158 offset:1024
	ds_read_b128 v[154:157], v158 offset:2048
	ds_read_b128 v[158:161], v158 offset:3072
	ds_read_b128 v[166:169], v165
	ds_read_b128 v[170:173], v165 offset:1024
	ds_read_b128 v[174:177], v165 offset:2048
	ds_read_b128 v[178:181], v165 offset:3072
	v_lshl_add_u64 v[200:201], s[62:63], 0, v[142:143]
	s_add_i32 m0, s82, 0xc000
	ds_read_b128 v[182:185], v164
	ds_read_b128 v[186:189], v164 offset:1024
	ds_read_b128 v[190:193], v164 offset:2048
	ds_read_b128 v[194:197], v164 offset:3072
	ds_read_b128 v[206:209], v164 offset:4096
	ds_read_b128 v[210:213], v164 offset:5120
	ds_read_b128 v[222:225], v164 offset:6144
	ds_read_b128 v[226:229], v164 offset:7168
	global_load_lds_dwordx4 v[200:201], off
	v_lshl_add_u64 v[200:201], s[62:63], 0, v[144:145]
	s_add_i32 m0, s82, 0xe000
	s_nop 0
	global_load_lds_dwordx4 v[200:201], off
	s_waitcnt vmcnt(8)
	s_waitcnt lgkmcnt(0)
	s_barrier
	s_setprio 1
	v_mfma_f32_16x16x32_bf16 v[126:129], v[146:149], v[182:185], v[126:129]
	v_mfma_f32_16x16x32_bf16 v[126:129], v[150:153], v[186:189], v[126:129]
	v_mfma_f32_16x16x32_bf16 v[122:125], v[154:157], v[182:185], v[122:125]
	v_mfma_f32_16x16x32_bf16 v[122:125], v[158:161], v[186:189], v[122:125]
	v_mfma_f32_16x16x32_bf16 v[110:113], v[146:149], v[190:193], v[110:113]
	v_mfma_f32_16x16x32_bf16 v[110:113], v[150:153], v[194:197], v[110:113]
	v_mfma_f32_16x16x32_bf16 v[106:109], v[154:157], v[190:193], v[106:109]
	v_mfma_f32_16x16x32_bf16 v[106:109], v[158:161], v[194:197], v[106:109]
	v_mfma_f32_16x16x32_bf16 v[92:95], v[146:149], v[206:209], v[92:95]
	v_mfma_f32_16x16x32_bf16 v[92:95], v[150:153], v[210:213], v[92:95]
	v_mfma_f32_16x16x32_bf16 v[88:91], v[154:157], v[206:209], v[88:91]
	v_mfma_f32_16x16x32_bf16 v[88:91], v[158:161], v[210:213], v[88:91]
	v_mfma_f32_16x16x32_bf16 v[76:79], v[146:149], v[222:225], v[76:79]
	v_mfma_f32_16x16x32_bf16 v[76:79], v[150:153], v[226:229], v[76:79]
	v_mfma_f32_16x16x32_bf16 v[72:75], v[154:157], v[222:225], v[72:75]
	v_mfma_f32_16x16x32_bf16 v[72:75], v[158:161], v[226:229], v[72:75]
	s_setprio 0
	s_setprio 1
	v_mfma_f32_16x16x32_bf16 v[118:121], v[166:169], v[182:185], v[118:121]
	v_mfma_f32_16x16x32_bf16 v[118:121], v[170:173], v[186:189], v[118:121]
	v_mfma_f32_16x16x32_bf16 v[114:117], v[174:177], v[182:185], v[114:117]
	v_mfma_f32_16x16x32_bf16 v[114:117], v[178:181], v[186:189], v[114:117]
	v_mfma_f32_16x16x32_bf16 v[102:105], v[166:169], v[190:193], v[102:105]
	v_mfma_f32_16x16x32_bf16 v[102:105], v[170:173], v[194:197], v[102:105]
	v_mfma_f32_16x16x32_bf16 v[98:101], v[174:177], v[190:193], v[98:101]
	v_mfma_f32_16x16x32_bf16 v[98:101], v[178:181], v[194:197], v[98:101]
	v_mfma_f32_16x16x32_bf16 v[84:87], v[166:169], v[206:209], v[84:87]
	v_mfma_f32_16x16x32_bf16 v[84:87], v[170:173], v[210:213], v[84:87]
	v_mfma_f32_16x16x32_bf16 v[80:83], v[174:177], v[206:209], v[80:83]
	v_mfma_f32_16x16x32_bf16 v[80:83], v[178:181], v[210:213], v[80:83]
	v_mfma_f32_16x16x32_bf16 v[68:71], v[166:169], v[222:225], v[68:71]
	v_mfma_f32_16x16x32_bf16 v[68:71], v[170:173], v[226:229], v[68:71]
	s_setprio 2
	s_barrier
	v_mfma_f32_16x16x32_bf16 v[64:67], v[174:177], v[222:225], v[64:67]
	v_mfma_f32_16x16x32_bf16 v[64:67], v[178:181], v[226:229], v[64:67]
	s_setprio 0
	s_add_i32 s26, s27, s73
	v_lshl_add_u64 v[200:201], s[66:67], 0, v[132:133]
	s_mov_b32 m0, s26
	ds_read_b128 v[182:185], v164 offset:16384
	ds_read_b128 v[186:189], v164 offset:17408
	ds_read_b128 v[190:193], v164 offset:18432
	ds_read_b128 v[194:197], v164 offset:19456
	ds_read_b128 v[206:209], v164 offset:20480
	ds_read_b128 v[210:213], v164 offset:21504
	ds_read_b128 v[222:225], v164 offset:22528
	ds_read_b128 v[226:229], v164 offset:23552
	global_load_lds_dwordx4 v[200:201], off
	s_add_i32 m0, s26, 0x2000
	s_add_u32 s26, s66, 0x80000
	v_lshl_add_u64 v[202:203], s[66:67], 0, v[136:137]
	s_addc_u32 s27, s67, 0
	s_add_i32 s25, s25, s73
	global_load_lds_dwordx4 v[202:203], off
	v_lshl_add_u64 v[230:231], s[26:27], 0, v[132:133]
	s_mov_b32 m0, s25
	v_lshl_add_u64 v[232:233], s[68:69], 0, v[134:135]
	global_load_lds_dwordx4 v[230:231], off
	v_lshl_add_u64 v[230:231], s[26:27], 0, v[136:137]
	s_add_i32 m0, s25, 0x2000
	s_nop 0
	global_load_lds_dwordx4 v[230:231], off
	v_lshl_add_u64 v[230:231], s[68:69], 0, v[130:131]
	s_mov_b32 m0, s82
	s_nop 0
	global_load_lds_dwordx4 v[230:231], off
	s_mov_b32 m0, s83
	s_nop 0
	global_load_lds_dwordx4 v[232:233], off
	s_waitcnt vmcnt(8)
	s_waitcnt lgkmcnt(0)
	s_barrier
; #define PG8_STAGE(bufoff, gbase, voff) do { _Pragma("unroll") for (int _i = 0; _i < 2; ++_i) \
;         __builtin_amdgcn_global_load_lds((const unsigned*)((const char*)(gbase) + (voff)[_i]), (PG8_LAS unsigned*)(lds + (bufoff) + ldsw + _i * 8192), 16, 0, 0); } while (0)
; #define PG8_LDA(dst, b, h) do { _Pragma("unroll") for (int m = 0; m < 4; ++m) _Pragma("unroll") for (int k = 0; k < 2; ++k) dst[m][k] = *(const PG8_LAS bf16x8*)(lds + PG8_SA(b, h) + aoff + m * 2048 + k * 1024); } while (0)
; #define PG8_LDB(dst, b, h) do { _Pragma("unroll") for (int n = 0; n < 2; ++n) _Pragma("unroll") for (int k = 0; k < 2; ++k) dst[n][k] = *(const PG8_LAS bf16x8*)(lds + PG8_SB(b, h) + boff + n * 2048 + k * 1024); } while (0)
; #define PG8_MMA(ai, bj, At, Bt) do { __builtin_amdgcn_s_setprio(1); _Pragma("unroll") for (int m = 0; m < 4; ++m) _Pragma("unroll") for (int n = 0; n < 2; ++n) _Pragma("unroll") for (int k = 0; k < 2; ++k) \
;         acc[ai][bj][m][n] = __builtin_amdgcn_mfma_f32_16x16x32_bf16(Bt[n][k], At[m][k], acc[ai][bj][m][n], 0, 0, 0); __builtin_amdgcn_s_setprio(0); } while (0)
; #define PG8_BAR __builtin_amdgcn_s_barrier()
; template <class Epi, class Sched, bool ALIGN_EPI = true, bool SP2 = true>
; __device__ __forceinline__ void gemm_phase(PG8_LAS unsigned char* lds, const Gemm g, const Sched& S, const Epi& E, const int tid) {
;     ...
;             PG8_LDB(B0, 0, 0); PG8_LDB(B1, 0, 1); PG8_SCHED; PG8_LDA(At, 0, 0); PG8_STAGE(PG8_SA(1, 1), a1 + hstepA, voffA);
;             PG8_WAIT_V(8); PG8_WAIT_L(0); PG8_BAR; PG8_MMA(0, 0, At, B0); PG8_MMA(0, 1, At, B1); PG8_BAR; PG8_SCHED;
;             PG8_LDA(At, 0, 1); PG8_STAGE(PG8_SB(0, 0), b2, voffB); PG8_STAGE(PG8_SB(0, 1), b2 + hstepB, voffB); PG8_STAGE(PG8_SA(0, 0), a2, voffA);
;             PG8_WAIT_V(8); PG8_WAIT_L(0); PG8_BAR; PG8_MMA(1, 0, At, B0); PG8_MMA(1, 1, At, B1); PG8_BAR; PG8_SCHED;
;             PG8_LDB(B0, 1, 0); PG8_LDB(B1, 1, 1); PG8_SCHED; PG8_LDA(At, 1, 0); PG8_STAGE(PG8_SA(0, 1), a2 + hstepA, voffA);
;             PG8_WAIT_V(8); PG8_WAIT_L(0); PG8_BAR; PG8_MMA(0, 0, At, B0); PG8_MMA(0, 1, At, B1); PG8_BAR; PG8_SCHED;
;             PG8_LDA(At, 1, 1); PG8_STAGE(PG8_SB(1, 0), b3, voffB); PG8_STAGE(PG8_SB(1, 1), b3 + hstepB, voffB); PG8_STAGE(PG8_SA(1, 0), a3, voffA);
;             PG8_WAIT_V(8); PG8_WAIT_L(0); PG8_BAR; PG8_MMA(1, 0, At, B0); PG8_MMA(1, 1, At, B1); PG8_BAR; PG8_SCHED;
	s_setprio 1
	v_mfma_f32_16x16x32_bf16 v[60:63], v[146:149], v[182:185], v[60:63]
	v_mfma_f32_16x16x32_bf16 v[60:63], v[150:153], v[186:189], v[60:63]
	v_mfma_f32_16x16x32_bf16 v[56:59], v[154:157], v[182:185], v[56:59]
	v_mfma_f32_16x16x32_bf16 v[56:59], v[158:161], v[186:189], v[56:59]
	v_mfma_f32_16x16x32_bf16 v[44:47], v[146:149], v[190:193], v[44:47]
	v_mfma_f32_16x16x32_bf16 v[44:47], v[150:153], v[194:197], v[44:47]
	v_mfma_f32_16x16x32_bf16 v[40:43], v[154:157], v[190:193], v[40:43]
	v_mfma_f32_16x16x32_bf16 v[40:43], v[158:161], v[194:197], v[40:43]
	v_mfma_f32_16x16x32_bf16 v[28:31], v[146:149], v[206:209], v[28:31]
	v_mfma_f32_16x16x32_bf16 v[28:31], v[150:153], v[210:213], v[28:31]
	v_mfma_f32_16x16x32_bf16 v[24:27], v[154:157], v[206:209], v[24:27]
	v_mfma_f32_16x16x32_bf16 v[24:27], v[158:161], v[210:213], v[24:27]
	v_mfma_f32_16x16x32_bf16 v[12:15], v[146:149], v[222:225], v[12:15]
	v_mfma_f32_16x16x32_bf16 v[12:15], v[150:153], v[226:229], v[12:15]
	v_mfma_f32_16x16x32_bf16 v[8:11], v[154:157], v[222:225], v[8:11]
	v_mfma_f32_16x16x32_bf16 v[8:11], v[158:161], v[226:229], v[8:11]
	s_setprio 0
	s_setprio 1
	v_mfma_f32_16x16x32_bf16 v[52:55], v[166:169], v[182:185], v[52:55]
	v_mfma_f32_16x16x32_bf16 v[52:55], v[170:173], v[186:189], v[52:55]
	v_mfma_f32_16x16x32_bf16 v[48:51], v[174:177], v[182:185], v[48:51]
	v_mfma_f32_16x16x32_bf16 v[48:51], v[178:181], v[186:189], v[48:51]
	v_mfma_f32_16x16x32_bf16 v[36:39], v[166:169], v[190:193], v[36:39]
	v_mfma_f32_16x16x32_bf16 v[36:39], v[170:173], v[194:197], v[36:39]
	v_mfma_f32_16x16x32_bf16 v[32:35], v[174:177], v[190:193], v[32:35]
	v_mfma_f32_16x16x32_bf16 v[32:35], v[178:181], v[194:197], v[32:35]
	v_mfma_f32_16x16x32_bf16 v[20:23], v[166:169], v[206:209], v[20:23]
	v_mfma_f32_16x16x32_bf16 v[20:23], v[170:173], v[210:213], v[20:23]
	v_mfma_f32_16x16x32_bf16 v[16:19], v[174:177], v[206:209], v[16:19]
	v_mfma_f32_16x16x32_bf16 v[16:19], v[178:181], v[210:213], v[16:19]
	v_mfma_f32_16x16x32_bf16 v[4:7], v[166:169], v[222:225], v[4:7]
	v_mfma_f32_16x16x32_bf16 v[4:7], v[170:173], v[226:229], v[4:7]
	s_setprio 2
	s_barrier
	v_mfma_f32_16x16x32_bf16 v[0:3], v[174:177], v[222:225], v[0:3]
	v_mfma_f32_16x16x32_bf16 v[0:3], v[178:181], v[226:229], v[0:3]
	s_setprio 0
	s_add_i32 s25, 0, 0x18000
	s_add_i32 s28, 0, 0x1c000
	v_add_u32_e32 v158, s25, v163
	v_add_u32_e32 v165, s28, v163
	ds_read_b128 v[146:149], v158
	ds_read_b128 v[150:153], v158 offset:1024
	ds_read_b128 v[154:157], v158 offset:2048
	ds_read_b128 v[158:161], v158 offset:3072
	ds_read_b128 v[166:169], v165
	ds_read_b128 v[170:173], v165 offset:1024
	ds_read_b128 v[174:177], v165 offset:2048
	ds_read_b128 v[178:181], v165 offset:3072
	s_add_u32 s26, s68, 0x80000
	s_addc_u32 s27, s69, 0
	s_mov_b32 m0, s84
	v_lshl_add_u64 v[234:235], s[26:27], 0, v[130:131]
	ds_read_b128 v[182:185], v164 offset:32768
	ds_read_b128 v[186:189], v164 offset:33792
	ds_read_b128 v[190:193], v164 offset:34816
	ds_read_b128 v[194:197], v164 offset:35840
	ds_read_b128 v[206:209], v164 offset:36864
	ds_read_b128 v[210:213], v164 offset:37888
	ds_read_b128 v[222:225], v164 offset:38912
	ds_read_b128 v[226:229], v164 offset:39936
	global_load_lds_dwordx4 v[234:235], off
	v_lshl_add_u64 v[234:235], s[26:27], 0, v[134:135]
	s_mov_b32 m0, s85
	s_nop 0
	global_load_lds_dwordx4 v[234:235], off
	s_waitcnt vmcnt(8)
	s_waitcnt lgkmcnt(0)
	s_barrier
	s_setprio 1
	v_mfma_f32_16x16x32_bf16 v[126:129], v[146:149], v[182:185], v[126:129]
	v_mfma_f32_16x16x32_bf16 v[126:129], v[150:153], v[186:189], v[126:129]
	v_mfma_f32_16x16x32_bf16 v[122:125], v[154:157], v[182:185], v[122:125]
	v_mfma_f32_16x16x32_bf16 v[122:125], v[158:161], v[186:189], v[122:125]
	v_mfma_f32_16x16x32_bf16 v[110:113], v[146:149], v[190:193], v[110:113]
	v_mfma_f32_16x16x32_bf16 v[110:113], v[150:153], v[194:197], v[110:113]
	v_mfma_f32_16x16x32_bf16 v[106:109], v[154:157], v[190:193], v[106:109]
	v_mfma_f32_16x16x32_bf16 v[106:109], v[158:161], v[194:197], v[106:109]
	v_mfma_f32_16x16x32_bf16 v[92:95], v[146:149], v[206:209], v[92:95]
	v_mfma_f32_16x16x32_bf16 v[92:95], v[150:153], v[210:213], v[92:95]
	v_mfma_f32_16x16x32_bf16 v[88:91], v[154:157], v[206:209], v[88:91]
	v_mfma_f32_16x16x32_bf16 v[88:91], v[158:161], v[210:213], v[88:91]
	v_mfma_f32_16x16x32_bf16 v[76:79], v[146:149], v[222:225], v[76:79]
	v_mfma_f32_16x16x32_bf16 v[76:79], v[150:153], v[226:229], v[76:79]
	v_mfma_f32_16x16x32_bf16 v[72:75], v[154:157], v[222:225], v[72:75]
	v_mfma_f32_16x16x32_bf16 v[72:75], v[158:161], v[226:229], v[72:75]
	s_setprio 0
	s_setprio 1
	v_mfma_f32_16x16x32_bf16 v[118:121], v[166:169], v[182:185], v[118:121]
	v_mfma_f32_16x16x32_bf16 v[118:121], v[170:173], v[186:189], v[118:121]
	v_mfma_f32_16x16x32_bf16 v[114:117], v[174:177], v[182:185], v[114:117]
	v_mfma_f32_16x16x32_bf16 v[114:117], v[178:181], v[186:189], v[114:117]
	v_mfma_f32_16x16x32_bf16 v[102:105], v[166:169], v[190:193], v[102:105]
	v_mfma_f32_16x16x32_bf16 v[102:105], v[170:173], v[194:197], v[102:105]
	v_mfma_f32_16x16x32_bf16 v[98:101], v[174:177], v[190:193], v[98:101]
	v_mfma_f32_16x16x32_bf16 v[98:101], v[178:181], v[194:197], v[98:101]
	v_mfma_f32_16x16x32_bf16 v[84:87], v[166:169], v[206:209], v[84:87]
	v_mfma_f32_16x16x32_bf16 v[84:87], v[170:173], v[210:213], v[84:87]
	v_mfma_f32_16x16x32_bf16 v[80:83], v[174:177], v[206:209], v[80:83]
	v_mfma_f32_16x16x32_bf16 v[80:83], v[178:181], v[210:213], v[80:83]
	v_mfma_f32_16x16x32_bf16 v[68:71], v[166:169], v[222:225], v[68:71]
	v_mfma_f32_16x16x32_bf16 v[68:71], v[170:173], v[226:229], v[68:71]
	s_setprio 2
	s_barrier
; #define PG8_STAGE(bufoff, gbase, voff) do { _Pragma("unroll") for (int _i = 0; _i < 2; ++_i) \
;         __builtin_amdgcn_global_load_lds((const unsigned*)((const char*)(gbase) + (voff)[_i]), (PG8_LAS unsigned*)(lds + (bufoff) + ldsw + _i * 8192), 16, 0, 0); } while (0)
; #define PG8_LDA(dst, b, h) do { _Pragma("unroll") for (int m = 0; m < 4; ++m) _Pragma("unroll") for (int k = 0; k < 2; ++k) dst[m][k] = *(const PG8_LAS bf16x8*)(lds + PG8_SA(b, h) + aoff + m * 2048 + k * 1024); } while (0)
; #define PG8_WAIT_V(n) asm volatile("s_waitcnt vmcnt(" #n ")" ::: "memory")
; #define PG8_WAIT_L(n) asm volatile("s_waitcnt lgkmcnt(" #n ")" ::: "memory")
; #define PG8_BAR __builtin_amdgcn_s_barrier()
; template <class Epi, class Sched, bool ALIGN_EPI = true, bool SP2 = true>
; __device__ __forceinline__ void gemm_phase(PG8_LAS unsigned char* lds, const Gemm g, const Sched& S, const Epi& E, const int tid) {
;     ...
;         for (int t = 0; t < nt; t += 2) {
;             const bool last = (t == nt - 2);
;             const char* a1 = cA + (size_t)(t + 1) * kstep;
;             const char* a2 = last ? nA : cA + (size_t)(t + 2) * kstep; const char* b2 = last ? nB : cB + (size_t)(t + 2) * kstep;
;             const char* a3 = a2 + kstep; const char* b3 = b2 + kstep;
;             if (last && has_next) S.a_ready(nxt);
;             if constexpr (SP2) {
;             PG8_LDB(B0, 0, 0); PG8_LDB(B1, 0, 1); PG8_SCHED; PG8_LDA(At, 0, 0); PG8_STAGE(PG8_SA(1, 1), a1 + hstepA, voffA);
;             PG8_WAIT_V(8); PG8_WAIT_L(0); PG8_BAR; PG8_MMA(0, 0, At, B0); PG8_MMA(0, 1, At, B1); PG8_BAR; PG8_SCHED;
;             PG8_LDA(At, 0, 1); PG8_STAGE(PG8_SB(0, 0), b2, voffB); PG8_STAGE(PG8_SB(0, 1), b2 + hstepB, voffB); PG8_STAGE(PG8_SA(0, 0), a2, voffA);
;             PG8_WAIT_V(8); PG8_WAIT_L(0); PG8_BAR; PG8_MMA(1, 0, At, B0); PG8_MMA(1, 1, At, B1); PG8_BAR; PG8_SCHED;
;             PG8_LDB(B0, 1, 0); PG8_LDB(B1, 1, 1); PG8_SCHED; PG8_LDA(At, 1, 0); PG8_STAGE(PG8_SA(0, 1), a2 + hstepA, voffA);
;             PG8_WAIT_V(8); PG8_WAIT_L(0); PG8_BAR; PG8_MMA(0, 0, At, B0); PG8_MMA(0, 1, At, B1); PG8_BAR; PG8_SCHED;
;             PG8_LDA(At, 1, 1); PG8_STAGE(PG8_SB(1, 0), b3, voffB); PG8_STAGE(PG8_SB(1, 1), b3 + hstepB, voffB); PG8_STAGE(PG8_SA(1, 0), a3, voffA);
;             PG8_WAIT_V(8); PG8_WAIT_L(0); PG8_BAR; PG8_MMA(1, 0, At, B0); PG8_MMA(1, 1, At, B1); PG8_BAR; PG8_SCHED;
	v_mfma_f32_16x16x32_bf16 v[64:67], v[174:177], v[222:225], v[64:67]
	v_mfma_f32_16x16x32_bf16 v[64:67], v[178:181], v[226:229], v[64:67]
	s_setprio 0
	s_add_i32 s25, s25, s73
	v_lshl_add_u64 v[200:201], v[200:201], 0, s[4:5]
	s_mov_b32 m0, s25
	ds_read_b128 v[182:185], v164 offset:49152
	ds_read_b128 v[186:189], v164 offset:50176
	ds_read_b128 v[190:193], v164 offset:51200
	ds_read_b128 v[194:197], v164 offset:52224
	ds_read_b128 v[206:209], v164 offset:53248
	ds_read_b128 v[210:213], v164 offset:54272
	ds_read_b128 v[222:225], v164 offset:55296
	ds_read_b128 v[226:229], v164 offset:56320
	global_load_lds_dwordx4 v[200:201], off
	s_add_i32 m0, s25, 0x2000
	s_add_u32 s26, s66, 0x80080
	v_lshl_add_u64 v[200:201], v[202:203], 0, s[4:5]
	s_addc_u32 s27, s67, 0
	s_add_i32 s25, s28, s73
	global_load_lds_dwordx4 v[200:201], off
	v_lshl_add_u64 v[200:201], s[26:27], 0, v[132:133]
	s_mov_b32 m0, s25
	s_nop 0
	global_load_lds_dwordx4 v[200:201], off
	v_lshl_add_u64 v[200:201], s[26:27], 0, v[136:137]
	s_add_i32 m0, s25, 0x2000
	s_nop 0
	global_load_lds_dwordx4 v[200:201], off
	v_lshl_add_u64 v[200:201], v[230:231], 0, s[4:5]
	s_mov_b32 m0, s88
	s_nop 0
	global_load_lds_dwordx4 v[200:201], off
	v_lshl_add_u64 v[200:201], v[232:233], 0, s[4:5]
	s_mov_b32 m0, s89
	s_nop 0
	global_load_lds_dwordx4 v[200:201], off
	s_waitcnt vmcnt(8)
	s_waitcnt lgkmcnt(0)
	s_barrier
	s_setprio 1
	v_mfma_f32_16x16x32_bf16 v[60:63], v[146:149], v[182:185], v[60:63]
	v_mfma_f32_16x16x32_bf16 v[60:63], v[150:153], v[186:189], v[60:63]
	v_mfma_f32_16x16x32_bf16 v[56:59], v[154:157], v[182:185], v[56:59]
	v_mfma_f32_16x16x32_bf16 v[56:59], v[158:161], v[186:189], v[56:59]
	v_mfma_f32_16x16x32_bf16 v[44:47], v[146:149], v[190:193], v[44:47]
	v_mfma_f32_16x16x32_bf16 v[44:47], v[150:153], v[194:197], v[44:47]
	v_mfma_f32_16x16x32_bf16 v[40:43], v[154:157], v[190:193], v[40:43]
	v_mfma_f32_16x16x32_bf16 v[40:43], v[158:161], v[194:197], v[40:43]
	v_mfma_f32_16x16x32_bf16 v[28:31], v[146:149], v[206:209], v[28:31]
	v_mfma_f32_16x16x32_bf16 v[28:31], v[150:153], v[210:213], v[28:31]
	v_mfma_f32_16x16x32_bf16 v[24:27], v[154:157], v[206:209], v[24:27]
	v_mfma_f32_16x16x32_bf16 v[24:27], v[158:161], v[210:213], v[24:27]
	v_mfma_f32_16x16x32_bf16 v[12:15], v[146:149], v[222:225], v[12:15]
	v_mfma_f32_16x16x32_bf16 v[12:15], v[150:153], v[226:229], v[12:15]
	v_mfma_f32_16x16x32_bf16 v[8:11], v[154:157], v[222:225], v[8:11]
	v_mfma_f32_16x16x32_bf16 v[8:11], v[158:161], v[226:229], v[8:11]
	s_setprio 0
	s_setprio 1
	v_mfma_f32_16x16x32_bf16 v[52:55], v[166:169], v[182:185], v[52:55]
	v_mfma_f32_16x16x32_bf16 v[52:55], v[170:173], v[186:189], v[52:55]
	v_mfma_f32_16x16x32_bf16 v[48:51], v[174:177], v[182:185], v[48:51]
	v_mfma_f32_16x16x32_bf16 v[48:51], v[178:181], v[186:189], v[48:51]
	v_mfma_f32_16x16x32_bf16 v[36:39], v[166:169], v[190:193], v[36:39]
	v_mfma_f32_16x16x32_bf16 v[36:39], v[170:173], v[194:197], v[36:39]
	v_mfma_f32_16x16x32_bf16 v[32:35], v[174:177], v[190:193], v[32:35]
	v_mfma_f32_16x16x32_bf16 v[32:35], v[178:181], v[194:197], v[32:35]
	v_mfma_f32_16x16x32_bf16 v[20:23], v[166:169], v[206:209], v[20:23]
	v_mfma_f32_16x16x32_bf16 v[20:23], v[170:173], v[210:213], v[20:23]
	v_mfma_f32_16x16x32_bf16 v[16:19], v[174:177], v[206:209], v[16:19]
	v_mfma_f32_16x16x32_bf16 v[16:19], v[178:181], v[210:213], v[16:19]
	v_mfma_f32_16x16x32_bf16 v[4:7], v[166:169], v[222:225], v[4:7]
	v_mfma_f32_16x16x32_bf16 v[4:7], v[170:173], v[226:229], v[4:7]
	s_setprio 2
	s_barrier
	v_mfma_f32_16x16x32_bf16 v[0:3], v[174:177], v[222:225], v[0:3]
	v_mfma_f32_16x16x32_bf16 v[0:3], v[178:181], v[226:229], v[0:3]
	s_setprio 0
	s_add_i32 s24, s24, 2
	s_add_u32 s62, s62, 0x100
	s_addc_u32 s63, s63, 0
	s_add_u32 s22, s22, 0x100
	s_addc_u32 s23, s23, 0
	s_cmp_gt_u32 s24, 29
	s_cbranch_scc0 .LBB0_381
	s_and_b64 vcc, exec, s[52:53]
	s_cbranch_vccz .LBB0_384
	s_barrier

; #define PG8_STAGE(bufoff, gbase, voff) do { _Pragma("unroll") for (int _i = 0; _i < 2; ++_i) \
;         __builtin_amdgcn_global_load_lds((const unsigned*)((const char*)(gbase) + (voff)[_i]), (PG8_LAS unsigned*)(lds + (bufoff) + ldsw + _i * 8192), 16, 0, 0); } while (0)
; #define PG8_LDA(dst, b, h) do { _Pragma("unroll") for (int m = 0; m < 4; ++m) _Pragma("unroll") for (int k = 0; k < 2; ++k) dst[m][k] = *(const PG8_LAS bf16x8*)(lds + PG8_SA(b, h) + aoff + m * 2048 + k * 1024); } while (0)
; #define PG8_LDB(dst, b, h) do { _Pragma("unroll") for (int n = 0; n < 2; ++n) _Pragma("unroll") for (int k = 0; k < 2; ++k) dst[n][k] = *(const PG8_LAS bf16x8*)(lds + PG8_SB(b, h) + boff + n * 2048 + k * 1024); } while (0)
; #define PG8_MMA(ai, bj, At, Bt) do { __builtin_amdgcn_s_setprio(1); _Pragma("unroll") for (int m = 0; m < 4; ++m) _Pragma("unroll") for (int n = 0; n < 2; ++n) _Pragma("unroll") for (int k = 0; k < 2; ++k) \
;         acc[ai][bj][m][n] = __builtin_amdgcn_mfma_f32_16x16x32_bf16(Bt[n][k], At[m][k], acc[ai][bj][m][n], 0, 0, 0); __builtin_amdgcn_s_setprio(0); } while (0)
; #define PG8_BAR __builtin_amdgcn_s_barrier()
; template <class Epi, class Sched, bool ALIGN_EPI = true, bool SP2 = true>
; __device__ __forceinline__ void gemm_phase(PG8_LAS unsigned char* lds, const Gemm g, const Sched& S, const Epi& E, const int tid) {
;     ...
;             PG8_LDB(B0, 0, 0); PG8_LDB(B1, 0, 1); PG8_SCHED; PG8_LDA(At, 0, 0); PG8_STAGE(PG8_SA(1, 1), a1 + hstepA, voffA);
;             PG8_WAIT_V(8); PG8_WAIT_L(0); PG8_BAR; PG8_MMA(0, 0, At, B0); PG8_MMA(0, 1, At, B1); PG8_BAR; PG8_SCHED;
;             PG8_LDA(At, 0, 1); PG8_STAGE(PG8_SB(0, 0), b2, voffB); PG8_STAGE(PG8_SB(0, 1), b2 + hstepB, voffB); PG8_STAGE(PG8_SA(0, 0), a2, voffA);
;             PG8_WAIT_V(8); PG8_WAIT_L(0); PG8_BAR; PG8_MMA(1, 0, At, B0); PG8_MMA(1, 1, At, B1); PG8_BAR; PG8_SCHED;
;             PG8_LDB(B0, 1, 0); PG8_LDB(B1, 1, 1); PG8_SCHED; PG8_LDA(At, 1, 0); PG8_STAGE(PG8_SA(0, 1), a2 + hstepA, voffA);
;             PG8_WAIT_V(8); PG8_WAIT_L(0); PG8_BAR; PG8_MMA(0, 0, At, B0); PG8_MMA(0, 1, At, B1); PG8_BAR; PG8_SCHED;
;             PG8_LDA(At, 1, 1); PG8_STAGE(PG8_SB(1, 0), b3, voffB); PG8_STAGE(PG8_SB(1, 1), b3 + hstepB, voffB); PG8_STAGE(PG8_SA(1, 0), a3, voffA);
;             PG8_WAIT_V(8); PG8_WAIT_L(0); PG8_BAR; PG8_MMA(1, 0, At, B0); PG8_MMA(1, 1, At, B1); PG8_BAR; PG8_SCHED;
.LBB0_700:
	s_add_i32 s29, s28, 2
	s_add_u32 s40, s42, 0x100
	s_addc_u32 s41, s43, 0
	s_add_i32 s48, 0, 0x10000
	s_cmp_eq_u32 s25, s28
	s_cselect_b32 s47, s71, s41
	s_cselect_b32 s46, s70, s40
	s_cselect_b32 s45, s73, s27
	s_cselect_b32 s44, s72, s26
	s_add_i32 s28, 0, 0x14000
	v_add_u32_e32 v162, s48, v152
	v_add_u32_e32 v178, s28, v152
	ds_read_b128 v[144:147], v162
	ds_read_b128 v[154:157], v162 offset:1024
	ds_read_b128 v[158:161], v162 offset:2048
	ds_read_b128 v[162:165], v162 offset:3072
	ds_read_b128 v[166:169], v178
	ds_read_b128 v[170:173], v178 offset:1024
	ds_read_b128 v[174:177], v178 offset:2048
	ds_read_b128 v[178:181], v178 offset:3072
	v_lshl_add_u64 v[200:201], s[42:43], 0, v[140:141]
	s_add_i32 m0, s89, 0xc000
	ds_read_b128 v[182:185], v153
	ds_read_b128 v[186:189], v153 offset:1024
	ds_read_b128 v[190:193], v153 offset:2048
	ds_read_b128 v[194:197], v153 offset:3072
	ds_read_b128 v[206:209], v153 offset:4096
	ds_read_b128 v[210:213], v153 offset:5120
	ds_read_b128 v[222:225], v153 offset:6144
	ds_read_b128 v[226:229], v153 offset:7168
	global_load_lds_dwordx4 v[200:201], off
	v_lshl_add_u64 v[200:201], s[42:43], 0, v[142:143]
	s_add_i32 m0, s89, 0xe000
	s_nop 0
	global_load_lds_dwordx4 v[200:201], off
	s_waitcnt vmcnt(8)
	s_waitcnt lgkmcnt(0)
	s_barrier
	s_setprio 1
	v_mfma_f32_16x16x32_bf16 v[126:129], v[144:147], v[182:185], v[126:129]
	v_mfma_f32_16x16x32_bf16 v[126:129], v[154:157], v[186:189], v[126:129]
	v_mfma_f32_16x16x32_bf16 v[122:125], v[158:161], v[182:185], v[122:125]
	v_mfma_f32_16x16x32_bf16 v[122:125], v[162:165], v[186:189], v[122:125]
	v_mfma_f32_16x16x32_bf16 v[110:113], v[144:147], v[190:193], v[110:113]
	v_mfma_f32_16x16x32_bf16 v[110:113], v[154:157], v[194:197], v[110:113]
	v_mfma_f32_16x16x32_bf16 v[106:109], v[158:161], v[190:193], v[106:109]
	v_mfma_f32_16x16x32_bf16 v[106:109], v[162:165], v[194:197], v[106:109]
	v_mfma_f32_16x16x32_bf16 v[92:95], v[144:147], v[206:209], v[92:95]
	v_mfma_f32_16x16x32_bf16 v[92:95], v[154:157], v[210:213], v[92:95]
	v_mfma_f32_16x16x32_bf16 v[88:91], v[158:161], v[206:209], v[88:91]
	v_mfma_f32_16x16x32_bf16 v[88:91], v[162:165], v[210:213], v[88:91]
	v_mfma_f32_16x16x32_bf16 v[76:79], v[144:147], v[222:225], v[76:79]
	v_mfma_f32_16x16x32_bf16 v[76:79], v[154:157], v[226:229], v[76:79]
	v_mfma_f32_16x16x32_bf16 v[72:75], v[158:161], v[222:225], v[72:75]
	v_mfma_f32_16x16x32_bf16 v[72:75], v[162:165], v[226:229], v[72:75]
	s_setprio 0
	s_setprio 1
	v_mfma_f32_16x16x32_bf16 v[118:121], v[166:169], v[182:185], v[118:121]
	v_mfma_f32_16x16x32_bf16 v[118:121], v[170:173], v[186:189], v[118:121]
	v_mfma_f32_16x16x32_bf16 v[114:117], v[174:177], v[182:185], v[114:117]
	v_mfma_f32_16x16x32_bf16 v[114:117], v[178:181], v[186:189], v[114:117]
	v_mfma_f32_16x16x32_bf16 v[102:105], v[166:169], v[190:193], v[102:105]
	v_mfma_f32_16x16x32_bf16 v[102:105], v[170:173], v[194:197], v[102:105]
	v_mfma_f32_16x16x32_bf16 v[98:101], v[174:177], v[190:193], v[98:101]
	v_mfma_f32_16x16x32_bf16 v[98:101], v[178:181], v[194:197], v[98:101]
	v_mfma_f32_16x16x32_bf16 v[84:87], v[166:169], v[206:209], v[84:87]
	v_mfma_f32_16x16x32_bf16 v[84:87], v[170:173], v[210:213], v[84:87]
	v_mfma_f32_16x16x32_bf16 v[80:83], v[174:177], v[206:209], v[80:83]
	v_mfma_f32_16x16x32_bf16 v[80:83], v[178:181], v[210:213], v[80:83]
	v_mfma_f32_16x16x32_bf16 v[68:71], v[166:169], v[222:225], v[68:71]
	v_mfma_f32_16x16x32_bf16 v[68:71], v[170:173], v[226:229], v[68:71]
	s_setprio 2
	s_barrier
	v_mfma_f32_16x16x32_bf16 v[64:67], v[174:177], v[222:225], v[64:67]
	v_mfma_f32_16x16x32_bf16 v[64:67], v[178:181], v[226:229], v[64:67]
	s_setprio 0
	s_add_i32 s42, s48, s88
	v_lshl_add_u64 v[200:201], s[44:45], 0, v[132:133]
	s_mov_b32 m0, s42
	ds_read_b128 v[182:185], v153 offset:16384
	ds_read_b128 v[186:189], v153 offset:17408
	ds_read_b128 v[190:193], v153 offset:18432
	ds_read_b128 v[194:197], v153 offset:19456
	ds_read_b128 v[206:209], v153 offset:20480
	ds_read_b128 v[210:213], v153 offset:21504
	ds_read_b128 v[222:225], v153 offset:22528
	ds_read_b128 v[226:229], v153 offset:23552
	global_load_lds_dwordx4 v[200:201], off
	s_add_i32 m0, s42, 0x2000
	s_add_u32 s42, s44, 0x28000
	v_lshl_add_u64 v[202:203], s[44:45], 0, v[136:137]
	s_addc_u32 s43, s45, 0
	s_add_i32 s28, s28, s88
	global_load_lds_dwordx4 v[202:203], off
	v_lshl_add_u64 v[230:231], s[42:43], 0, v[132:133]
	s_mov_b32 m0, s28
	v_lshl_add_u64 v[232:233], s[46:47], 0, v[134:135]
	global_load_lds_dwordx4 v[230:231], off
	v_lshl_add_u64 v[230:231], s[42:43], 0, v[136:137]
	s_add_i32 m0, s28, 0x2000
	s_nop 0
	global_load_lds_dwordx4 v[230:231], off
	v_lshl_add_u64 v[230:231], s[46:47], 0, v[130:131]
	s_mov_b32 m0, s89
	s_nop 0
	global_load_lds_dwordx4 v[230:231], off
	s_mov_b32 m0, s90
	s_nop 0
	global_load_lds_dwordx4 v[232:233], off
	s_waitcnt vmcnt(8)
	s_waitcnt lgkmcnt(0)
	s_barrier
; #define PG8_STAGE(bufoff, gbase, voff) do { _Pragma("unroll") for (int _i = 0; _i < 2; ++_i) \
;         __builtin_amdgcn_global_load_lds((const unsigned*)((const char*)(gbase) + (voff)[_i]), (PG8_LAS unsigned*)(lds + (bufoff) + ldsw + _i * 8192), 16, 0, 0); } while (0)
; #define PG8_LDA(dst, b, h) do { _Pragma("unroll") for (int m = 0; m < 4; ++m) _Pragma("unroll") for (int k = 0; k < 2; ++k) dst[m][k] = *(const PG8_LAS bf16x8*)(lds + PG8_SA(b, h) + aoff + m * 2048 + k * 1024); } while (0)
; #define PG8_LDB(dst, b, h) do { _Pragma("unroll") for (int n = 0; n < 2; ++n) _Pragma("unroll") for (int k = 0; k < 2; ++k) dst[n][k] = *(const PG8_LAS bf16x8*)(lds + PG8_SB(b, h) + boff + n * 2048 + k * 1024); } while (0)
; #define PG8_MMA(ai, bj, At, Bt) do { __builtin_amdgcn_s_setprio(1); _Pragma("unroll") for (int m = 0; m < 4; ++m) _Pragma("unroll") for (int n = 0; n < 2; ++n) _Pragma("unroll") for (int k = 0; k < 2; ++k) \
;         acc[ai][bj][m][n] = __builtin_amdgcn_mfma_f32_16x16x32_bf16(Bt[n][k], At[m][k], acc[ai][bj][m][n], 0, 0, 0); __builtin_amdgcn_s_setprio(0); } while (0)
; #define PG8_BAR __builtin_amdgcn_s_barrier()
; template <class Epi, class Sched, bool ALIGN_EPI = true, bool SP2 = true>
; __device__ __forceinline__ void gemm_phase(PG8_LAS unsigned char* lds, const Gemm g, const Sched& S, const Epi& E, const int tid) {
;     ...
;             PG8_LDB(B0, 0, 0); PG8_LDB(B1, 0, 1); PG8_SCHED; PG8_LDA(At, 0, 0); PG8_STAGE(PG8_SA(1, 1), a1 + hstepA, voffA);
;             PG8_WAIT_V(8); PG8_WAIT_L(0); PG8_BAR; PG8_MMA(0, 0, At, B0); PG8_MMA(0, 1, At, B1); PG8_BAR; PG8_SCHED;
;             PG8_LDA(At, 0, 1); PG8_STAGE(PG8_SB(0, 0), b2, voffB); PG8_STAGE(PG8_SB(0, 1), b2 + hstepB, voffB); PG8_STAGE(PG8_SA(0, 0), a2, voffA);
;             PG8_WAIT_V(8); PG8_WAIT_L(0); PG8_BAR; PG8_MMA(1, 0, At, B0); PG8_MMA(1, 1, At, B1); PG8_BAR; PG8_SCHED;
;             PG8_LDB(B0, 1, 0); PG8_LDB(B1, 1, 1); PG8_SCHED; PG8_LDA(At, 1, 0); PG8_STAGE(PG8_SA(0, 1), a2 + hstepA, voffA);
;             PG8_WAIT_V(8); PG8_WAIT_L(0); PG8_BAR; PG8_MMA(0, 0, At, B0); PG8_MMA(0, 1, At, B1); PG8_BAR; PG8_SCHED;
;             PG8_LDA(At, 1, 1); PG8_STAGE(PG8_SB(1, 0), b3, voffB); PG8_STAGE(PG8_SB(1, 1), b3 + hstepB, voffB); PG8_STAGE(PG8_SA(1, 0), a3, voffA);
;             PG8_WAIT_V(8); PG8_WAIT_L(0); PG8_BAR; PG8_MMA(1, 0, At, B0); PG8_MMA(1, 1, At, B1); PG8_BAR; PG8_SCHED;
	s_setprio 1
	v_mfma_f32_16x16x32_bf16 v[60:63], v[144:147], v[182:185], v[60:63]
	v_mfma_f32_16x16x32_bf16 v[60:63], v[154:157], v[186:189], v[60:63]
	v_mfma_f32_16x16x32_bf16 v[56:59], v[158:161], v[182:185], v[56:59]
	v_mfma_f32_16x16x32_bf16 v[56:59], v[162:165], v[186:189], v[56:59]
	v_mfma_f32_16x16x32_bf16 v[44:47], v[144:147], v[190:193], v[44:47]
	v_mfma_f32_16x16x32_bf16 v[44:47], v[154:157], v[194:197], v[44:47]
	v_mfma_f32_16x16x32_bf16 v[40:43], v[158:161], v[190:193], v[40:43]
	v_mfma_f32_16x16x32_bf16 v[40:43], v[162:165], v[194:197], v[40:43]
	v_mfma_f32_16x16x32_bf16 v[28:31], v[144:147], v[206:209], v[28:31]
	v_mfma_f32_16x16x32_bf16 v[28:31], v[154:157], v[210:213], v[28:31]
	v_mfma_f32_16x16x32_bf16 v[24:27], v[158:161], v[206:209], v[24:27]
	v_mfma_f32_16x16x32_bf16 v[24:27], v[162:165], v[210:213], v[24:27]
	v_mfma_f32_16x16x32_bf16 v[12:15], v[144:147], v[222:225], v[12:15]
	v_mfma_f32_16x16x32_bf16 v[12:15], v[154:157], v[226:229], v[12:15]
	v_mfma_f32_16x16x32_bf16 v[8:11], v[158:161], v[222:225], v[8:11]
	v_mfma_f32_16x16x32_bf16 v[8:11], v[162:165], v[226:229], v[8:11]
	s_setprio 0
	s_setprio 1
	v_mfma_f32_16x16x32_bf16 v[52:55], v[166:169], v[182:185], v[52:55]
	v_mfma_f32_16x16x32_bf16 v[52:55], v[170:173], v[186:189], v[52:55]
	v_mfma_f32_16x16x32_bf16 v[48:51], v[174:177], v[182:185], v[48:51]
	v_mfma_f32_16x16x32_bf16 v[48:51], v[178:181], v[186:189], v[48:51]
	v_mfma_f32_16x16x32_bf16 v[36:39], v[166:169], v[190:193], v[36:39]
	v_mfma_f32_16x16x32_bf16 v[36:39], v[170:173], v[194:197], v[36:39]
	v_mfma_f32_16x16x32_bf16 v[32:35], v[174:177], v[190:193], v[32:35]
	v_mfma_f32_16x16x32_bf16 v[32:35], v[178:181], v[194:197], v[32:35]
	v_mfma_f32_16x16x32_bf16 v[20:23], v[166:169], v[206:209], v[20:23]
	v_mfma_f32_16x16x32_bf16 v[20:23], v[170:173], v[210:213], v[20:23]
	v_mfma_f32_16x16x32_bf16 v[16:19], v[174:177], v[206:209], v[16:19]
	v_mfma_f32_16x16x32_bf16 v[16:19], v[178:181], v[210:213], v[16:19]
	v_mfma_f32_16x16x32_bf16 v[4:7], v[166:169], v[222:225], v[4:7]
	v_mfma_f32_16x16x32_bf16 v[4:7], v[170:173], v[226:229], v[4:7]
	s_setprio 2
	s_barrier
	v_mfma_f32_16x16x32_bf16 v[0:3], v[174:177], v[222:225], v[0:3]
	v_mfma_f32_16x16x32_bf16 v[0:3], v[178:181], v[226:229], v[0:3]
	s_setprio 0
	s_add_i32 s28, 0, 0x18000
	s_add_i32 s48, 0, 0x1c000
	v_add_u32_e32 v162, s28, v152
	v_add_u32_e32 v178, s48, v152
	ds_read_b128 v[144:147], v162
	ds_read_b128 v[154:157], v162 offset:1024
	ds_read_b128 v[158:161], v162 offset:2048
	ds_read_b128 v[162:165], v162 offset:3072
	ds_read_b128 v[166:169], v178
	ds_read_b128 v[170:173], v178 offset:1024
	ds_read_b128 v[174:177], v178 offset:2048
	ds_read_b128 v[178:181], v178 offset:3072
	s_add_u32 s42, s46, 0x150000
	s_addc_u32 s43, s47, 0
	s_mov_b32 m0, s91
	v_lshl_add_u64 v[234:235], s[42:43], 0, v[130:131]
	ds_read_b128 v[182:185], v153 offset:32768
	ds_read_b128 v[186:189], v153 offset:33792
	ds_read_b128 v[190:193], v153 offset:34816
	ds_read_b128 v[194:197], v153 offset:35840
	ds_read_b128 v[206:209], v153 offset:36864
	ds_read_b128 v[210:213], v153 offset:37888
	ds_read_b128 v[222:225], v153 offset:38912
	ds_read_b128 v[226:229], v153 offset:39936
	global_load_lds_dwordx4 v[234:235], off
	v_lshl_add_u64 v[234:235], s[42:43], 0, v[134:135]
	s_mov_b32 m0, s80
	s_nop 0
	global_load_lds_dwordx4 v[234:235], off
	s_waitcnt vmcnt(8)
	s_waitcnt lgkmcnt(0)
	s_barrier
	s_setprio 1
	v_mfma_f32_16x16x32_bf16 v[126:129], v[144:147], v[182:185], v[126:129]
	v_mfma_f32_16x16x32_bf16 v[126:129], v[154:157], v[186:189], v[126:129]
	v_mfma_f32_16x16x32_bf16 v[122:125], v[158:161], v[182:185], v[122:125]
	v_mfma_f32_16x16x32_bf16 v[122:125], v[162:165], v[186:189], v[122:125]
	v_mfma_f32_16x16x32_bf16 v[110:113], v[144:147], v[190:193], v[110:113]
	v_mfma_f32_16x16x32_bf16 v[110:113], v[154:157], v[194:197], v[110:113]
	v_mfma_f32_16x16x32_bf16 v[106:109], v[158:161], v[190:193], v[106:109]
	v_mfma_f32_16x16x32_bf16 v[106:109], v[162:165], v[194:197], v[106:109]
	v_mfma_f32_16x16x32_bf16 v[92:95], v[144:147], v[206:209], v[92:95]
	v_mfma_f32_16x16x32_bf16 v[92:95], v[154:157], v[210:213], v[92:95]
	v_mfma_f32_16x16x32_bf16 v[88:91], v[158:161], v[206:209], v[88:91]
	v_mfma_f32_16x16x32_bf16 v[88:91], v[162:165], v[210:213], v[88:91]
	v_mfma_f32_16x16x32_bf16 v[76:79], v[144:147], v[222:225], v[76:79]
	v_mfma_f32_16x16x32_bf16 v[76:79], v[154:157], v[226:229], v[76:79]
	v_mfma_f32_16x16x32_bf16 v[72:75], v[158:161], v[222:225], v[72:75]
	v_mfma_f32_16x16x32_bf16 v[72:75], v[162:165], v[226:229], v[72:75]
	s_setprio 0
	s_setprio 1
	v_mfma_f32_16x16x32_bf16 v[118:121], v[166:169], v[182:185], v[118:121]
	v_mfma_f32_16x16x32_bf16 v[118:121], v[170:173], v[186:189], v[118:121]
	v_mfma_f32_16x16x32_bf16 v[114:117], v[174:177], v[182:185], v[114:117]
	v_mfma_f32_16x16x32_bf16 v[114:117], v[178:181], v[186:189], v[114:117]
	v_mfma_f32_16x16x32_bf16 v[102:105], v[166:169], v[190:193], v[102:105]
	v_mfma_f32_16x16x32_bf16 v[102:105], v[170:173], v[194:197], v[102:105]
	v_mfma_f32_16x16x32_bf16 v[98:101], v[174:177], v[190:193], v[98:101]
	v_mfma_f32_16x16x32_bf16 v[98:101], v[178:181], v[194:197], v[98:101]
	v_mfma_f32_16x16x32_bf16 v[84:87], v[166:169], v[206:209], v[84:87]
	v_mfma_f32_16x16x32_bf16 v[84:87], v[170:173], v[210:213], v[84:87]
	v_mfma_f32_16x16x32_bf16 v[80:83], v[174:177], v[206:209], v[80:83]
	v_mfma_f32_16x16x32_bf16 v[80:83], v[178:181], v[210:213], v[80:83]
	v_mfma_f32_16x16x32_bf16 v[68:71], v[166:169], v[222:225], v[68:71]
	v_mfma_f32_16x16x32_bf16 v[68:71], v[170:173], v[226:229], v[68:71]
	s_setprio 2
	s_barrier
; #define PG8_STAGE(bufoff, gbase, voff) do { _Pragma("unroll") for (int _i = 0; _i < 2; ++_i) \
;         __builtin_amdgcn_global_load_lds((const unsigned*)((const char*)(gbase) + (voff)[_i]), (PG8_LAS unsigned*)(lds + (bufoff) + ldsw + _i * 8192), 16, 0, 0); } while (0)
; #define PG8_LDA(dst, b, h) do { _Pragma("unroll") for (int m = 0; m < 4; ++m) _Pragma("unroll") for (int k = 0; k < 2; ++k) dst[m][k] = *(const PG8_LAS bf16x8*)(lds + PG8_SA(b, h) + aoff + m * 2048 + k * 1024); } while (0)
; #define PG8_WAIT_V(n) asm volatile("s_waitcnt vmcnt(" #n ")" ::: "memory")
; #define PG8_WAIT_L(n) asm volatile("s_waitcnt lgkmcnt(" #n ")" ::: "memory")
; #define PG8_BAR __builtin_amdgcn_s_barrier()
; template <class Epi, class Sched, bool ALIGN_EPI = true, bool SP2 = true>
; __device__ __forceinline__ void gemm_phase(PG8_LAS unsigned char* lds, const Gemm g, const Sched& S, const Epi& E, const int tid) {
;     ...
;         for (int t = 0; t < nt; t += 2) {
;             const bool last = (t == nt - 2);
;             const char* a1 = cA + (size_t)(t + 1) * kstep;
;             const char* a2 = last ? nA : cA + (size_t)(t + 2) * kstep; const char* b2 = last ? nB : cB + (size_t)(t + 2) * kstep;
;             const char* a3 = a2 + kstep; const char* b3 = b2 + kstep;
;             if (last && has_next) S.a_ready(nxt);
;             if constexpr (SP2) {
;             PG8_LDB(B0, 0, 0); PG8_LDB(B1, 0, 1); PG8_SCHED; PG8_LDA(At, 0, 0); PG8_STAGE(PG8_SA(1, 1), a1 + hstepA, voffA);
;             PG8_WAIT_V(8); PG8_WAIT_L(0); PG8_BAR; PG8_MMA(0, 0, At, B0); PG8_MMA(0, 1, At, B1); PG8_BAR; PG8_SCHED;
;             PG8_LDA(At, 0, 1); PG8_STAGE(PG8_SB(0, 0), b2, voffB); PG8_STAGE(PG8_SB(0, 1), b2 + hstepB, voffB); PG8_STAGE(PG8_SA(0, 0), a2, voffA);
;             PG8_WAIT_V(8); PG8_WAIT_L(0); PG8_BAR; PG8_MMA(1, 0, At, B0); PG8_MMA(1, 1, At, B1); PG8_BAR; PG8_SCHED;
;             PG8_LDB(B0, 1, 0); PG8_LDB(B1, 1, 1); PG8_SCHED; PG8_LDA(At, 1, 0); PG8_STAGE(PG8_SA(0, 1), a2 + hstepA, voffA);
;             PG8_WAIT_V(8); PG8_WAIT_L(0); PG8_BAR; PG8_MMA(0, 0, At, B0); PG8_MMA(0, 1, At, B1); PG8_BAR; PG8_SCHED;
;             PG8_LDA(At, 1, 1); PG8_STAGE(PG8_SB(1, 0), b3, voffB); PG8_STAGE(PG8_SB(1, 1), b3 + hstepB, voffB); PG8_STAGE(PG8_SA(1, 0), a3, voffA);
;             PG8_WAIT_V(8); PG8_WAIT_L(0); PG8_BAR; PG8_MMA(1, 0, At, B0); PG8_MMA(1, 1, At, B1); PG8_BAR; PG8_SCHED;
	v_mfma_f32_16x16x32_bf16 v[64:67], v[174:177], v[222:225], v[64:67]
	v_mfma_f32_16x16x32_bf16 v[64:67], v[178:181], v[226:229], v[64:67]
	s_setprio 0
	s_add_i32 s28, s28, s88
	v_lshl_add_u64 v[200:201], v[200:201], 0, s[4:5]
	s_mov_b32 m0, s28
	ds_read_b128 v[182:185], v153 offset:49152
	ds_read_b128 v[186:189], v153 offset:50176
	ds_read_b128 v[190:193], v153 offset:51200
	ds_read_b128 v[194:197], v153 offset:52224
	ds_read_b128 v[206:209], v153 offset:53248
	ds_read_b128 v[210:213], v153 offset:54272
	ds_read_b128 v[222:225], v153 offset:55296
	ds_read_b128 v[226:229], v153 offset:56320
	global_load_lds_dwordx4 v[200:201], off
	s_add_i32 m0, s28, 0x2000
	s_add_u32 s42, s44, 0x28080
	v_lshl_add_u64 v[200:201], v[202:203], 0, s[4:5]
	s_addc_u32 s43, s45, 0
	s_add_i32 s28, s48, s88
	global_load_lds_dwordx4 v[200:201], off
	v_lshl_add_u64 v[200:201], s[42:43], 0, v[132:133]
	s_mov_b32 m0, s28
	s_nop 0
	global_load_lds_dwordx4 v[200:201], off
	v_lshl_add_u64 v[200:201], s[42:43], 0, v[136:137]
	s_add_i32 m0, s28, 0x2000
	s_nop 0
	global_load_lds_dwordx4 v[200:201], off
	v_lshl_add_u64 v[200:201], v[230:231], 0, s[4:5]
	s_mov_b32 m0, s56
	s_nop 0
	global_load_lds_dwordx4 v[200:201], off
	v_lshl_add_u64 v[200:201], v[232:233], 0, s[4:5]
	s_mov_b32 m0, s57
	s_nop 0
	global_load_lds_dwordx4 v[200:201], off
	s_waitcnt vmcnt(8)
	s_waitcnt lgkmcnt(0)
	s_barrier
	s_setprio 1
	v_mfma_f32_16x16x32_bf16 v[60:63], v[144:147], v[182:185], v[60:63]
	v_mfma_f32_16x16x32_bf16 v[60:63], v[154:157], v[186:189], v[60:63]
	v_mfma_f32_16x16x32_bf16 v[56:59], v[158:161], v[182:185], v[56:59]
	v_mfma_f32_16x16x32_bf16 v[56:59], v[162:165], v[186:189], v[56:59]
	v_mfma_f32_16x16x32_bf16 v[44:47], v[144:147], v[190:193], v[44:47]
	v_mfma_f32_16x16x32_bf16 v[44:47], v[154:157], v[194:197], v[44:47]
	v_mfma_f32_16x16x32_bf16 v[40:43], v[158:161], v[190:193], v[40:43]
	v_mfma_f32_16x16x32_bf16 v[40:43], v[162:165], v[194:197], v[40:43]
	v_mfma_f32_16x16x32_bf16 v[28:31], v[144:147], v[206:209], v[28:31]
	v_mfma_f32_16x16x32_bf16 v[28:31], v[154:157], v[210:213], v[28:31]
	v_mfma_f32_16x16x32_bf16 v[24:27], v[158:161], v[206:209], v[24:27]
	v_mfma_f32_16x16x32_bf16 v[24:27], v[162:165], v[210:213], v[24:27]
	v_mfma_f32_16x16x32_bf16 v[12:15], v[144:147], v[222:225], v[12:15]
	v_mfma_f32_16x16x32_bf16 v[12:15], v[154:157], v[226:229], v[12:15]
	v_mfma_f32_16x16x32_bf16 v[8:11], v[158:161], v[222:225], v[8:11]
	v_mfma_f32_16x16x32_bf16 v[8:11], v[162:165], v[226:229], v[8:11]
	s_setprio 0
	s_setprio 1
	v_mfma_f32_16x16x32_bf16 v[52:55], v[166:169], v[182:185], v[52:55]
	v_mfma_f32_16x16x32_bf16 v[52:55], v[170:173], v[186:189], v[52:55]
	v_mfma_f32_16x16x32_bf16 v[48:51], v[174:177], v[182:185], v[48:51]
	v_mfma_f32_16x16x32_bf16 v[48:51], v[178:181], v[186:189], v[48:51]
	v_mfma_f32_16x16x32_bf16 v[36:39], v[166:169], v[190:193], v[36:39]
	v_mfma_f32_16x16x32_bf16 v[36:39], v[170:173], v[194:197], v[36:39]
	v_mfma_f32_16x16x32_bf16 v[32:35], v[174:177], v[190:193], v[32:35]
	v_mfma_f32_16x16x32_bf16 v[32:35], v[178:181], v[194:197], v[32:35]
	v_mfma_f32_16x16x32_bf16 v[20:23], v[166:169], v[206:209], v[20:23]
	v_mfma_f32_16x16x32_bf16 v[20:23], v[170:173], v[210:213], v[20:23]
	v_mfma_f32_16x16x32_bf16 v[16:19], v[174:177], v[206:209], v[16:19]
	v_mfma_f32_16x16x32_bf16 v[16:19], v[178:181], v[210:213], v[16:19]
	v_mfma_f32_16x16x32_bf16 v[4:7], v[166:169], v[222:225], v[4:7]
	v_mfma_f32_16x16x32_bf16 v[4:7], v[170:173], v[226:229], v[4:7]
	s_setprio 2
	s_barrier
	v_mfma_f32_16x16x32_bf16 v[0:3], v[174:177], v[222:225], v[0:3]
	v_mfma_f32_16x16x32_bf16 v[0:3], v[178:181], v[226:229], v[0:3]
	s_setprio 0
	s_add_u32 s26, s26, 0x100
	s_addc_u32 s27, s27, 0
	s_cmp_ge_i32 s29, s24
	s_mov_b64 s[42:43], s[40:41]
	s_mov_b32 s28, s29
	s_cbranch_scc0 .LBB0_700
	s_and_b64 vcc, exec, s[64:65]
	s_cbranch_vccz .LBB0_703
	s_barrier

; #define PG8_STAGE(bufoff, gbase, voff) do { _Pragma("unroll") for (int _i = 0; _i < 2; ++_i) \
;         __builtin_amdgcn_global_load_lds((const unsigned*)((const char*)(gbase) + (voff)[_i]), (PG8_LAS unsigned*)(lds + (bufoff) + ldsw + _i * 8192), 16, 0, 0); } while (0)
; #define PG8_LDA(dst, b, h) do { _Pragma("unroll") for (int m = 0; m < 4; ++m) _Pragma("unroll") for (int k = 0; k < 2; ++k) dst[m][k] = *(const PG8_LAS bf16x8*)(lds + PG8_SA(b, h) + aoff + m * 2048 + k * 1024); } while (0)
; #define PG8_LDB(dst, b, h) do { _Pragma("unroll") for (int n = 0; n < 2; ++n) _Pragma("unroll") for (int k = 0; k < 2; ++k) dst[n][k] = *(const PG8_LAS bf16x8*)(lds + PG8_SB(b, h) + boff + n * 2048 + k * 1024); } while (0)
; #define PG8_MMA(ai, bj, At, Bt) do { __builtin_amdgcn_s_setprio(1); _Pragma("unroll") for (int m = 0; m < 4; ++m) _Pragma("unroll") for (int n = 0; n < 2; ++n) _Pragma("unroll") for (int k = 0; k < 2; ++k) \
;         acc[ai][bj][m][n] = __builtin_amdgcn_mfma_f32_16x16x32_bf16(Bt[n][k], At[m][k], acc[ai][bj][m][n], 0, 0, 0); __builtin_amdgcn_s_setprio(0); } while (0)
; #define PG8_BAR __builtin_amdgcn_s_barrier()
; template <class Epi, class Sched, bool ALIGN_EPI = true, bool SP2 = true>
; __device__ __forceinline__ void gemm_phase(PG8_LAS unsigned char* lds, const Gemm g, const Sched& S, const Epi& E, const int tid) {
;     ...
;             PG8_LDB(B0, 0, 0); PG8_LDB(B1, 0, 1); PG8_SCHED; PG8_LDA(At, 0, 0); PG8_STAGE(PG8_SA(1, 1), a1 + hstepA, voffA);
;             PG8_WAIT_V(8); PG8_WAIT_L(0); PG8_BAR; PG8_MMA(0, 0, At, B0); PG8_MMA(0, 1, At, B1); PG8_BAR; PG8_SCHED;
;             PG8_LDA(At, 0, 1); PG8_STAGE(PG8_SB(0, 0), b2, voffB); PG8_STAGE(PG8_SB(0, 1), b2 + hstepB, voffB); PG8_STAGE(PG8_SA(0, 0), a2, voffA);
;             PG8_WAIT_V(8); PG8_WAIT_L(0); PG8_BAR; PG8_MMA(1, 0, At, B0); PG8_MMA(1, 1, At, B1); PG8_BAR; PG8_SCHED;
;             PG8_LDB(B0, 1, 0); PG8_LDB(B1, 1, 1); PG8_SCHED; PG8_LDA(At, 1, 0); PG8_STAGE(PG8_SA(0, 1), a2 + hstepA, voffA);
;             PG8_WAIT_V(8); PG8_WAIT_L(0); PG8_BAR; PG8_MMA(0, 0, At, B0); PG8_MMA(0, 1, At, B1); PG8_BAR; PG8_SCHED;
;             PG8_LDA(At, 1, 1); PG8_STAGE(PG8_SB(1, 0), b3, voffB); PG8_STAGE(PG8_SB(1, 1), b3 + hstepB, voffB); PG8_STAGE(PG8_SA(1, 0), a3, voffA);
;             PG8_WAIT_V(8); PG8_WAIT_L(0); PG8_BAR; PG8_MMA(1, 0, At, B0); PG8_MMA(1, 1, At, B1); PG8_BAR; PG8_SCHED;
.LBB0_1039:
	s_add_i32 s29, s28, 2
	s_add_u32 s30, s62, 0xfff80080
	s_addc_u32 s31, s63, -1
	s_add_i32 s53, 0, 0x10000
	s_cmp_eq_u32 s17, s28
	s_cselect_b32 s67, s57, s31
	s_cselect_b32 s66, s56, s30
	s_cselect_b32 s65, s59, s27
	s_cselect_b32 s64, s58, s25
	s_add_i32 s28, 0, 0x14000
	v_add_u32_e32 v142, s53, v159
	v_add_u32_e32 v163, s28, v159
	ds_read_b128 v[130:133], v142
	ds_read_b128 v[134:137], v142 offset:1024
	ds_read_b128 v[138:141], v142 offset:2048
	ds_read_b128 v[142:145], v142 offset:3072
	ds_read_b128 v[154:157], v163
	ds_read_b128 v[164:167], v163 offset:1024
	ds_read_b128 v[168:171], v163 offset:2048
	ds_read_b128 v[172:175], v163 offset:3072
	v_lshl_add_u64 v[196:197], s[62:63], 0, v[150:151]
	s_add_i32 m0, s23, 0xc000
	ds_read_b128 v[176:179], v162
	ds_read_b128 v[180:183], v162 offset:1024
	ds_read_b128 v[184:187], v162 offset:2048
	ds_read_b128 v[188:191], v162 offset:3072
	ds_read_b128 v[192:195], v162 offset:4096
	ds_read_b128 v[200:203], v162 offset:5120
	ds_read_b128 v[206:209], v162 offset:6144
	ds_read_b128 v[210:213], v162 offset:7168
	global_load_lds_dwordx4 v[196:197], off
	v_lshl_add_u64 v[196:197], s[62:63], 0, v[152:153]
	s_add_i32 m0, s23, 0xe000
	s_nop 0
	global_load_lds_dwordx4 v[196:197], off
	s_waitcnt vmcnt(8)
	s_waitcnt lgkmcnt(0)
	s_barrier
	s_setprio 1
	v_mfma_f32_16x16x32_bf16 v[126:129], v[130:133], v[176:179], v[126:129]
	v_mfma_f32_16x16x32_bf16 v[122:125], v[138:141], v[176:179], v[122:125]
	v_mfma_f32_16x16x32_bf16 v[110:113], v[130:133], v[184:187], v[110:113]
	v_mfma_f32_16x16x32_bf16 v[106:109], v[138:141], v[184:187], v[106:109]
	v_mfma_f32_16x16x32_bf16 v[92:95], v[130:133], v[192:195], v[92:95]
	v_mfma_f32_16x16x32_bf16 v[88:91], v[138:141], v[192:195], v[88:91]
	v_mfma_f32_16x16x32_bf16 v[76:79], v[130:133], v[206:209], v[76:79]
	v_mfma_f32_16x16x32_bf16 v[72:75], v[138:141], v[206:209], v[72:75]
	v_mfma_f32_16x16x32_bf16 v[126:129], v[134:137], v[180:183], v[126:129]
	v_mfma_f32_16x16x32_bf16 v[122:125], v[142:145], v[180:183], v[122:125]
	v_mfma_f32_16x16x32_bf16 v[110:113], v[134:137], v[188:191], v[110:113]
	v_mfma_f32_16x16x32_bf16 v[106:109], v[142:145], v[188:191], v[106:109]
	v_mfma_f32_16x16x32_bf16 v[92:95], v[134:137], v[200:203], v[92:95]
	v_mfma_f32_16x16x32_bf16 v[88:91], v[142:145], v[200:203], v[88:91]
	v_mfma_f32_16x16x32_bf16 v[76:79], v[134:137], v[210:213], v[76:79]
	v_mfma_f32_16x16x32_bf16 v[72:75], v[142:145], v[210:213], v[72:75]
	s_setprio 0
	s_setprio 1
	v_mfma_f32_16x16x32_bf16 v[118:121], v[154:157], v[176:179], v[118:121]
	v_mfma_f32_16x16x32_bf16 v[114:117], v[168:171], v[176:179], v[114:117]
	v_mfma_f32_16x16x32_bf16 v[102:105], v[154:157], v[184:187], v[102:105]
	v_mfma_f32_16x16x32_bf16 v[98:101], v[168:171], v[184:187], v[98:101]
	v_mfma_f32_16x16x32_bf16 v[84:87], v[154:157], v[192:195], v[84:87]
	v_mfma_f32_16x16x32_bf16 v[80:83], v[168:171], v[192:195], v[80:83]
	v_mfma_f32_16x16x32_bf16 v[68:71], v[154:157], v[206:209], v[68:71]
	v_mfma_f32_16x16x32_bf16 v[64:67], v[168:171], v[206:209], v[64:67]
	v_mfma_f32_16x16x32_bf16 v[118:121], v[164:167], v[180:183], v[118:121]
	v_mfma_f32_16x16x32_bf16 v[114:117], v[172:175], v[180:183], v[114:117]
	v_mfma_f32_16x16x32_bf16 v[102:105], v[164:167], v[188:191], v[102:105]
	v_mfma_f32_16x16x32_bf16 v[98:101], v[172:175], v[188:191], v[98:101]
	v_mfma_f32_16x16x32_bf16 v[84:87], v[164:167], v[200:203], v[84:87]
	v_mfma_f32_16x16x32_bf16 v[80:83], v[172:175], v[200:203], v[80:83]
	v_mfma_f32_16x16x32_bf16 v[68:71], v[164:167], v[210:213], v[68:71]
	v_mfma_f32_16x16x32_bf16 v[64:67], v[172:175], v[210:213], v[64:67]
	s_setprio 0
	s_barrier
	s_add_i32 s30, s53, s22
	v_lshl_add_u64 v[196:197], s[64:65], 0, v[146:147]
	s_mov_b32 m0, s30
	ds_read_b128 v[176:179], v162 offset:16384
	ds_read_b128 v[180:183], v162 offset:17408
	ds_read_b128 v[184:187], v162 offset:18432
	ds_read_b128 v[188:191], v162 offset:19456
	ds_read_b128 v[192:195], v162 offset:20480
	ds_read_b128 v[200:203], v162 offset:21504
	ds_read_b128 v[206:209], v162 offset:22528
	ds_read_b128 v[210:213], v162 offset:23552
	global_load_lds_dwordx4 v[196:197], off
	s_add_i32 m0, s30, 0x2000
	s_add_u32 s84, s64, 0x80000
	v_lshl_add_u64 v[222:223], s[64:65], 0, v[148:149]
	s_addc_u32 s85, s65, 0
	s_add_i32 s28, s28, s22
	global_load_lds_dwordx4 v[222:223], off
	v_lshl_add_u64 v[224:225], s[84:85], 0, v[146:147]
	s_mov_b32 m0, s28
	v_lshl_add_u64 v[226:227], s[66:67], 0, v[148:149]
	global_load_lds_dwordx4 v[224:225], off
	v_lshl_add_u64 v[224:225], s[84:85], 0, v[148:149]
	s_add_i32 m0, s28, 0x2000
	s_nop 0
	global_load_lds_dwordx4 v[224:225], off
	v_lshl_add_u64 v[224:225], s[66:67], 0, v[146:147]
	s_mov_b32 m0, s23
	s_nop 0
	global_load_lds_dwordx4 v[224:225], off
	s_mov_b32 m0, s68
	s_nop 0
	global_load_lds_dwordx4 v[226:227], off
	s_waitcnt vmcnt(8)
	s_waitcnt lgkmcnt(0)
	s_barrier
; #define PG8_STAGE(bufoff, gbase, voff) do { _Pragma("unroll") for (int _i = 0; _i < 2; ++_i) \
;         __builtin_amdgcn_global_load_lds((const unsigned*)((const char*)(gbase) + (voff)[_i]), (PG8_LAS unsigned*)(lds + (bufoff) + ldsw + _i * 8192), 16, 0, 0); } while (0)
; #define PG8_LDA(dst, b, h) do { _Pragma("unroll") for (int m = 0; m < 4; ++m) _Pragma("unroll") for (int k = 0; k < 2; ++k) dst[m][k] = *(const PG8_LAS bf16x8*)(lds + PG8_SA(b, h) + aoff + m * 2048 + k * 1024); } while (0)
; #define PG8_LDB(dst, b, h) do { _Pragma("unroll") for (int n = 0; n < 2; ++n) _Pragma("unroll") for (int k = 0; k < 2; ++k) dst[n][k] = *(const PG8_LAS bf16x8*)(lds + PG8_SB(b, h) + boff + n * 2048 + k * 1024); } while (0)
; #define PG8_MMA(ai, bj, At, Bt) do { __builtin_amdgcn_s_setprio(1); _Pragma("unroll") for (int m = 0; m < 4; ++m) _Pragma("unroll") for (int n = 0; n < 2; ++n) _Pragma("unroll") for (int k = 0; k < 2; ++k) \
;         acc[ai][bj][m][n] = __builtin_amdgcn_mfma_f32_16x16x32_bf16(Bt[n][k], At[m][k], acc[ai][bj][m][n], 0, 0, 0); __builtin_amdgcn_s_setprio(0); } while (0)
; template <class Epi, class Sched, bool ALIGN_EPI = true, bool SP2 = true>
; __device__ __forceinline__ void gemm_phase(PG8_LAS unsigned char* lds, const Gemm g, const Sched& S, const Epi& E, const int tid) {
;     ...
;             if constexpr (SP2) {
;             PG8_LDB(B0, 0, 0); PG8_LDB(B1, 0, 1); PG8_SCHED; PG8_LDA(At, 0, 0); PG8_STAGE(PG8_SA(1, 1), a1 + hstepA, voffA);
;             PG8_WAIT_V(8); PG8_WAIT_L(0); PG8_BAR; PG8_MMA(0, 0, At, B0); PG8_MMA(0, 1, At, B1); PG8_BAR; PG8_SCHED;
;             PG8_LDA(At, 0, 1); PG8_STAGE(PG8_SB(0, 0), b2, voffB); PG8_STAGE(PG8_SB(0, 1), b2 + hstepB, voffB); PG8_STAGE(PG8_SA(0, 0), a2, voffA);
;             PG8_WAIT_V(8); PG8_WAIT_L(0); PG8_BAR; PG8_MMA(1, 0, At, B0); PG8_MMA(1, 1, At, B1); PG8_BAR; PG8_SCHED;
;             PG8_LDB(B0, 1, 0); PG8_LDB(B1, 1, 1); PG8_SCHED; PG8_LDA(At, 1, 0); PG8_STAGE(PG8_SA(0, 1), a2 + hstepA, voffA);
;             PG8_WAIT_V(8); PG8_WAIT_L(0); PG8_BAR; PG8_MMA(0, 0, At, B0); PG8_MMA(0, 1, At, B1); PG8_BAR; PG8_SCHED;
;             PG8_LDA(At, 1, 1); PG8_STAGE(PG8_SB(1, 0), b3, voffB); PG8_STAGE(PG8_SB(1, 1), b3 + hstepB, voffB); PG8_STAGE(PG8_SA(1, 0), a3, voffA);
;             PG8_WAIT_V(8); PG8_WAIT_L(0); PG8_BAR; PG8_MMA(1, 0, At, B0); PG8_MMA(1, 1, At, B1); PG8_BAR; PG8_SCHED;
	s_setprio 1
	v_mfma_f32_16x16x32_bf16 v[60:63], v[130:133], v[176:179], v[60:63]
	v_mfma_f32_16x16x32_bf16 v[56:59], v[138:141], v[176:179], v[56:59]
	v_mfma_f32_16x16x32_bf16 v[44:47], v[130:133], v[184:187], v[44:47]
	v_mfma_f32_16x16x32_bf16 v[40:43], v[138:141], v[184:187], v[40:43]
	v_mfma_f32_16x16x32_bf16 v[28:31], v[130:133], v[192:195], v[28:31]
	v_mfma_f32_16x16x32_bf16 v[24:27], v[138:141], v[192:195], v[24:27]
	v_mfma_f32_16x16x32_bf16 v[12:15], v[130:133], v[206:209], v[12:15]
	v_mfma_f32_16x16x32_bf16 v[8:11], v[138:141], v[206:209], v[8:11]
	v_mfma_f32_16x16x32_bf16 v[60:63], v[134:137], v[180:183], v[60:63]
	v_mfma_f32_16x16x32_bf16 v[56:59], v[142:145], v[180:183], v[56:59]
	v_mfma_f32_16x16x32_bf16 v[44:47], v[134:137], v[188:191], v[44:47]
	v_mfma_f32_16x16x32_bf16 v[40:43], v[142:145], v[188:191], v[40:43]
	v_mfma_f32_16x16x32_bf16 v[28:31], v[134:137], v[200:203], v[28:31]
	v_mfma_f32_16x16x32_bf16 v[24:27], v[142:145], v[200:203], v[24:27]
	v_mfma_f32_16x16x32_bf16 v[12:15], v[134:137], v[210:213], v[12:15]
	v_mfma_f32_16x16x32_bf16 v[8:11], v[142:145], v[210:213], v[8:11]
	s_setprio 0
	s_setprio 1
	v_mfma_f32_16x16x32_bf16 v[52:55], v[154:157], v[176:179], v[52:55]
	v_mfma_f32_16x16x32_bf16 v[48:51], v[168:171], v[176:179], v[48:51]
	v_mfma_f32_16x16x32_bf16 v[36:39], v[154:157], v[184:187], v[36:39]
	v_mfma_f32_16x16x32_bf16 v[32:35], v[168:171], v[184:187], v[32:35]
	v_mfma_f32_16x16x32_bf16 v[20:23], v[154:157], v[192:195], v[20:23]
	v_mfma_f32_16x16x32_bf16 v[16:19], v[168:171], v[192:195], v[16:19]
	v_mfma_f32_16x16x32_bf16 v[4:7], v[154:157], v[206:209], v[4:7]
	v_mfma_f32_16x16x32_bf16 v[0:3], v[168:171], v[206:209], v[0:3]
	v_mfma_f32_16x16x32_bf16 v[52:55], v[164:167], v[180:183], v[52:55]
	v_mfma_f32_16x16x32_bf16 v[48:51], v[172:175], v[180:183], v[48:51]
	v_mfma_f32_16x16x32_bf16 v[36:39], v[164:167], v[188:191], v[36:39]
	v_mfma_f32_16x16x32_bf16 v[32:35], v[172:175], v[188:191], v[32:35]
	v_mfma_f32_16x16x32_bf16 v[20:23], v[164:167], v[200:203], v[20:23]
	v_mfma_f32_16x16x32_bf16 v[16:19], v[172:175], v[200:203], v[16:19]
	v_mfma_f32_16x16x32_bf16 v[4:7], v[164:167], v[210:213], v[4:7]
	v_mfma_f32_16x16x32_bf16 v[0:3], v[172:175], v[210:213], v[0:3]
	s_setprio 0
	s_barrier
	s_add_i32 s28, 0, 0x18000
	s_add_i32 s30, 0, 0x1c000
	v_add_u32_e32 v142, s28, v159
	v_add_u32_e32 v163, s30, v159
	ds_read_b128 v[130:133], v142
	ds_read_b128 v[134:137], v142 offset:1024
	ds_read_b128 v[138:141], v142 offset:2048
	ds_read_b128 v[142:145], v142 offset:3072
	ds_read_b128 v[154:157], v163
	ds_read_b128 v[164:167], v163 offset:1024
	ds_read_b128 v[168:171], v163 offset:2048
	ds_read_b128 v[172:175], v163 offset:3072
	s_add_u32 s66, s66, 0x80000
	s_addc_u32 s67, s67, 0
	s_mov_b32 m0, s69
	v_lshl_add_u64 v[228:229], s[66:67], 0, v[146:147]
	ds_read_b128 v[176:179], v162 offset:32768
	ds_read_b128 v[180:183], v162 offset:33792
	ds_read_b128 v[184:187], v162 offset:34816
	ds_read_b128 v[188:191], v162 offset:35840
	ds_read_b128 v[192:195], v162 offset:36864
	ds_read_b128 v[200:203], v162 offset:37888
	ds_read_b128 v[206:209], v162 offset:38912
	ds_read_b128 v[210:213], v162 offset:39936
	global_load_lds_dwordx4 v[228:229], off
	v_lshl_add_u64 v[228:229], s[66:67], 0, v[148:149]
	s_mov_b32 m0, s70
	s_nop 0
	global_load_lds_dwordx4 v[228:229], off
	s_waitcnt vmcnt(8)
	s_waitcnt lgkmcnt(0)
	s_barrier
	s_setprio 1
	v_mfma_f32_16x16x32_bf16 v[126:129], v[130:133], v[176:179], v[126:129]
	v_mfma_f32_16x16x32_bf16 v[122:125], v[138:141], v[176:179], v[122:125]
	v_mfma_f32_16x16x32_bf16 v[110:113], v[130:133], v[184:187], v[110:113]
	v_mfma_f32_16x16x32_bf16 v[106:109], v[138:141], v[184:187], v[106:109]
	v_mfma_f32_16x16x32_bf16 v[92:95], v[130:133], v[192:195], v[92:95]
	v_mfma_f32_16x16x32_bf16 v[88:91], v[138:141], v[192:195], v[88:91]
	v_mfma_f32_16x16x32_bf16 v[76:79], v[130:133], v[206:209], v[76:79]
	v_mfma_f32_16x16x32_bf16 v[72:75], v[138:141], v[206:209], v[72:75]
	v_mfma_f32_16x16x32_bf16 v[126:129], v[134:137], v[180:183], v[126:129]
	v_mfma_f32_16x16x32_bf16 v[122:125], v[142:145], v[180:183], v[122:125]
	v_mfma_f32_16x16x32_bf16 v[110:113], v[134:137], v[188:191], v[110:113]
	v_mfma_f32_16x16x32_bf16 v[106:109], v[142:145], v[188:191], v[106:109]
	v_mfma_f32_16x16x32_bf16 v[92:95], v[134:137], v[200:203], v[92:95]
	v_mfma_f32_16x16x32_bf16 v[88:91], v[142:145], v[200:203], v[88:91]
	v_mfma_f32_16x16x32_bf16 v[76:79], v[134:137], v[210:213], v[76:79]
	v_mfma_f32_16x16x32_bf16 v[72:75], v[142:145], v[210:213], v[72:75]
	s_setprio 0
	s_setprio 1
	v_mfma_f32_16x16x32_bf16 v[118:121], v[154:157], v[176:179], v[118:121]
	v_mfma_f32_16x16x32_bf16 v[114:117], v[168:171], v[176:179], v[114:117]
	v_mfma_f32_16x16x32_bf16 v[102:105], v[154:157], v[184:187], v[102:105]
	v_mfma_f32_16x16x32_bf16 v[98:101], v[168:171], v[184:187], v[98:101]
	v_mfma_f32_16x16x32_bf16 v[84:87], v[154:157], v[192:195], v[84:87]
	v_mfma_f32_16x16x32_bf16 v[80:83], v[168:171], v[192:195], v[80:83]
	v_mfma_f32_16x16x32_bf16 v[68:71], v[154:157], v[206:209], v[68:71]
	v_mfma_f32_16x16x32_bf16 v[64:67], v[168:171], v[206:209], v[64:67]
	v_mfma_f32_16x16x32_bf16 v[118:121], v[164:167], v[180:183], v[118:121]
	v_mfma_f32_16x16x32_bf16 v[114:117], v[172:175], v[180:183], v[114:117]
	v_mfma_f32_16x16x32_bf16 v[102:105], v[164:167], v[188:191], v[102:105]
	v_mfma_f32_16x16x32_bf16 v[98:101], v[172:175], v[188:191], v[98:101]
	v_mfma_f32_16x16x32_bf16 v[84:87], v[164:167], v[200:203], v[84:87]
	v_mfma_f32_16x16x32_bf16 v[80:83], v[172:175], v[200:203], v[80:83]
	v_mfma_f32_16x16x32_bf16 v[68:71], v[164:167], v[210:213], v[68:71]
	v_mfma_f32_16x16x32_bf16 v[64:67], v[172:175], v[210:213], v[64:67]
	s_setprio 0
	s_barrier
; #define PG8_STAGE(bufoff, gbase, voff) do { _Pragma("unroll") for (int _i = 0; _i < 2; ++_i) \
;         __builtin_amdgcn_global_load_lds((const unsigned*)((const char*)(gbase) + (voff)[_i]), (PG8_LAS unsigned*)(lds + (bufoff) + ldsw + _i * 8192), 16, 0, 0); } while (0)
; #define PG8_LDA(dst, b, h) do { _Pragma("unroll") for (int m = 0; m < 4; ++m) _Pragma("unroll") for (int k = 0; k < 2; ++k) dst[m][k] = *(const PG8_LAS bf16x8*)(lds + PG8_SA(b, h) + aoff + m * 2048 + k * 1024); } while (0)
; #define PG8_WAIT_V(n) asm volatile("s_waitcnt vmcnt(" #n ")" ::: "memory")
; #define PG8_WAIT_L(n) asm volatile("s_waitcnt lgkmcnt(" #n ")" ::: "memory")
; #define PG8_BAR __builtin_amdgcn_s_barrier()
; template <class Epi, class Sched, bool ALIGN_EPI = true, bool SP2 = true>
; __device__ __forceinline__ void gemm_phase(PG8_LAS unsigned char* lds, const Gemm g, const Sched& S, const Epi& E, const int tid) {
;     ...
;         for (int t = 0; t < nt; t += 2) {
;             const bool last = (t == nt - 2);
;             const char* a1 = cA + (size_t)(t + 1) * kstep;
;             const char* a2 = last ? nA : cA + (size_t)(t + 2) * kstep; const char* b2 = last ? nB : cB + (size_t)(t + 2) * kstep;
;             const char* a3 = a2 + kstep; const char* b3 = b2 + kstep;
;             if (last && has_next) S.a_ready(nxt);
;             if constexpr (SP2) {
;             PG8_LDB(B0, 0, 0); PG8_LDB(B1, 0, 1); PG8_SCHED; PG8_LDA(At, 0, 0); PG8_STAGE(PG8_SA(1, 1), a1 + hstepA, voffA);
;             PG8_WAIT_V(8); PG8_WAIT_L(0); PG8_BAR; PG8_MMA(0, 0, At, B0); PG8_MMA(0, 1, At, B1); PG8_BAR; PG8_SCHED;
;             PG8_LDA(At, 0, 1); PG8_STAGE(PG8_SB(0, 0), b2, voffB); PG8_STAGE(PG8_SB(0, 1), b2 + hstepB, voffB); PG8_STAGE(PG8_SA(0, 0), a2, voffA);
;             PG8_WAIT_V(8); PG8_WAIT_L(0); PG8_BAR; PG8_MMA(1, 0, At, B0); PG8_MMA(1, 1, At, B1); PG8_BAR; PG8_SCHED;
;             PG8_LDB(B0, 1, 0); PG8_LDB(B1, 1, 1); PG8_SCHED; PG8_LDA(At, 1, 0); PG8_STAGE(PG8_SA(0, 1), a2 + hstepA, voffA);
;             PG8_WAIT_V(8); PG8_WAIT_L(0); PG8_BAR; PG8_MMA(0, 0, At, B0); PG8_MMA(0, 1, At, B1); PG8_BAR; PG8_SCHED;
;             PG8_LDA(At, 1, 1); PG8_STAGE(PG8_SB(1, 0), b3, voffB); PG8_STAGE(PG8_SB(1, 1), b3 + hstepB, voffB); PG8_STAGE(PG8_SA(1, 0), a3, voffA);
;             PG8_WAIT_V(8); PG8_WAIT_L(0); PG8_BAR; PG8_MMA(1, 0, At, B0); PG8_MMA(1, 1, At, B1); PG8_BAR; PG8_SCHED;
	s_add_i32 s28, s28, s22
	v_lshl_add_u64 v[196:197], v[196:197], 0, s[4:5]
	s_mov_b32 m0, s28
	ds_read_b128 v[176:179], v162 offset:49152
	ds_read_b128 v[180:183], v162 offset:50176
	ds_read_b128 v[184:187], v162 offset:51200
	ds_read_b128 v[188:191], v162 offset:52224
	ds_read_b128 v[192:195], v162 offset:53248
	ds_read_b128 v[200:203], v162 offset:54272
	ds_read_b128 v[206:209], v162 offset:55296
	ds_read_b128 v[210:213], v162 offset:56320
	global_load_lds_dwordx4 v[196:197], off
	s_add_i32 m0, s28, 0x2000
	s_add_u32 s64, s64, 0x80080
	v_lshl_add_u64 v[196:197], v[222:223], 0, s[4:5]
	s_addc_u32 s65, s65, 0
	s_add_i32 s28, s30, s22
	global_load_lds_dwordx4 v[196:197], off
	v_lshl_add_u64 v[196:197], s[64:65], 0, v[146:147]
	s_mov_b32 m0, s28
	s_nop 0
	global_load_lds_dwordx4 v[196:197], off
	v_lshl_add_u64 v[196:197], s[64:65], 0, v[148:149]
	s_add_i32 m0, s28, 0x2000
	s_nop 0
	global_load_lds_dwordx4 v[196:197], off
	v_lshl_add_u64 v[196:197], v[224:225], 0, s[4:5]
	s_mov_b32 m0, s79
	s_nop 0
	global_load_lds_dwordx4 v[196:197], off
	v_lshl_add_u64 v[196:197], v[226:227], 0, s[4:5]
	s_mov_b32 m0, s80
	s_nop 0
	global_load_lds_dwordx4 v[196:197], off
	s_waitcnt vmcnt(8)
	s_waitcnt lgkmcnt(0)
	s_barrier
	s_setprio 1
	v_mfma_f32_16x16x32_bf16 v[60:63], v[130:133], v[176:179], v[60:63]
	v_mfma_f32_16x16x32_bf16 v[56:59], v[138:141], v[176:179], v[56:59]
	v_mfma_f32_16x16x32_bf16 v[44:47], v[130:133], v[184:187], v[44:47]
	v_mfma_f32_16x16x32_bf16 v[40:43], v[138:141], v[184:187], v[40:43]
	v_mfma_f32_16x16x32_bf16 v[28:31], v[130:133], v[192:195], v[28:31]
	v_mfma_f32_16x16x32_bf16 v[24:27], v[138:141], v[192:195], v[24:27]
	v_mfma_f32_16x16x32_bf16 v[12:15], v[130:133], v[206:209], v[12:15]
	v_mfma_f32_16x16x32_bf16 v[8:11], v[138:141], v[206:209], v[8:11]
	v_mfma_f32_16x16x32_bf16 v[60:63], v[134:137], v[180:183], v[60:63]
	v_mfma_f32_16x16x32_bf16 v[56:59], v[142:145], v[180:183], v[56:59]
	v_mfma_f32_16x16x32_bf16 v[44:47], v[134:137], v[188:191], v[44:47]
	v_mfma_f32_16x16x32_bf16 v[40:43], v[142:145], v[188:191], v[40:43]
	v_mfma_f32_16x16x32_bf16 v[28:31], v[134:137], v[200:203], v[28:31]
	v_mfma_f32_16x16x32_bf16 v[24:27], v[142:145], v[200:203], v[24:27]
	v_mfma_f32_16x16x32_bf16 v[12:15], v[134:137], v[210:213], v[12:15]
	v_mfma_f32_16x16x32_bf16 v[8:11], v[142:145], v[210:213], v[8:11]
	s_setprio 0
	s_setprio 1
	v_mfma_f32_16x16x32_bf16 v[52:55], v[154:157], v[176:179], v[52:55]
	v_mfma_f32_16x16x32_bf16 v[48:51], v[168:171], v[176:179], v[48:51]
	v_mfma_f32_16x16x32_bf16 v[36:39], v[154:157], v[184:187], v[36:39]
	v_mfma_f32_16x16x32_bf16 v[32:35], v[168:171], v[184:187], v[32:35]
	v_mfma_f32_16x16x32_bf16 v[20:23], v[154:157], v[192:195], v[20:23]
	v_mfma_f32_16x16x32_bf16 v[16:19], v[168:171], v[192:195], v[16:19]
	v_mfma_f32_16x16x32_bf16 v[4:7], v[154:157], v[206:209], v[4:7]
	v_mfma_f32_16x16x32_bf16 v[0:3], v[168:171], v[206:209], v[0:3]
	v_mfma_f32_16x16x32_bf16 v[52:55], v[164:167], v[180:183], v[52:55]
	v_mfma_f32_16x16x32_bf16 v[48:51], v[172:175], v[180:183], v[48:51]
	v_mfma_f32_16x16x32_bf16 v[36:39], v[164:167], v[188:191], v[36:39]
	v_mfma_f32_16x16x32_bf16 v[32:35], v[172:175], v[188:191], v[32:35]
	v_mfma_f32_16x16x32_bf16 v[20:23], v[164:167], v[200:203], v[20:23]
	v_mfma_f32_16x16x32_bf16 v[16:19], v[172:175], v[200:203], v[16:19]
	v_mfma_f32_16x16x32_bf16 v[4:7], v[164:167], v[210:213], v[4:7]
	v_mfma_f32_16x16x32_bf16 v[0:3], v[172:175], v[210:213], v[0:3]
	s_setprio 0
	s_barrier
	s_add_u32 s62, s62, 0x100
	s_addc_u32 s63, s63, 0
	s_add_u32 s25, s25, 0x100
	s_addc_u32 s27, s27, 0
	s_cmp_ge_i32 s29, s24
	s_mov_b32 s28, s29
	s_cbranch_scc0 .LBB0_1039
	s_and_b64 vcc, exec, s[50:51]
	s_cbranch_vccz .LBB0_1042

; #define PG8_STAGE(bufoff, gbase, voff) do { _Pragma("unroll") for (int _i = 0; _i < 2; ++_i) \
;         __builtin_amdgcn_global_load_lds((const unsigned*)((const char*)(gbase) + (voff)[_i]), (PG8_LAS unsigned*)(lds + (bufoff) + ldsw + _i * 8192), 16, 0, 0); } while (0)
; #define PG8_LDA(dst, b, h) do { _Pragma("unroll") for (int m = 0; m < 4; ++m) _Pragma("unroll") for (int k = 0; k < 2; ++k) dst[m][k] = *(const PG8_LAS bf16x8*)(lds + PG8_SA(b, h) + aoff + m * 2048 + k * 1024); } while (0)
; #define PG8_WAIT_V(n) asm volatile("s_waitcnt vmcnt(" #n ")" ::: "memory")
; #define PG8_WAIT_L(n) asm volatile("s_waitcnt lgkmcnt(" #n ")" ::: "memory")
; #define PG8_BAR __builtin_amdgcn_s_barrier()
; template <class Epi, class Sched, bool ALIGN_EPI = true, bool SP2 = true>
; __device__ __forceinline__ void gemm_phase(PG8_LAS unsigned char* lds, const Gemm g, const Sched& S, const Epi& E, const int tid) {
;     ...
;         for (int t = 0; t < nt; t += 2) {
;             const bool last = (t == nt - 2);
;             const char* a1 = cA + (size_t)(t + 1) * kstep;
;             const char* a2 = last ? nA : cA + (size_t)(t + 2) * kstep; const char* b2 = last ? nB : cB + (size_t)(t + 2) * kstep;
;             const char* a3 = a2 + kstep; const char* b3 = b2 + kstep;
;             if (last && has_next) S.a_ready(nxt);
;             if constexpr (SP2) {
;             PG8_LDB(B0, 0, 0); PG8_LDB(B1, 0, 1); PG8_SCHED; PG8_LDA(At, 0, 0); PG8_STAGE(PG8_SA(1, 1), a1 + hstepA, voffA);
;             PG8_WAIT_V(8); PG8_WAIT_L(0); PG8_BAR; PG8_MMA(0, 0, At, B0); PG8_MMA(0, 1, At, B1); PG8_BAR; PG8_SCHED;
;             PG8_LDA(At, 0, 1); PG8_STAGE(PG8_SB(0, 0), b2, voffB); PG8_STAGE(PG8_SB(0, 1), b2 + hstepB, voffB); PG8_STAGE(PG8_SA(0, 0), a2, voffA);
;             PG8_WAIT_V(8); PG8_WAIT_L(0); PG8_BAR; PG8_MMA(1, 0, At, B0); PG8_MMA(1, 1, At, B1); PG8_BAR; PG8_SCHED;
;             PG8_LDB(B0, 1, 0); PG8_LDB(B1, 1, 1); PG8_SCHED; PG8_LDA(At, 1, 0); PG8_STAGE(PG8_SA(0, 1), a2 + hstepA, voffA);
;             PG8_WAIT_V(8); PG8_WAIT_L(0); PG8_BAR; PG8_MMA(0, 0, At, B0); PG8_MMA(0, 1, At, B1); PG8_BAR; PG8_SCHED;
;             PG8_LDA(At, 1, 1); PG8_STAGE(PG8_SB(1, 0), b3, voffB); PG8_STAGE(PG8_SB(1, 1), b3 + hstepB, voffB); PG8_STAGE(PG8_SA(1, 0), a3, voffA);
;             PG8_WAIT_V(8); PG8_WAIT_L(0); PG8_BAR; PG8_MMA(1, 0, At, B0); PG8_MMA(1, 1, At, B1); PG8_BAR; PG8_SCHED;
.LBB0_1077:
	s_add_i32 s63, s82, 2
	s_add_u32 s83, s80, 0xfff80080
	s_addc_u32 s84, s81, -1
	s_add_i32 vcc_lo, 0, 0x10000
	s_cmp_eq_u32 s29, s82
	s_cselect_b32 s85, s67, s84
	s_cselect_b32 s84, s66, s83
	v_add_u32_e32 v96, vcc_lo, v141
	s_cselect_b32 s83, s69, s61
	s_cselect_b32 s82, s68, s59
	s_add_i32 s30, 0, 0x14000
	ds_read_b128 v[146:149], v96
	ds_read_b128 v[150:153], v96 offset:1024
	ds_read_b128 v[154:157], v96 offset:2048
	ds_read_b128 v[158:161], v96 offset:3072
	v_add_u32_e32 v96, s30, v141
	ds_read_b128 v[162:165], v96
	ds_read_b128 v[166:169], v96 offset:1024
	ds_read_b128 v[170:173], v96 offset:2048
	ds_read_b128 v[174:177], v96 offset:3072
	v_lshl_add_u64 v[98:99], s[80:81], 0, v[136:137]
	s_add_i32 m0, s25, 0xc000
	ds_read_b128 v[178:181], v145
	ds_read_b128 v[182:185], v145 offset:1024
	ds_read_b128 v[186:189], v145 offset:2048
	ds_read_b128 v[190:193], v145 offset:3072
	ds_read_b128 v[194:197], v145 offset:4096
	ds_read_b128 v[200:203], v145 offset:5120
	ds_read_b128 v[206:209], v145 offset:6144
	ds_read_b128 v[210:213], v145 offset:7168
	global_load_lds_dwordx4 v[98:99], off
	v_lshl_add_u64 v[98:99], s[80:81], 0, v[138:139]
	s_add_i32 m0, s25, 0xe000
	s_nop 0
	global_load_lds_dwordx4 v[98:99], off
	s_waitcnt vmcnt(8)
	s_waitcnt lgkmcnt(0)
	s_barrier
	s_setprio 1
	v_mfma_f32_16x16x32_bf16 v[92:95], v[146:149], v[178:181], v[92:95]
	v_mfma_f32_16x16x32_bf16 v[92:95], v[150:153], v[182:185], v[92:95]
	v_mfma_f32_16x16x32_bf16 v[130:133], v[154:157], v[178:181], v[130:133]
	v_mfma_f32_16x16x32_bf16 v[130:133], v[158:161], v[182:185], v[130:133]
	v_mfma_f32_16x16x32_bf16 v[126:129], v[146:149], v[186:189], v[126:129]
	v_mfma_f32_16x16x32_bf16 v[126:129], v[150:153], v[190:193], v[126:129]
	v_mfma_f32_16x16x32_bf16 v[122:125], v[154:157], v[186:189], v[122:125]
	v_mfma_f32_16x16x32_bf16 v[122:125], v[158:161], v[190:193], v[122:125]
	v_mfma_f32_16x16x32_bf16 v[118:121], v[146:149], v[194:197], v[118:121]
	v_mfma_f32_16x16x32_bf16 v[118:121], v[150:153], v[200:203], v[118:121]
	v_mfma_f32_16x16x32_bf16 v[110:113], v[154:157], v[194:197], v[110:113]
	v_mfma_f32_16x16x32_bf16 v[110:113], v[158:161], v[200:203], v[110:113]
	v_mfma_f32_16x16x32_bf16 v[76:79], v[146:149], v[206:209], v[76:79]
	v_mfma_f32_16x16x32_bf16 v[76:79], v[150:153], v[210:213], v[76:79]
	v_mfma_f32_16x16x32_bf16 v[72:75], v[154:157], v[206:209], v[72:75]
	v_mfma_f32_16x16x32_bf16 v[72:75], v[158:161], v[210:213], v[72:75]
	s_setprio 0
	s_setprio 1
	v_mfma_f32_16x16x32_bf16 v[88:91], v[162:165], v[178:181], v[88:91]
	v_mfma_f32_16x16x32_bf16 v[88:91], v[166:169], v[182:185], v[88:91]
	v_mfma_f32_16x16x32_bf16 v[84:87], v[170:173], v[178:181], v[84:87]
	v_mfma_f32_16x16x32_bf16 v[84:87], v[174:177], v[182:185], v[84:87]
	v_mfma_f32_16x16x32_bf16 v[114:117], v[162:165], v[186:189], v[114:117]
	v_mfma_f32_16x16x32_bf16 v[114:117], v[166:169], v[190:193], v[114:117]
	v_mfma_f32_16x16x32_bf16 v[106:109], v[170:173], v[186:189], v[106:109]
	v_mfma_f32_16x16x32_bf16 v[106:109], v[174:177], v[190:193], v[106:109]
	v_mfma_f32_16x16x32_bf16 v[102:105], v[162:165], v[194:197], v[102:105]
	v_mfma_f32_16x16x32_bf16 v[102:105], v[166:169], v[200:203], v[102:105]
	v_mfma_f32_16x16x32_bf16 v[80:83], v[170:173], v[194:197], v[80:83]
	v_mfma_f32_16x16x32_bf16 v[80:83], v[174:177], v[200:203], v[80:83]
	v_mfma_f32_16x16x32_bf16 v[68:71], v[162:165], v[206:209], v[68:71]
	v_mfma_f32_16x16x32_bf16 v[68:71], v[166:169], v[210:213], v[68:71]
	s_setprio 2
	s_barrier
	v_mfma_f32_16x16x32_bf16 v[64:67], v[170:173], v[206:209], v[64:67]
	v_mfma_f32_16x16x32_bf16 v[64:67], v[174:177], v[210:213], v[64:67]
	s_setprio 0
	s_add_i32 s31, vcc_lo, s24
	v_lshl_add_u64 v[98:99], s[82:83], 0, v[100:101]
	s_mov_b32 m0, s31
	ds_read_b128 v[178:181], v145 offset:16384
	ds_read_b128 v[182:185], v145 offset:17408
	ds_read_b128 v[186:189], v145 offset:18432
	ds_read_b128 v[190:193], v145 offset:19456
	ds_read_b128 v[194:197], v145 offset:20480
	ds_read_b128 v[200:203], v145 offset:21504
	ds_read_b128 v[206:209], v145 offset:22528
	ds_read_b128 v[210:213], v145 offset:23552
	global_load_lds_dwordx4 v[98:99], off
	s_add_i32 m0, s31, 0x2000
	s_add_u32 vcc_lo, s82, 0x80000
	v_lshl_add_u64 v[224:225], s[82:83], 0, v[134:135]
	s_addc_u32 vcc_hi, s83, 0
	s_add_i32 s30, s30, s24
	global_load_lds_dwordx4 v[224:225], off
	v_lshl_add_u64 v[226:227], vcc, 0, v[100:101]
	s_mov_b32 m0, s30
	v_lshl_add_u64 v[228:229], s[84:85], 0, v[134:135]
	global_load_lds_dwordx4 v[226:227], off
	v_lshl_add_u64 v[226:227], vcc, 0, v[134:135]
	s_add_i32 m0, s30, 0x2000
	s_nop 0
	global_load_lds_dwordx4 v[226:227], off
	v_lshl_add_u64 v[226:227], s[84:85], 0, v[100:101]
	s_mov_b32 m0, s25
	s_nop 0
	global_load_lds_dwordx4 v[226:227], off
	s_mov_b32 m0, s49
	s_nop 0
	global_load_lds_dwordx4 v[228:229], off
	s_waitcnt vmcnt(8)
	s_waitcnt lgkmcnt(0)
	s_barrier
; #define PG8_STAGE(bufoff, gbase, voff) do { _Pragma("unroll") for (int _i = 0; _i < 2; ++_i) \
;         __builtin_amdgcn_global_load_lds((const unsigned*)((const char*)(gbase) + (voff)[_i]), (PG8_LAS unsigned*)(lds + (bufoff) + ldsw + _i * 8192), 16, 0, 0); } while (0)
; #define PG8_LDA(dst, b, h) do { _Pragma("unroll") for (int m = 0; m < 4; ++m) _Pragma("unroll") for (int k = 0; k < 2; ++k) dst[m][k] = *(const PG8_LAS bf16x8*)(lds + PG8_SA(b, h) + aoff + m * 2048 + k * 1024); } while (0)
; #define PG8_LDB(dst, b, h) do { _Pragma("unroll") for (int n = 0; n < 2; ++n) _Pragma("unroll") for (int k = 0; k < 2; ++k) dst[n][k] = *(const PG8_LAS bf16x8*)(lds + PG8_SB(b, h) + boff + n * 2048 + k * 1024); } while (0)
; #define PG8_MMA(ai, bj, At, Bt) do { __builtin_amdgcn_s_setprio(1); _Pragma("unroll") for (int m = 0; m < 4; ++m) _Pragma("unroll") for (int n = 0; n < 2; ++n) _Pragma("unroll") for (int k = 0; k < 2; ++k) \
;         acc[ai][bj][m][n] = __builtin_amdgcn_mfma_f32_16x16x32_bf16(Bt[n][k], At[m][k], acc[ai][bj][m][n], 0, 0, 0); __builtin_amdgcn_s_setprio(0); } while (0)
; template <class Epi, class Sched, bool ALIGN_EPI = true, bool SP2 = true>
; __device__ __forceinline__ void gemm_phase(PG8_LAS unsigned char* lds, const Gemm g, const Sched& S, const Epi& E, const int tid) {
;     ...
;             if constexpr (SP2) {
;             PG8_LDB(B0, 0, 0); PG8_LDB(B1, 0, 1); PG8_SCHED; PG8_LDA(At, 0, 0); PG8_STAGE(PG8_SA(1, 1), a1 + hstepA, voffA);
;             PG8_WAIT_V(8); PG8_WAIT_L(0); PG8_BAR; PG8_MMA(0, 0, At, B0); PG8_MMA(0, 1, At, B1); PG8_BAR; PG8_SCHED;
;             PG8_LDA(At, 0, 1); PG8_STAGE(PG8_SB(0, 0), b2, voffB); PG8_STAGE(PG8_SB(0, 1), b2 + hstepB, voffB); PG8_STAGE(PG8_SA(0, 0), a2, voffA);
;             PG8_WAIT_V(8); PG8_WAIT_L(0); PG8_BAR; PG8_MMA(1, 0, At, B0); PG8_MMA(1, 1, At, B1); PG8_BAR; PG8_SCHED;
;             PG8_LDB(B0, 1, 0); PG8_LDB(B1, 1, 1); PG8_SCHED; PG8_LDA(At, 1, 0); PG8_STAGE(PG8_SA(0, 1), a2 + hstepA, voffA);
;             PG8_WAIT_V(8); PG8_WAIT_L(0); PG8_BAR; PG8_MMA(0, 0, At, B0); PG8_MMA(0, 1, At, B1); PG8_BAR; PG8_SCHED;
;             PG8_LDA(At, 1, 1); PG8_STAGE(PG8_SB(1, 0), b3, voffB); PG8_STAGE(PG8_SB(1, 1), b3 + hstepB, voffB); PG8_STAGE(PG8_SA(1, 0), a3, voffA);
;             PG8_WAIT_V(8); PG8_WAIT_L(0); PG8_BAR; PG8_MMA(1, 0, At, B0); PG8_MMA(1, 1, At, B1); PG8_BAR; PG8_SCHED;
	s_setprio 1
	v_mfma_f32_16x16x32_bf16 v[56:59], v[146:149], v[178:181], v[56:59]
	v_mfma_f32_16x16x32_bf16 v[56:59], v[150:153], v[182:185], v[56:59]
	v_mfma_f32_16x16x32_bf16 v[60:63], v[154:157], v[178:181], v[60:63]
	v_mfma_f32_16x16x32_bf16 v[60:63], v[158:161], v[182:185], v[60:63]
	v_mfma_f32_16x16x32_bf16 v[44:47], v[146:149], v[186:189], v[44:47]
	v_mfma_f32_16x16x32_bf16 v[44:47], v[150:153], v[190:193], v[44:47]
	v_mfma_f32_16x16x32_bf16 v[40:43], v[154:157], v[186:189], v[40:43]
	v_mfma_f32_16x16x32_bf16 v[40:43], v[158:161], v[190:193], v[40:43]
	v_mfma_f32_16x16x32_bf16 v[28:31], v[146:149], v[194:197], v[28:31]
	v_mfma_f32_16x16x32_bf16 v[28:31], v[150:153], v[200:203], v[28:31]
	v_mfma_f32_16x16x32_bf16 v[24:27], v[154:157], v[194:197], v[24:27]
	v_mfma_f32_16x16x32_bf16 v[24:27], v[158:161], v[200:203], v[24:27]
	v_mfma_f32_16x16x32_bf16 v[12:15], v[146:149], v[206:209], v[12:15]
	v_mfma_f32_16x16x32_bf16 v[12:15], v[150:153], v[210:213], v[12:15]
	v_mfma_f32_16x16x32_bf16 v[8:11], v[154:157], v[206:209], v[8:11]
	v_mfma_f32_16x16x32_bf16 v[8:11], v[158:161], v[210:213], v[8:11]
	s_setprio 0
	s_setprio 1
	v_mfma_f32_16x16x32_bf16 v[52:55], v[162:165], v[178:181], v[52:55]
	v_mfma_f32_16x16x32_bf16 v[52:55], v[166:169], v[182:185], v[52:55]
	v_mfma_f32_16x16x32_bf16 v[48:51], v[170:173], v[178:181], v[48:51]
	v_mfma_f32_16x16x32_bf16 v[48:51], v[174:177], v[182:185], v[48:51]
	v_mfma_f32_16x16x32_bf16 v[36:39], v[162:165], v[186:189], v[36:39]
	v_mfma_f32_16x16x32_bf16 v[36:39], v[166:169], v[190:193], v[36:39]
	v_mfma_f32_16x16x32_bf16 v[32:35], v[170:173], v[186:189], v[32:35]
	v_mfma_f32_16x16x32_bf16 v[32:35], v[174:177], v[190:193], v[32:35]
	v_mfma_f32_16x16x32_bf16 v[20:23], v[162:165], v[194:197], v[20:23]
	v_mfma_f32_16x16x32_bf16 v[20:23], v[166:169], v[200:203], v[20:23]
	v_mfma_f32_16x16x32_bf16 v[16:19], v[170:173], v[194:197], v[16:19]
	v_mfma_f32_16x16x32_bf16 v[16:19], v[174:177], v[200:203], v[16:19]
	v_mfma_f32_16x16x32_bf16 v[4:7], v[162:165], v[206:209], v[4:7]
	v_mfma_f32_16x16x32_bf16 v[4:7], v[166:169], v[210:213], v[4:7]
	s_setprio 2
	s_barrier
	v_mfma_f32_16x16x32_bf16 v[0:3], v[170:173], v[206:209], v[0:3]
	v_mfma_f32_16x16x32_bf16 v[0:3], v[174:177], v[210:213], v[0:3]
	s_setprio 0
	s_add_i32 s30, 0, 0x18000
	v_add_u32_e32 v96, s30, v141
	s_add_i32 s31, 0, 0x1c000
	ds_read_b128 v[146:149], v96
	ds_read_b128 v[150:153], v96 offset:1024
	ds_read_b128 v[154:157], v96 offset:2048
	ds_read_b128 v[158:161], v96 offset:3072
	v_add_u32_e32 v96, s31, v141
	ds_read_b128 v[162:165], v96
	ds_read_b128 v[166:169], v96 offset:1024
	ds_read_b128 v[170:173], v96 offset:2048
	ds_read_b128 v[174:177], v96 offset:3072
	s_add_u32 s84, s84, 0x80000
	s_addc_u32 s85, s85, 0
	s_mov_b32 m0, s51
	v_lshl_add_u64 v[230:231], s[84:85], 0, v[100:101]
	ds_read_b128 v[178:181], v145 offset:32768
	ds_read_b128 v[182:185], v145 offset:33792
	ds_read_b128 v[186:189], v145 offset:34816
	ds_read_b128 v[190:193], v145 offset:35840
	ds_read_b128 v[194:197], v145 offset:36864
	ds_read_b128 v[200:203], v145 offset:37888
	ds_read_b128 v[206:209], v145 offset:38912
	ds_read_b128 v[210:213], v145 offset:39936
	global_load_lds_dwordx4 v[230:231], off
	v_lshl_add_u64 v[230:231], s[84:85], 0, v[134:135]
	s_mov_b32 m0, s76
	s_nop 0
	global_load_lds_dwordx4 v[230:231], off
	s_waitcnt vmcnt(8)
	s_waitcnt lgkmcnt(0)
	s_barrier
	s_setprio 1
	v_mfma_f32_16x16x32_bf16 v[92:95], v[146:149], v[178:181], v[92:95]
	v_mfma_f32_16x16x32_bf16 v[92:95], v[150:153], v[182:185], v[92:95]
	v_mfma_f32_16x16x32_bf16 v[130:133], v[154:157], v[178:181], v[130:133]
	v_mfma_f32_16x16x32_bf16 v[130:133], v[158:161], v[182:185], v[130:133]
	v_mfma_f32_16x16x32_bf16 v[126:129], v[146:149], v[186:189], v[126:129]
	v_mfma_f32_16x16x32_bf16 v[126:129], v[150:153], v[190:193], v[126:129]
	v_mfma_f32_16x16x32_bf16 v[122:125], v[154:157], v[186:189], v[122:125]
	v_mfma_f32_16x16x32_bf16 v[122:125], v[158:161], v[190:193], v[122:125]
	v_mfma_f32_16x16x32_bf16 v[118:121], v[146:149], v[194:197], v[118:121]
	v_mfma_f32_16x16x32_bf16 v[118:121], v[150:153], v[200:203], v[118:121]
	v_mfma_f32_16x16x32_bf16 v[110:113], v[154:157], v[194:197], v[110:113]
	v_mfma_f32_16x16x32_bf16 v[110:113], v[158:161], v[200:203], v[110:113]
	v_mfma_f32_16x16x32_bf16 v[76:79], v[146:149], v[206:209], v[76:79]
	v_mfma_f32_16x16x32_bf16 v[76:79], v[150:153], v[210:213], v[76:79]
	v_mfma_f32_16x16x32_bf16 v[72:75], v[154:157], v[206:209], v[72:75]
	v_mfma_f32_16x16x32_bf16 v[72:75], v[158:161], v[210:213], v[72:75]
	s_setprio 0
	s_setprio 1
	v_mfma_f32_16x16x32_bf16 v[88:91], v[162:165], v[178:181], v[88:91]
	v_mfma_f32_16x16x32_bf16 v[88:91], v[166:169], v[182:185], v[88:91]
	v_mfma_f32_16x16x32_bf16 v[84:87], v[170:173], v[178:181], v[84:87]
	v_mfma_f32_16x16x32_bf16 v[84:87], v[174:177], v[182:185], v[84:87]
	v_mfma_f32_16x16x32_bf16 v[114:117], v[162:165], v[186:189], v[114:117]
	v_mfma_f32_16x16x32_bf16 v[114:117], v[166:169], v[190:193], v[114:117]
	v_mfma_f32_16x16x32_bf16 v[106:109], v[170:173], v[186:189], v[106:109]
	v_mfma_f32_16x16x32_bf16 v[106:109], v[174:177], v[190:193], v[106:109]
	v_mfma_f32_16x16x32_bf16 v[102:105], v[162:165], v[194:197], v[102:105]
	v_mfma_f32_16x16x32_bf16 v[102:105], v[166:169], v[200:203], v[102:105]
	v_mfma_f32_16x16x32_bf16 v[80:83], v[170:173], v[194:197], v[80:83]
	v_mfma_f32_16x16x32_bf16 v[80:83], v[174:177], v[200:203], v[80:83]
	v_mfma_f32_16x16x32_bf16 v[68:71], v[162:165], v[206:209], v[68:71]
	v_mfma_f32_16x16x32_bf16 v[68:71], v[166:169], v[210:213], v[68:71]
	s_setprio 2
	s_barrier
; #define PG8_STAGE(bufoff, gbase, voff) do { _Pragma("unroll") for (int _i = 0; _i < 2; ++_i) \
;         __builtin_amdgcn_global_load_lds((const unsigned*)((const char*)(gbase) + (voff)[_i]), (PG8_LAS unsigned*)(lds + (bufoff) + ldsw + _i * 8192), 16, 0, 0); } while (0)
; #define PG8_LDA(dst, b, h) do { _Pragma("unroll") for (int m = 0; m < 4; ++m) _Pragma("unroll") for (int k = 0; k < 2; ++k) dst[m][k] = *(const PG8_LAS bf16x8*)(lds + PG8_SA(b, h) + aoff + m * 2048 + k * 1024); } while (0)
; #define PG8_WAIT_V(n) asm volatile("s_waitcnt vmcnt(" #n ")" ::: "memory")
; #define PG8_WAIT_L(n) asm volatile("s_waitcnt lgkmcnt(" #n ")" ::: "memory")
; #define PG8_BAR __builtin_amdgcn_s_barrier()
; template <class Epi, class Sched, bool ALIGN_EPI = true, bool SP2 = true>
; __device__ __forceinline__ void gemm_phase(PG8_LAS unsigned char* lds, const Gemm g, const Sched& S, const Epi& E, const int tid) {
;     ...
;         for (int t = 0; t < nt; t += 2) {
;             const bool last = (t == nt - 2);
;             const char* a1 = cA + (size_t)(t + 1) * kstep;
;             const char* a2 = last ? nA : cA + (size_t)(t + 2) * kstep; const char* b2 = last ? nB : cB + (size_t)(t + 2) * kstep;
;             const char* a3 = a2 + kstep; const char* b3 = b2 + kstep;
;             if (last && has_next) S.a_ready(nxt);
;             if constexpr (SP2) {
;             PG8_LDB(B0, 0, 0); PG8_LDB(B1, 0, 1); PG8_SCHED; PG8_LDA(At, 0, 0); PG8_STAGE(PG8_SA(1, 1), a1 + hstepA, voffA);
;             PG8_WAIT_V(8); PG8_WAIT_L(0); PG8_BAR; PG8_MMA(0, 0, At, B0); PG8_MMA(0, 1, At, B1); PG8_BAR; PG8_SCHED;
;             PG8_LDA(At, 0, 1); PG8_STAGE(PG8_SB(0, 0), b2, voffB); PG8_STAGE(PG8_SB(0, 1), b2 + hstepB, voffB); PG8_STAGE(PG8_SA(0, 0), a2, voffA);
;             PG8_WAIT_V(8); PG8_WAIT_L(0); PG8_BAR; PG8_MMA(1, 0, At, B0); PG8_MMA(1, 1, At, B1); PG8_BAR; PG8_SCHED;
;             PG8_LDB(B0, 1, 0); PG8_LDB(B1, 1, 1); PG8_SCHED; PG8_LDA(At, 1, 0); PG8_STAGE(PG8_SA(0, 1), a2 + hstepA, voffA);
;             PG8_WAIT_V(8); PG8_WAIT_L(0); PG8_BAR; PG8_MMA(0, 0, At, B0); PG8_MMA(0, 1, At, B1); PG8_BAR; PG8_SCHED;
;             PG8_LDA(At, 1, 1); PG8_STAGE(PG8_SB(1, 0), b3, voffB); PG8_STAGE(PG8_SB(1, 1), b3 + hstepB, voffB); PG8_STAGE(PG8_SA(1, 0), a3, voffA);
;             PG8_WAIT_V(8); PG8_WAIT_L(0); PG8_BAR; PG8_MMA(1, 0, At, B0); PG8_MMA(1, 1, At, B1); PG8_BAR; PG8_SCHED;
	v_mfma_f32_16x16x32_bf16 v[64:67], v[170:173], v[206:209], v[64:67]
	v_mfma_f32_16x16x32_bf16 v[64:67], v[174:177], v[210:213], v[64:67]
	s_setprio 0
	s_add_i32 s30, s30, s24
	v_lshl_add_u64 v[98:99], v[98:99], 0, s[4:5]
	s_mov_b32 m0, s30
	ds_read_b128 v[178:181], v145 offset:49152
	ds_read_b128 v[182:185], v145 offset:50176
	ds_read_b128 v[186:189], v145 offset:51200
	ds_read_b128 v[190:193], v145 offset:52224
	ds_read_b128 v[194:197], v145 offset:53248
	ds_read_b128 v[200:203], v145 offset:54272
	ds_read_b128 v[206:209], v145 offset:55296
	ds_read_b128 v[210:213], v145 offset:56320
	global_load_lds_dwordx4 v[98:99], off
	s_add_i32 m0, s30, 0x2000
	s_add_u32 s82, s82, 0x80080
	v_lshl_add_u64 v[98:99], v[224:225], 0, s[4:5]
	s_addc_u32 s83, s83, 0
	s_add_i32 s30, s31, s24
	global_load_lds_dwordx4 v[98:99], off
	v_lshl_add_u64 v[98:99], s[82:83], 0, v[100:101]
	s_mov_b32 m0, s30
	s_nop 0
	global_load_lds_dwordx4 v[98:99], off
	v_lshl_add_u64 v[98:99], s[82:83], 0, v[134:135]
	s_add_i32 m0, s30, 0x2000
	s_nop 0
	global_load_lds_dwordx4 v[98:99], off
	v_lshl_add_u64 v[98:99], v[226:227], 0, s[4:5]
	s_mov_b32 m0, s90
	s_nop 0
	global_load_lds_dwordx4 v[98:99], off
	v_lshl_add_u64 v[98:99], v[228:229], 0, s[4:5]
	s_mov_b32 m0, s91
	s_nop 0
	global_load_lds_dwordx4 v[98:99], off
	s_waitcnt vmcnt(8)
	s_waitcnt lgkmcnt(0)
	s_barrier
	s_setprio 1
	v_mfma_f32_16x16x32_bf16 v[56:59], v[146:149], v[178:181], v[56:59]
	v_mfma_f32_16x16x32_bf16 v[56:59], v[150:153], v[182:185], v[56:59]
	v_mfma_f32_16x16x32_bf16 v[60:63], v[154:157], v[178:181], v[60:63]
	v_mfma_f32_16x16x32_bf16 v[60:63], v[158:161], v[182:185], v[60:63]
	v_mfma_f32_16x16x32_bf16 v[44:47], v[146:149], v[186:189], v[44:47]
	v_mfma_f32_16x16x32_bf16 v[44:47], v[150:153], v[190:193], v[44:47]
	v_mfma_f32_16x16x32_bf16 v[40:43], v[154:157], v[186:189], v[40:43]
	v_mfma_f32_16x16x32_bf16 v[40:43], v[158:161], v[190:193], v[40:43]
	v_mfma_f32_16x16x32_bf16 v[28:31], v[146:149], v[194:197], v[28:31]
	v_mfma_f32_16x16x32_bf16 v[28:31], v[150:153], v[200:203], v[28:31]
	v_mfma_f32_16x16x32_bf16 v[24:27], v[154:157], v[194:197], v[24:27]
	v_mfma_f32_16x16x32_bf16 v[24:27], v[158:161], v[200:203], v[24:27]
	v_mfma_f32_16x16x32_bf16 v[12:15], v[146:149], v[206:209], v[12:15]
	v_mfma_f32_16x16x32_bf16 v[12:15], v[150:153], v[210:213], v[12:15]
	v_mfma_f32_16x16x32_bf16 v[8:11], v[154:157], v[206:209], v[8:11]
	v_mfma_f32_16x16x32_bf16 v[8:11], v[158:161], v[210:213], v[8:11]
	s_setprio 0
	s_setprio 1
	v_mfma_f32_16x16x32_bf16 v[52:55], v[162:165], v[178:181], v[52:55]
	v_mfma_f32_16x16x32_bf16 v[52:55], v[166:169], v[182:185], v[52:55]
	v_mfma_f32_16x16x32_bf16 v[48:51], v[170:173], v[178:181], v[48:51]
	v_mfma_f32_16x16x32_bf16 v[48:51], v[174:177], v[182:185], v[48:51]
	v_mfma_f32_16x16x32_bf16 v[36:39], v[162:165], v[186:189], v[36:39]
	v_mfma_f32_16x16x32_bf16 v[36:39], v[166:169], v[190:193], v[36:39]
	v_mfma_f32_16x16x32_bf16 v[32:35], v[170:173], v[186:189], v[32:35]
	v_mfma_f32_16x16x32_bf16 v[32:35], v[174:177], v[190:193], v[32:35]
	v_mfma_f32_16x16x32_bf16 v[20:23], v[162:165], v[194:197], v[20:23]
	v_mfma_f32_16x16x32_bf16 v[20:23], v[166:169], v[200:203], v[20:23]
	v_mfma_f32_16x16x32_bf16 v[16:19], v[170:173], v[194:197], v[16:19]
	v_mfma_f32_16x16x32_bf16 v[16:19], v[174:177], v[200:203], v[16:19]
	v_mfma_f32_16x16x32_bf16 v[4:7], v[162:165], v[206:209], v[4:7]
	v_mfma_f32_16x16x32_bf16 v[4:7], v[166:169], v[210:213], v[4:7]
	s_setprio 2
	s_barrier
	v_mfma_f32_16x16x32_bf16 v[0:3], v[170:173], v[206:209], v[0:3]
	v_mfma_f32_16x16x32_bf16 v[0:3], v[174:177], v[210:213], v[0:3]
	s_setprio 0
	s_add_u32 s80, s80, 0x100
	s_addc_u32 s81, s81, 0
	s_add_u32 s59, s59, 0x100
	s_addc_u32 s61, s61, 0
	s_cmp_ge_i32 s63, s57
	s_mov_b32 s82, s63
	s_cbranch_scc0 .LBB0_1077

; #define PG8_STAGE(bufoff, gbase, voff) do { _Pragma("unroll") for (int _i = 0; _i < 2; ++_i) \
;         __builtin_amdgcn_global_load_lds((const unsigned*)((const char*)(gbase) + (voff)[_i]), (PG8_LAS unsigned*)(lds + (bufoff) + ldsw + _i * 8192), 16, 0, 0); } while (0)
; #define PG8_LDA(dst, b, h) do { _Pragma("unroll") for (int m = 0; m < 4; ++m) _Pragma("unroll") for (int k = 0; k < 2; ++k) dst[m][k] = *(const PG8_LAS bf16x8*)(lds + PG8_SA(b, h) + aoff + m * 2048 + k * 1024); } while (0)
; #define PG8_WAIT_V(n) asm volatile("s_waitcnt vmcnt(" #n ")" ::: "memory")
; #define PG8_WAIT_L(n) asm volatile("s_waitcnt lgkmcnt(" #n ")" ::: "memory")
; #define PG8_BAR __builtin_amdgcn_s_barrier()
; template <class Epi, class Sched, bool ALIGN_EPI = true, bool SP2 = true>
; __device__ __forceinline__ void gemm_phase(PG8_LAS unsigned char* lds, const Gemm g, const Sched& S, const Epi& E, const int tid) {
;     ...
;         for (int t = 0; t < nt; t += 2) {
;             const bool last = (t == nt - 2);
;             const char* a1 = cA + (size_t)(t + 1) * kstep;
;             const char* a2 = last ? nA : cA + (size_t)(t + 2) * kstep; const char* b2 = last ? nB : cB + (size_t)(t + 2) * kstep;
;             const char* a3 = a2 + kstep; const char* b3 = b2 + kstep;
;             if (last && has_next) S.a_ready(nxt);
;             if constexpr (SP2) {
;             PG8_LDB(B0, 0, 0); PG8_LDB(B1, 0, 1); PG8_SCHED; PG8_LDA(At, 0, 0); PG8_STAGE(PG8_SA(1, 1), a1 + hstepA, voffA);
;             PG8_WAIT_V(8); PG8_WAIT_L(0); PG8_BAR; PG8_MMA(0, 0, At, B0); PG8_MMA(0, 1, At, B1); PG8_BAR; PG8_SCHED;
;             PG8_LDA(At, 0, 1); PG8_STAGE(PG8_SB(0, 0), b2, voffB); PG8_STAGE(PG8_SB(0, 1), b2 + hstepB, voffB); PG8_STAGE(PG8_SA(0, 0), a2, voffA);
;             PG8_WAIT_V(8); PG8_WAIT_L(0); PG8_BAR; PG8_MMA(1, 0, At, B0); PG8_MMA(1, 1, At, B1); PG8_BAR; PG8_SCHED;
;             PG8_LDB(B0, 1, 0); PG8_LDB(B1, 1, 1); PG8_SCHED; PG8_LDA(At, 1, 0); PG8_STAGE(PG8_SA(0, 1), a2 + hstepA, voffA);
;             PG8_WAIT_V(8); PG8_WAIT_L(0); PG8_BAR; PG8_MMA(0, 0, At, B0); PG8_MMA(0, 1, At, B1); PG8_BAR; PG8_SCHED;
;             PG8_LDA(At, 1, 1); PG8_STAGE(PG8_SB(1, 0), b3, voffB); PG8_STAGE(PG8_SB(1, 1), b3 + hstepB, voffB); PG8_STAGE(PG8_SA(1, 0), a3, voffA);
;             PG8_WAIT_V(8); PG8_WAIT_L(0); PG8_BAR; PG8_MMA(1, 0, At, B0); PG8_MMA(1, 1, At, B1); PG8_BAR; PG8_SCHED;
.LBB0_1319:
	s_add_u32 s28, s62, 0xfff80080
	s_addc_u32 s29, s63, -1
	s_add_i32 s30, 0, 0x10000
	s_cmp_eq_u32 s52, 28
	s_cselect_b32 s67, s24, s29
	s_cselect_b32 s66, s25, s28
	v_add_u32_e32 v145, s30, v142
	s_cselect_b32 s65, s26, s51
	s_cselect_b32 s64, s27, s49
	s_add_i32 s31, 0, 0x14000
	ds_read_b128 v[146:149], v145
	ds_read_b128 v[150:153], v145 offset:1024
	ds_read_b128 v[154:157], v145 offset:2048
	ds_read_b128 v[158:161], v145 offset:3072
	v_add_u32_e32 v145, s31, v142
	ds_read_b128 v[162:165], v145
	ds_read_b128 v[166:169], v145 offset:1024
	ds_read_b128 v[170:173], v145 offset:2048
	ds_read_b128 v[174:177], v145 offset:3072
	v_lshl_add_u64 v[222:223], s[62:63], 0, v[138:139]
	s_add_i32 m0, s22, 0xc000
	ds_read_b128 v[178:181], v144
	ds_read_b128 v[182:185], v144 offset:1024
	ds_read_b128 v[186:189], v144 offset:2048
	ds_read_b128 v[190:193], v144 offset:3072
	ds_read_b128 v[194:197], v144 offset:4096
	ds_read_b128 v[200:203], v144 offset:5120
	ds_read_b128 v[206:209], v144 offset:6144
	ds_read_b128 v[210:213], v144 offset:7168
	global_load_lds_dwordx4 v[222:223], off
	v_lshl_add_u64 v[222:223], s[62:63], 0, v[140:141]
	s_add_i32 m0, s22, 0xe000
	s_nop 0
	global_load_lds_dwordx4 v[222:223], off
	s_waitcnt vmcnt(8)
	s_waitcnt lgkmcnt(0)
	s_barrier
	s_setprio 1
	v_mfma_f32_16x16x32_bf16 v[126:129], v[146:149], v[178:181], v[126:129]
	v_mfma_f32_16x16x32_bf16 v[126:129], v[150:153], v[182:185], v[126:129]
	v_mfma_f32_16x16x32_bf16 v[118:121], v[154:157], v[178:181], v[118:121]
	v_mfma_f32_16x16x32_bf16 v[118:121], v[158:161], v[182:185], v[118:121]
	v_mfma_f32_16x16x32_bf16 v[110:113], v[146:149], v[186:189], v[110:113]
	v_mfma_f32_16x16x32_bf16 v[110:113], v[150:153], v[190:193], v[110:113]
	v_mfma_f32_16x16x32_bf16 v[102:105], v[154:157], v[186:189], v[102:105]
	v_mfma_f32_16x16x32_bf16 v[102:105], v[158:161], v[190:193], v[102:105]
	v_mfma_f32_16x16x32_bf16 v[92:95], v[146:149], v[194:197], v[92:95]
	v_mfma_f32_16x16x32_bf16 v[92:95], v[150:153], v[200:203], v[92:95]
	v_mfma_f32_16x16x32_bf16 v[84:87], v[154:157], v[194:197], v[84:87]
	v_mfma_f32_16x16x32_bf16 v[84:87], v[158:161], v[200:203], v[84:87]
	v_mfma_f32_16x16x32_bf16 v[76:79], v[146:149], v[206:209], v[76:79]
	v_mfma_f32_16x16x32_bf16 v[76:79], v[150:153], v[210:213], v[76:79]
	v_mfma_f32_16x16x32_bf16 v[68:71], v[154:157], v[206:209], v[68:71]
	v_mfma_f32_16x16x32_bf16 v[68:71], v[158:161], v[210:213], v[68:71]
	s_setprio 0
	s_setprio 1
	v_mfma_f32_16x16x32_bf16 v[122:125], v[162:165], v[178:181], v[122:125]
	v_mfma_f32_16x16x32_bf16 v[122:125], v[166:169], v[182:185], v[122:125]
	v_mfma_f32_16x16x32_bf16 v[114:117], v[170:173], v[178:181], v[114:117]
	v_mfma_f32_16x16x32_bf16 v[114:117], v[174:177], v[182:185], v[114:117]
	v_mfma_f32_16x16x32_bf16 v[106:109], v[162:165], v[186:189], v[106:109]
	v_mfma_f32_16x16x32_bf16 v[106:109], v[166:169], v[190:193], v[106:109]
	v_mfma_f32_16x16x32_bf16 v[98:101], v[170:173], v[186:189], v[98:101]
	v_mfma_f32_16x16x32_bf16 v[98:101], v[174:177], v[190:193], v[98:101]
	v_mfma_f32_16x16x32_bf16 v[88:91], v[162:165], v[194:197], v[88:91]
	v_mfma_f32_16x16x32_bf16 v[88:91], v[166:169], v[200:203], v[88:91]
	v_mfma_f32_16x16x32_bf16 v[80:83], v[170:173], v[194:197], v[80:83]
	v_mfma_f32_16x16x32_bf16 v[80:83], v[174:177], v[200:203], v[80:83]
	v_mfma_f32_16x16x32_bf16 v[72:75], v[162:165], v[206:209], v[72:75]
	v_mfma_f32_16x16x32_bf16 v[72:75], v[166:169], v[210:213], v[72:75]
	s_setprio 2
	s_barrier
	v_mfma_f32_16x16x32_bf16 v[64:67], v[170:173], v[206:209], v[64:67]
	v_mfma_f32_16x16x32_bf16 v[64:67], v[174:177], v[210:213], v[64:67]
	s_setprio 0
	s_add_i32 s28, s30, s21
	v_lshl_add_u64 v[222:223], s[64:65], 0, v[134:135]
	s_mov_b32 m0, s28
	ds_read_b128 v[178:181], v144 offset:16384
	ds_read_b128 v[182:185], v144 offset:17408
	ds_read_b128 v[186:189], v144 offset:18432
	ds_read_b128 v[190:193], v144 offset:19456
	ds_read_b128 v[194:197], v144 offset:20480
	ds_read_b128 v[200:203], v144 offset:21504
	ds_read_b128 v[206:209], v144 offset:22528
	ds_read_b128 v[210:213], v144 offset:23552
	global_load_lds_dwordx4 v[222:223], off
	s_add_i32 m0, s28, 0x2000
	s_add_u32 s28, s64, 0x80000
	v_lshl_add_u64 v[224:225], s[64:65], 0, v[130:131]
	s_addc_u32 s29, s65, 0
	s_add_i32 s30, s31, s21
	global_load_lds_dwordx4 v[224:225], off
	v_lshl_add_u64 v[226:227], s[28:29], 0, v[134:135]
	s_mov_b32 m0, s30
	v_lshl_add_u64 v[228:229], s[66:67], 0, v[132:133]
	global_load_lds_dwordx4 v[226:227], off
	v_lshl_add_u64 v[226:227], s[28:29], 0, v[130:131]
	s_add_i32 m0, s30, 0x2000
	s_nop 0
	global_load_lds_dwordx4 v[226:227], off
	v_lshl_add_u64 v[226:227], s[66:67], 0, v[136:137]
	s_mov_b32 m0, s22
	s_nop 0
	global_load_lds_dwordx4 v[226:227], off
	s_mov_b32 m0, s23
	s_nop 0
	global_load_lds_dwordx4 v[228:229], off
	s_waitcnt vmcnt(8)
	s_waitcnt lgkmcnt(0)
	s_barrier
; #define PG8_STAGE(bufoff, gbase, voff) do { _Pragma("unroll") for (int _i = 0; _i < 2; ++_i) \
;         __builtin_amdgcn_global_load_lds((const unsigned*)((const char*)(gbase) + (voff)[_i]), (PG8_LAS unsigned*)(lds + (bufoff) + ldsw + _i * 8192), 16, 0, 0); } while (0)
; #define PG8_LDA(dst, b, h) do { _Pragma("unroll") for (int m = 0; m < 4; ++m) _Pragma("unroll") for (int k = 0; k < 2; ++k) dst[m][k] = *(const PG8_LAS bf16x8*)(lds + PG8_SA(b, h) + aoff + m * 2048 + k * 1024); } while (0)
; #define PG8_LDB(dst, b, h) do { _Pragma("unroll") for (int n = 0; n < 2; ++n) _Pragma("unroll") for (int k = 0; k < 2; ++k) dst[n][k] = *(const PG8_LAS bf16x8*)(lds + PG8_SB(b, h) + boff + n * 2048 + k * 1024); } while (0)
; #define PG8_MMA(ai, bj, At, Bt) do { __builtin_amdgcn_s_setprio(1); _Pragma("unroll") for (int m = 0; m < 4; ++m) _Pragma("unroll") for (int n = 0; n < 2; ++n) _Pragma("unroll") for (int k = 0; k < 2; ++k) \
;         acc[ai][bj][m][n] = __builtin_amdgcn_mfma_f32_16x16x32_bf16(Bt[n][k], At[m][k], acc[ai][bj][m][n], 0, 0, 0); __builtin_amdgcn_s_setprio(0); } while (0)
; template <class Epi, class Sched, bool ALIGN_EPI = true, bool SP2 = true>
; __device__ __forceinline__ void gemm_phase(PG8_LAS unsigned char* lds, const Gemm g, const Sched& S, const Epi& E, const int tid) {
;     ...
;             if constexpr (SP2) {
;             PG8_LDB(B0, 0, 0); PG8_LDB(B1, 0, 1); PG8_SCHED; PG8_LDA(At, 0, 0); PG8_STAGE(PG8_SA(1, 1), a1 + hstepA, voffA);
;             PG8_WAIT_V(8); PG8_WAIT_L(0); PG8_BAR; PG8_MMA(0, 0, At, B0); PG8_MMA(0, 1, At, B1); PG8_BAR; PG8_SCHED;
;             PG8_LDA(At, 0, 1); PG8_STAGE(PG8_SB(0, 0), b2, voffB); PG8_STAGE(PG8_SB(0, 1), b2 + hstepB, voffB); PG8_STAGE(PG8_SA(0, 0), a2, voffA);
;             PG8_WAIT_V(8); PG8_WAIT_L(0); PG8_BAR; PG8_MMA(1, 0, At, B0); PG8_MMA(1, 1, At, B1); PG8_BAR; PG8_SCHED;
;             PG8_LDB(B0, 1, 0); PG8_LDB(B1, 1, 1); PG8_SCHED; PG8_LDA(At, 1, 0); PG8_STAGE(PG8_SA(0, 1), a2 + hstepA, voffA);
;             PG8_WAIT_V(8); PG8_WAIT_L(0); PG8_BAR; PG8_MMA(0, 0, At, B0); PG8_MMA(0, 1, At, B1); PG8_BAR; PG8_SCHED;
;             PG8_LDA(At, 1, 1); PG8_STAGE(PG8_SB(1, 0), b3, voffB); PG8_STAGE(PG8_SB(1, 1), b3 + hstepB, voffB); PG8_STAGE(PG8_SA(1, 0), a3, voffA);
;             PG8_WAIT_V(8); PG8_WAIT_L(0); PG8_BAR; PG8_MMA(1, 0, At, B0); PG8_MMA(1, 1, At, B1); PG8_BAR; PG8_SCHED;
	s_setprio 1
	v_mfma_f32_16x16x32_bf16 v[60:63], v[146:149], v[178:181], v[60:63]
	v_mfma_f32_16x16x32_bf16 v[60:63], v[150:153], v[182:185], v[60:63]
	v_mfma_f32_16x16x32_bf16 v[52:55], v[154:157], v[178:181], v[52:55]
	v_mfma_f32_16x16x32_bf16 v[52:55], v[158:161], v[182:185], v[52:55]
	v_mfma_f32_16x16x32_bf16 v[44:47], v[146:149], v[186:189], v[44:47]
	v_mfma_f32_16x16x32_bf16 v[44:47], v[150:153], v[190:193], v[44:47]
	v_mfma_f32_16x16x32_bf16 v[36:39], v[154:157], v[186:189], v[36:39]
	v_mfma_f32_16x16x32_bf16 v[36:39], v[158:161], v[190:193], v[36:39]
	v_mfma_f32_16x16x32_bf16 v[28:31], v[146:149], v[194:197], v[28:31]
	v_mfma_f32_16x16x32_bf16 v[28:31], v[150:153], v[200:203], v[28:31]
	v_mfma_f32_16x16x32_bf16 v[20:23], v[154:157], v[194:197], v[20:23]
	v_mfma_f32_16x16x32_bf16 v[20:23], v[158:161], v[200:203], v[20:23]
	v_mfma_f32_16x16x32_bf16 v[12:15], v[146:149], v[206:209], v[12:15]
	v_mfma_f32_16x16x32_bf16 v[12:15], v[150:153], v[210:213], v[12:15]
	v_mfma_f32_16x16x32_bf16 v[4:7], v[154:157], v[206:209], v[4:7]
	v_mfma_f32_16x16x32_bf16 v[4:7], v[158:161], v[210:213], v[4:7]
	s_setprio 0
	s_setprio 1
	v_mfma_f32_16x16x32_bf16 v[56:59], v[162:165], v[178:181], v[56:59]
	v_mfma_f32_16x16x32_bf16 v[56:59], v[166:169], v[182:185], v[56:59]
	v_mfma_f32_16x16x32_bf16 v[48:51], v[170:173], v[178:181], v[48:51]
	v_mfma_f32_16x16x32_bf16 v[48:51], v[174:177], v[182:185], v[48:51]
	v_mfma_f32_16x16x32_bf16 v[40:43], v[162:165], v[186:189], v[40:43]
	v_mfma_f32_16x16x32_bf16 v[40:43], v[166:169], v[190:193], v[40:43]
	v_mfma_f32_16x16x32_bf16 v[32:35], v[170:173], v[186:189], v[32:35]
	v_mfma_f32_16x16x32_bf16 v[32:35], v[174:177], v[190:193], v[32:35]
	v_mfma_f32_16x16x32_bf16 v[24:27], v[162:165], v[194:197], v[24:27]
	v_mfma_f32_16x16x32_bf16 v[24:27], v[166:169], v[200:203], v[24:27]
	v_mfma_f32_16x16x32_bf16 v[16:19], v[170:173], v[194:197], v[16:19]
	v_mfma_f32_16x16x32_bf16 v[16:19], v[174:177], v[200:203], v[16:19]
	v_mfma_f32_16x16x32_bf16 v[8:11], v[162:165], v[206:209], v[8:11]
	v_mfma_f32_16x16x32_bf16 v[8:11], v[166:169], v[210:213], v[8:11]
	s_setprio 2
	s_barrier
	v_mfma_f32_16x16x32_bf16 v[0:3], v[170:173], v[206:209], v[0:3]
	v_mfma_f32_16x16x32_bf16 v[0:3], v[174:177], v[210:213], v[0:3]
	s_setprio 0
	s_add_i32 s30, 0, 0x18000
	v_add_u32_e32 v145, s30, v142
	s_add_i32 s31, 0, 0x1c000
	ds_read_b128 v[146:149], v145
	ds_read_b128 v[150:153], v145 offset:1024
	ds_read_b128 v[154:157], v145 offset:2048
	ds_read_b128 v[158:161], v145 offset:3072
	v_add_u32_e32 v145, s31, v142
	ds_read_b128 v[162:165], v145
	ds_read_b128 v[166:169], v145 offset:1024
	ds_read_b128 v[170:173], v145 offset:2048
	ds_read_b128 v[174:177], v145 offset:3072
	s_add_u32 s28, s66, 0x80000
	s_addc_u32 s29, s67, 0
	s_mov_b32 m0, s61
	v_lshl_add_u64 v[230:231], s[28:29], 0, v[136:137]
	ds_read_b128 v[178:181], v144 offset:32768
	ds_read_b128 v[182:185], v144 offset:33792
	ds_read_b128 v[186:189], v144 offset:34816
	ds_read_b128 v[190:193], v144 offset:35840
	ds_read_b128 v[194:197], v144 offset:36864
	ds_read_b128 v[200:203], v144 offset:37888
	ds_read_b128 v[206:209], v144 offset:38912
	ds_read_b128 v[210:213], v144 offset:39936
	global_load_lds_dwordx4 v[230:231], off
	v_lshl_add_u64 v[230:231], s[28:29], 0, v[132:133]
	s_mov_b32 m0, s70
	s_nop 0
	global_load_lds_dwordx4 v[230:231], off
	s_waitcnt vmcnt(8)
	s_waitcnt lgkmcnt(0)
	s_barrier
	s_setprio 1
	v_mfma_f32_16x16x32_bf16 v[126:129], v[146:149], v[178:181], v[126:129]
	v_mfma_f32_16x16x32_bf16 v[126:129], v[150:153], v[182:185], v[126:129]
	v_mfma_f32_16x16x32_bf16 v[118:121], v[154:157], v[178:181], v[118:121]
	v_mfma_f32_16x16x32_bf16 v[118:121], v[158:161], v[182:185], v[118:121]
	v_mfma_f32_16x16x32_bf16 v[110:113], v[146:149], v[186:189], v[110:113]
	v_mfma_f32_16x16x32_bf16 v[110:113], v[150:153], v[190:193], v[110:113]
	v_mfma_f32_16x16x32_bf16 v[102:105], v[154:157], v[186:189], v[102:105]
	v_mfma_f32_16x16x32_bf16 v[102:105], v[158:161], v[190:193], v[102:105]
	v_mfma_f32_16x16x32_bf16 v[92:95], v[146:149], v[194:197], v[92:95]
	v_mfma_f32_16x16x32_bf16 v[92:95], v[150:153], v[200:203], v[92:95]
	v_mfma_f32_16x16x32_bf16 v[84:87], v[154:157], v[194:197], v[84:87]
	v_mfma_f32_16x16x32_bf16 v[84:87], v[158:161], v[200:203], v[84:87]
	v_mfma_f32_16x16x32_bf16 v[76:79], v[146:149], v[206:209], v[76:79]
	v_mfma_f32_16x16x32_bf16 v[76:79], v[150:153], v[210:213], v[76:79]
	v_mfma_f32_16x16x32_bf16 v[68:71], v[154:157], v[206:209], v[68:71]
	v_mfma_f32_16x16x32_bf16 v[68:71], v[158:161], v[210:213], v[68:71]
	s_setprio 0
	s_setprio 1
	v_mfma_f32_16x16x32_bf16 v[122:125], v[162:165], v[178:181], v[122:125]
	v_mfma_f32_16x16x32_bf16 v[122:125], v[166:169], v[182:185], v[122:125]
	v_mfma_f32_16x16x32_bf16 v[114:117], v[170:173], v[178:181], v[114:117]
	v_mfma_f32_16x16x32_bf16 v[114:117], v[174:177], v[182:185], v[114:117]
	v_mfma_f32_16x16x32_bf16 v[106:109], v[162:165], v[186:189], v[106:109]
	v_mfma_f32_16x16x32_bf16 v[106:109], v[166:169], v[190:193], v[106:109]
	v_mfma_f32_16x16x32_bf16 v[98:101], v[170:173], v[186:189], v[98:101]
	v_mfma_f32_16x16x32_bf16 v[98:101], v[174:177], v[190:193], v[98:101]
	v_mfma_f32_16x16x32_bf16 v[88:91], v[162:165], v[194:197], v[88:91]
	v_mfma_f32_16x16x32_bf16 v[88:91], v[166:169], v[200:203], v[88:91]
	v_mfma_f32_16x16x32_bf16 v[80:83], v[170:173], v[194:197], v[80:83]
	v_mfma_f32_16x16x32_bf16 v[80:83], v[174:177], v[200:203], v[80:83]
	v_mfma_f32_16x16x32_bf16 v[72:75], v[162:165], v[206:209], v[72:75]
	v_mfma_f32_16x16x32_bf16 v[72:75], v[166:169], v[210:213], v[72:75]
	s_setprio 2
	s_barrier
; #define PG8_STAGE(bufoff, gbase, voff) do { _Pragma("unroll") for (int _i = 0; _i < 2; ++_i) \
;         __builtin_amdgcn_global_load_lds((const unsigned*)((const char*)(gbase) + (voff)[_i]), (PG8_LAS unsigned*)(lds + (bufoff) + ldsw + _i * 8192), 16, 0, 0); } while (0)
; #define PG8_LDA(dst, b, h) do { _Pragma("unroll") for (int m = 0; m < 4; ++m) _Pragma("unroll") for (int k = 0; k < 2; ++k) dst[m][k] = *(const PG8_LAS bf16x8*)(lds + PG8_SA(b, h) + aoff + m * 2048 + k * 1024); } while (0)
; #define PG8_WAIT_V(n) asm volatile("s_waitcnt vmcnt(" #n ")" ::: "memory")
; #define PG8_WAIT_L(n) asm volatile("s_waitcnt lgkmcnt(" #n ")" ::: "memory")
; #define PG8_BAR __builtin_amdgcn_s_barrier()
; template <class Epi, class Sched, bool ALIGN_EPI = true, bool SP2 = true>
; __device__ __forceinline__ void gemm_phase(PG8_LAS unsigned char* lds, const Gemm g, const Sched& S, const Epi& E, const int tid) {
;     ...
;         for (int t = 0; t < nt; t += 2) {
;             const bool last = (t == nt - 2);
;             const char* a1 = cA + (size_t)(t + 1) * kstep;
;             const char* a2 = last ? nA : cA + (size_t)(t + 2) * kstep; const char* b2 = last ? nB : cB + (size_t)(t + 2) * kstep;
;             const char* a3 = a2 + kstep; const char* b3 = b2 + kstep;
;             if (last && has_next) S.a_ready(nxt);
;             if constexpr (SP2) {
;             PG8_LDB(B0, 0, 0); PG8_LDB(B1, 0, 1); PG8_SCHED; PG8_LDA(At, 0, 0); PG8_STAGE(PG8_SA(1, 1), a1 + hstepA, voffA);
;             PG8_WAIT_V(8); PG8_WAIT_L(0); PG8_BAR; PG8_MMA(0, 0, At, B0); PG8_MMA(0, 1, At, B1); PG8_BAR; PG8_SCHED;
;             PG8_LDA(At, 0, 1); PG8_STAGE(PG8_SB(0, 0), b2, voffB); PG8_STAGE(PG8_SB(0, 1), b2 + hstepB, voffB); PG8_STAGE(PG8_SA(0, 0), a2, voffA);
;             PG8_WAIT_V(8); PG8_WAIT_L(0); PG8_BAR; PG8_MMA(1, 0, At, B0); PG8_MMA(1, 1, At, B1); PG8_BAR; PG8_SCHED;
;             PG8_LDB(B0, 1, 0); PG8_LDB(B1, 1, 1); PG8_SCHED; PG8_LDA(At, 1, 0); PG8_STAGE(PG8_SA(0, 1), a2 + hstepA, voffA);
;             PG8_WAIT_V(8); PG8_WAIT_L(0); PG8_BAR; PG8_MMA(0, 0, At, B0); PG8_MMA(0, 1, At, B1); PG8_BAR; PG8_SCHED;
;             PG8_LDA(At, 1, 1); PG8_STAGE(PG8_SB(1, 0), b3, voffB); PG8_STAGE(PG8_SB(1, 1), b3 + hstepB, voffB); PG8_STAGE(PG8_SA(1, 0), a3, voffA);
;             PG8_WAIT_V(8); PG8_WAIT_L(0); PG8_BAR; PG8_MMA(1, 0, At, B0); PG8_MMA(1, 1, At, B1); PG8_BAR; PG8_SCHED;
	v_mfma_f32_16x16x32_bf16 v[64:67], v[170:173], v[206:209], v[64:67]
	v_mfma_f32_16x16x32_bf16 v[64:67], v[174:177], v[210:213], v[64:67]
	s_setprio 0
	s_add_i32 s28, s30, s21
	v_lshl_add_u64 v[222:223], v[222:223], 0, s[4:5]
	s_mov_b32 m0, s28
	ds_read_b128 v[178:181], v144 offset:49152
	ds_read_b128 v[182:185], v144 offset:50176
	ds_read_b128 v[186:189], v144 offset:51200
	ds_read_b128 v[190:193], v144 offset:52224
	ds_read_b128 v[194:197], v144 offset:53248
	ds_read_b128 v[200:203], v144 offset:54272
	ds_read_b128 v[206:209], v144 offset:55296
	ds_read_b128 v[210:213], v144 offset:56320
	global_load_lds_dwordx4 v[222:223], off
	s_add_i32 m0, s28, 0x2000
	s_add_u32 s28, s64, 0x80080
	v_lshl_add_u64 v[222:223], v[224:225], 0, s[4:5]
	s_addc_u32 s29, s65, 0
	s_add_i32 s30, s31, s21
	global_load_lds_dwordx4 v[222:223], off
	v_lshl_add_u64 v[222:223], s[28:29], 0, v[134:135]
	s_mov_b32 m0, s30
	s_nop 0
	global_load_lds_dwordx4 v[222:223], off
	v_lshl_add_u64 v[222:223], s[28:29], 0, v[130:131]
	s_add_i32 m0, s30, 0x2000
	s_nop 0
	global_load_lds_dwordx4 v[222:223], off
	v_lshl_add_u64 v[222:223], v[226:227], 0, s[4:5]
	s_mov_b32 m0, s71
	s_nop 0
	global_load_lds_dwordx4 v[222:223], off
	v_lshl_add_u64 v[222:223], v[228:229], 0, s[4:5]
	s_mov_b32 m0, s72
	s_nop 0
	global_load_lds_dwordx4 v[222:223], off
	s_waitcnt vmcnt(8)
	s_waitcnt lgkmcnt(0)
	s_barrier
	s_setprio 1
	v_mfma_f32_16x16x32_bf16 v[60:63], v[146:149], v[178:181], v[60:63]
	v_mfma_f32_16x16x32_bf16 v[60:63], v[150:153], v[182:185], v[60:63]
	v_mfma_f32_16x16x32_bf16 v[52:55], v[154:157], v[178:181], v[52:55]
	v_mfma_f32_16x16x32_bf16 v[52:55], v[158:161], v[182:185], v[52:55]
	v_mfma_f32_16x16x32_bf16 v[44:47], v[146:149], v[186:189], v[44:47]
	v_mfma_f32_16x16x32_bf16 v[44:47], v[150:153], v[190:193], v[44:47]
	v_mfma_f32_16x16x32_bf16 v[36:39], v[154:157], v[186:189], v[36:39]
	v_mfma_f32_16x16x32_bf16 v[36:39], v[158:161], v[190:193], v[36:39]
	v_mfma_f32_16x16x32_bf16 v[28:31], v[146:149], v[194:197], v[28:31]
	v_mfma_f32_16x16x32_bf16 v[28:31], v[150:153], v[200:203], v[28:31]
	v_mfma_f32_16x16x32_bf16 v[20:23], v[154:157], v[194:197], v[20:23]
	v_mfma_f32_16x16x32_bf16 v[20:23], v[158:161], v[200:203], v[20:23]
	v_mfma_f32_16x16x32_bf16 v[12:15], v[146:149], v[206:209], v[12:15]
	v_mfma_f32_16x16x32_bf16 v[12:15], v[150:153], v[210:213], v[12:15]
	v_mfma_f32_16x16x32_bf16 v[4:7], v[154:157], v[206:209], v[4:7]
	v_mfma_f32_16x16x32_bf16 v[4:7], v[158:161], v[210:213], v[4:7]
	s_setprio 0
	s_setprio 1
	v_mfma_f32_16x16x32_bf16 v[56:59], v[162:165], v[178:181], v[56:59]
	v_mfma_f32_16x16x32_bf16 v[56:59], v[166:169], v[182:185], v[56:59]
	v_mfma_f32_16x16x32_bf16 v[48:51], v[170:173], v[178:181], v[48:51]
	v_mfma_f32_16x16x32_bf16 v[48:51], v[174:177], v[182:185], v[48:51]
	v_mfma_f32_16x16x32_bf16 v[40:43], v[162:165], v[186:189], v[40:43]
	v_mfma_f32_16x16x32_bf16 v[40:43], v[166:169], v[190:193], v[40:43]
	v_mfma_f32_16x16x32_bf16 v[32:35], v[170:173], v[186:189], v[32:35]
	v_mfma_f32_16x16x32_bf16 v[32:35], v[174:177], v[190:193], v[32:35]
	v_mfma_f32_16x16x32_bf16 v[24:27], v[162:165], v[194:197], v[24:27]
	v_mfma_f32_16x16x32_bf16 v[24:27], v[166:169], v[200:203], v[24:27]
	v_mfma_f32_16x16x32_bf16 v[16:19], v[170:173], v[194:197], v[16:19]
	v_mfma_f32_16x16x32_bf16 v[16:19], v[174:177], v[200:203], v[16:19]
	v_mfma_f32_16x16x32_bf16 v[8:11], v[162:165], v[206:209], v[8:11]
	v_mfma_f32_16x16x32_bf16 v[8:11], v[166:169], v[210:213], v[8:11]
	s_setprio 2
	s_barrier
	v_mfma_f32_16x16x32_bf16 v[0:3], v[170:173], v[206:209], v[0:3]
	v_mfma_f32_16x16x32_bf16 v[0:3], v[174:177], v[210:213], v[0:3]
	s_setprio 0
	s_add_i32 s52, s52, 2
	s_add_u32 s62, s62, 0x100
	s_addc_u32 s63, s63, 0
	s_add_u32 s49, s49, 0x100
	s_addc_u32 s51, s51, 0
	s_cmp_gt_u32 s52, 29
	s_cbranch_scc0 .LBB0_1319
	s_and_b64 vcc, exec, s[46:47]
	s_cbranch_vccz .LBB0_1322
	s_barrier

; #define PG8_STAGE(bufoff, gbase, voff) do { _Pragma("unroll") for (int _i = 0; _i < 2; ++_i) \
;         __builtin_amdgcn_global_load_lds((const unsigned*)((const char*)(gbase) + (voff)[_i]), (PG8_LAS unsigned*)(lds + (bufoff) + ldsw + _i * 8192), 16, 0, 0); } while (0)
; #define PG8_LDA(dst, b, h) do { _Pragma("unroll") for (int m = 0; m < 4; ++m) _Pragma("unroll") for (int k = 0; k < 2; ++k) dst[m][k] = *(const PG8_LAS bf16x8*)(lds + PG8_SA(b, h) + aoff + m * 2048 + k * 1024); } while (0)
; #define PG8_WAIT_V(n) asm volatile("s_waitcnt vmcnt(" #n ")" ::: "memory")
; #define PG8_WAIT_L(n) asm volatile("s_waitcnt lgkmcnt(" #n ")" ::: "memory")
; #define PG8_BAR __builtin_amdgcn_s_barrier()
; template <class Epi, class Sched, bool ALIGN_EPI = true, bool SP2 = true>
; __device__ __forceinline__ void gemm_phase(PG8_LAS unsigned char* lds, const Gemm g, const Sched& S, const Epi& E, const int tid) {
;     ...
;         for (int t = 0; t < nt; t += 2) {
;             const bool last = (t == nt - 2);
;             const char* a1 = cA + (size_t)(t + 1) * kstep;
;             const char* a2 = last ? nA : cA + (size_t)(t + 2) * kstep; const char* b2 = last ? nB : cB + (size_t)(t + 2) * kstep;
;             const char* a3 = a2 + kstep; const char* b3 = b2 + kstep;
;             if (last && has_next) S.a_ready(nxt);
;             if constexpr (SP2) {
;             PG8_LDB(B0, 0, 0); PG8_LDB(B1, 0, 1); PG8_SCHED; PG8_LDA(At, 0, 0); PG8_STAGE(PG8_SA(1, 1), a1 + hstepA, voffA);
;             PG8_WAIT_V(8); PG8_WAIT_L(0); PG8_BAR; PG8_MMA(0, 0, At, B0); PG8_MMA(0, 1, At, B1); PG8_BAR; PG8_SCHED;
;             PG8_LDA(At, 0, 1); PG8_STAGE(PG8_SB(0, 0), b2, voffB); PG8_STAGE(PG8_SB(0, 1), b2 + hstepB, voffB); PG8_STAGE(PG8_SA(0, 0), a2, voffA);
;             PG8_WAIT_V(8); PG8_WAIT_L(0); PG8_BAR; PG8_MMA(1, 0, At, B0); PG8_MMA(1, 1, At, B1); PG8_BAR; PG8_SCHED;
;             PG8_LDB(B0, 1, 0); PG8_LDB(B1, 1, 1); PG8_SCHED; PG8_LDA(At, 1, 0); PG8_STAGE(PG8_SA(0, 1), a2 + hstepA, voffA);
;             PG8_WAIT_V(8); PG8_WAIT_L(0); PG8_BAR; PG8_MMA(0, 0, At, B0); PG8_MMA(0, 1, At, B1); PG8_BAR; PG8_SCHED;
;             PG8_LDA(At, 1, 1); PG8_STAGE(PG8_SB(1, 0), b3, voffB); PG8_STAGE(PG8_SB(1, 1), b3 + hstepB, voffB); PG8_STAGE(PG8_SA(1, 0), a3, voffA);
;             PG8_WAIT_V(8); PG8_WAIT_L(0); PG8_BAR; PG8_MMA(1, 0, At, B0); PG8_MMA(1, 1, At, B1); PG8_BAR; PG8_SCHED;
.LBB0_1482:
	s_add_i32 s29, s28, 2
	s_add_u32 s64, s62, 0x100
	s_addc_u32 s65, s63, 0
	s_add_i32 s30, 0, 0x10000
	s_cmp_eq_u32 s25, s28
	s_cselect_b32 s69, s41, s65
	s_cselect_b32 s68, s40, s64
	s_cselect_b32 s67, s59, s27
	s_cselect_b32 s66, s58, s26
	s_add_i32 s28, 0, 0x14000
	v_add_u32_e32 v142, s30, v157
	v_add_u32_e32 v154, s28, v157
	ds_read_b128 v[130:133], v142
	ds_read_b128 v[134:137], v142 offset:1024
	ds_read_b128 v[138:141], v142 offset:2048
	ds_read_b128 v[142:145], v142 offset:3072
	ds_read_b128 v[162:165], v154
	ds_read_b128 v[166:169], v154 offset:1024
	ds_read_b128 v[170:173], v154 offset:2048
	ds_read_b128 v[174:177], v154 offset:3072
	v_lshl_add_u64 v[154:155], s[62:63], 0, v[150:151]
	s_add_i32 m0, s20, 0xc000
	ds_read_b128 v[178:181], v160
	ds_read_b128 v[182:185], v160 offset:1024
	ds_read_b128 v[186:189], v160 offset:2048
	ds_read_b128 v[190:193], v160 offset:3072
	ds_read_b128 v[194:197], v160 offset:4096
	ds_read_b128 v[200:203], v160 offset:5120
	ds_read_b128 v[206:209], v160 offset:6144
	ds_read_b128 v[210:213], v160 offset:7168
	global_load_lds_dwordx4 v[154:155], off
	v_lshl_add_u64 v[154:155], s[62:63], 0, v[152:153]
	s_add_i32 m0, s20, 0xe000
	s_nop 0
	global_load_lds_dwordx4 v[154:155], off
	s_waitcnt vmcnt(8)
	s_waitcnt lgkmcnt(0)
	s_barrier
	s_setprio 1
	v_mfma_f32_16x16x32_bf16 v[126:129], v[130:133], v[178:181], v[126:129]
	v_mfma_f32_16x16x32_bf16 v[122:125], v[138:141], v[178:181], v[122:125]
	v_mfma_f32_16x16x32_bf16 v[110:113], v[130:133], v[186:189], v[110:113]
	v_mfma_f32_16x16x32_bf16 v[106:109], v[138:141], v[186:189], v[106:109]
	v_mfma_f32_16x16x32_bf16 v[92:95], v[130:133], v[194:197], v[92:95]
	v_mfma_f32_16x16x32_bf16 v[88:91], v[138:141], v[194:197], v[88:91]
	v_mfma_f32_16x16x32_bf16 v[76:79], v[130:133], v[206:209], v[76:79]
	v_mfma_f32_16x16x32_bf16 v[72:75], v[138:141], v[206:209], v[72:75]
	v_mfma_f32_16x16x32_bf16 v[126:129], v[134:137], v[182:185], v[126:129]
	v_mfma_f32_16x16x32_bf16 v[122:125], v[142:145], v[182:185], v[122:125]
	v_mfma_f32_16x16x32_bf16 v[110:113], v[134:137], v[190:193], v[110:113]
	v_mfma_f32_16x16x32_bf16 v[106:109], v[142:145], v[190:193], v[106:109]
	v_mfma_f32_16x16x32_bf16 v[92:95], v[134:137], v[200:203], v[92:95]
	v_mfma_f32_16x16x32_bf16 v[88:91], v[142:145], v[200:203], v[88:91]
	v_mfma_f32_16x16x32_bf16 v[76:79], v[134:137], v[210:213], v[76:79]
	v_mfma_f32_16x16x32_bf16 v[72:75], v[142:145], v[210:213], v[72:75]
	s_setprio 0
	s_setprio 1
	v_mfma_f32_16x16x32_bf16 v[118:121], v[162:165], v[178:181], v[118:121]
	v_mfma_f32_16x16x32_bf16 v[114:117], v[170:173], v[178:181], v[114:117]
	v_mfma_f32_16x16x32_bf16 v[102:105], v[162:165], v[186:189], v[102:105]
	v_mfma_f32_16x16x32_bf16 v[98:101], v[170:173], v[186:189], v[98:101]
	v_mfma_f32_16x16x32_bf16 v[84:87], v[162:165], v[194:197], v[84:87]
	v_mfma_f32_16x16x32_bf16 v[80:83], v[170:173], v[194:197], v[80:83]
	v_mfma_f32_16x16x32_bf16 v[68:71], v[162:165], v[206:209], v[68:71]
	v_mfma_f32_16x16x32_bf16 v[64:67], v[170:173], v[206:209], v[64:67]
	v_mfma_f32_16x16x32_bf16 v[118:121], v[166:169], v[182:185], v[118:121]
	v_mfma_f32_16x16x32_bf16 v[114:117], v[174:177], v[182:185], v[114:117]
	v_mfma_f32_16x16x32_bf16 v[102:105], v[166:169], v[190:193], v[102:105]
	v_mfma_f32_16x16x32_bf16 v[98:101], v[174:177], v[190:193], v[98:101]
	v_mfma_f32_16x16x32_bf16 v[84:87], v[166:169], v[200:203], v[84:87]
	v_mfma_f32_16x16x32_bf16 v[80:83], v[174:177], v[200:203], v[80:83]
	v_mfma_f32_16x16x32_bf16 v[68:71], v[166:169], v[210:213], v[68:71]
	v_mfma_f32_16x16x32_bf16 v[64:67], v[174:177], v[210:213], v[64:67]
	s_setprio 0
	s_barrier
	s_add_i32 s30, s30, s19
	v_lshl_add_u64 v[154:155], s[66:67], 0, v[146:147]
	s_mov_b32 m0, s30
	ds_read_b128 v[178:181], v160 offset:16384
	ds_read_b128 v[182:185], v160 offset:17408
	ds_read_b128 v[186:189], v160 offset:18432
	ds_read_b128 v[190:193], v160 offset:19456
	ds_read_b128 v[194:197], v160 offset:20480
	ds_read_b128 v[200:203], v160 offset:21504
	ds_read_b128 v[206:209], v160 offset:22528
	ds_read_b128 v[210:213], v160 offset:23552
	global_load_lds_dwordx4 v[154:155], off
	s_add_i32 m0, s30, 0x2000
	s_add_u32 s52, s66, 0x160000
	v_lshl_add_u64 v[222:223], s[66:67], 0, v[148:149]
	s_addc_u32 s53, s67, 0
	s_add_i32 s28, s28, s19
	global_load_lds_dwordx4 v[222:223], off
	v_lshl_add_u64 v[224:225], s[52:53], 0, v[146:147]
	s_mov_b32 m0, s28
	v_lshl_add_u64 v[226:227], s[68:69], 0, v[148:149]
	global_load_lds_dwordx4 v[224:225], off
	v_lshl_add_u64 v[224:225], s[52:53], 0, v[148:149]
	s_add_i32 m0, s28, 0x2000
	s_nop 0
	global_load_lds_dwordx4 v[224:225], off
	v_lshl_add_u64 v[224:225], s[68:69], 0, v[146:147]
	s_mov_b32 m0, s20
	s_nop 0
	global_load_lds_dwordx4 v[224:225], off
	s_mov_b32 m0, s21
	s_nop 0
	global_load_lds_dwordx4 v[226:227], off
	s_waitcnt vmcnt(8)
	s_waitcnt lgkmcnt(0)
	s_barrier
; #define PG8_STAGE(bufoff, gbase, voff) do { _Pragma("unroll") for (int _i = 0; _i < 2; ++_i) \
;         __builtin_amdgcn_global_load_lds((const unsigned*)((const char*)(gbase) + (voff)[_i]), (PG8_LAS unsigned*)(lds + (bufoff) + ldsw + _i * 8192), 16, 0, 0); } while (0)
; #define PG8_LDA(dst, b, h) do { _Pragma("unroll") for (int m = 0; m < 4; ++m) _Pragma("unroll") for (int k = 0; k < 2; ++k) dst[m][k] = *(const PG8_LAS bf16x8*)(lds + PG8_SA(b, h) + aoff + m * 2048 + k * 1024); } while (0)
; #define PG8_LDB(dst, b, h) do { _Pragma("unroll") for (int n = 0; n < 2; ++n) _Pragma("unroll") for (int k = 0; k < 2; ++k) dst[n][k] = *(const PG8_LAS bf16x8*)(lds + PG8_SB(b, h) + boff + n * 2048 + k * 1024); } while (0)
; #define PG8_MMA(ai, bj, At, Bt) do { __builtin_amdgcn_s_setprio(1); _Pragma("unroll") for (int m = 0; m < 4; ++m) _Pragma("unroll") for (int n = 0; n < 2; ++n) _Pragma("unroll") for (int k = 0; k < 2; ++k) \
;         acc[ai][bj][m][n] = __builtin_amdgcn_mfma_f32_16x16x32_bf16(Bt[n][k], At[m][k], acc[ai][bj][m][n], 0, 0, 0); __builtin_amdgcn_s_setprio(0); } while (0)
; template <class Epi, class Sched, bool ALIGN_EPI = true, bool SP2 = true>
; __device__ __forceinline__ void gemm_phase(PG8_LAS unsigned char* lds, const Gemm g, const Sched& S, const Epi& E, const int tid) {
;     ...
;             if constexpr (SP2) {
;             PG8_LDB(B0, 0, 0); PG8_LDB(B1, 0, 1); PG8_SCHED; PG8_LDA(At, 0, 0); PG8_STAGE(PG8_SA(1, 1), a1 + hstepA, voffA);
;             PG8_WAIT_V(8); PG8_WAIT_L(0); PG8_BAR; PG8_MMA(0, 0, At, B0); PG8_MMA(0, 1, At, B1); PG8_BAR; PG8_SCHED;
;             PG8_LDA(At, 0, 1); PG8_STAGE(PG8_SB(0, 0), b2, voffB); PG8_STAGE(PG8_SB(0, 1), b2 + hstepB, voffB); PG8_STAGE(PG8_SA(0, 0), a2, voffA);
;             PG8_WAIT_V(8); PG8_WAIT_L(0); PG8_BAR; PG8_MMA(1, 0, At, B0); PG8_MMA(1, 1, At, B1); PG8_BAR; PG8_SCHED;
;             PG8_LDB(B0, 1, 0); PG8_LDB(B1, 1, 1); PG8_SCHED; PG8_LDA(At, 1, 0); PG8_STAGE(PG8_SA(0, 1), a2 + hstepA, voffA);
;             PG8_WAIT_V(8); PG8_WAIT_L(0); PG8_BAR; PG8_MMA(0, 0, At, B0); PG8_MMA(0, 1, At, B1); PG8_BAR; PG8_SCHED;
;             PG8_LDA(At, 1, 1); PG8_STAGE(PG8_SB(1, 0), b3, voffB); PG8_STAGE(PG8_SB(1, 1), b3 + hstepB, voffB); PG8_STAGE(PG8_SA(1, 0), a3, voffA);
;             PG8_WAIT_V(8); PG8_WAIT_L(0); PG8_BAR; PG8_MMA(1, 0, At, B0); PG8_MMA(1, 1, At, B1); PG8_BAR; PG8_SCHED;
	s_setprio 1
	v_mfma_f32_16x16x32_bf16 v[60:63], v[130:133], v[178:181], v[60:63]
	v_mfma_f32_16x16x32_bf16 v[56:59], v[138:141], v[178:181], v[56:59]
	v_mfma_f32_16x16x32_bf16 v[44:47], v[130:133], v[186:189], v[44:47]
	v_mfma_f32_16x16x32_bf16 v[40:43], v[138:141], v[186:189], v[40:43]
	v_mfma_f32_16x16x32_bf16 v[28:31], v[130:133], v[194:197], v[28:31]
	v_mfma_f32_16x16x32_bf16 v[24:27], v[138:141], v[194:197], v[24:27]
	v_mfma_f32_16x16x32_bf16 v[12:15], v[130:133], v[206:209], v[12:15]
	v_mfma_f32_16x16x32_bf16 v[8:11], v[138:141], v[206:209], v[8:11]
	v_mfma_f32_16x16x32_bf16 v[60:63], v[134:137], v[182:185], v[60:63]
	v_mfma_f32_16x16x32_bf16 v[56:59], v[142:145], v[182:185], v[56:59]
	v_mfma_f32_16x16x32_bf16 v[44:47], v[134:137], v[190:193], v[44:47]
	v_mfma_f32_16x16x32_bf16 v[40:43], v[142:145], v[190:193], v[40:43]
	v_mfma_f32_16x16x32_bf16 v[28:31], v[134:137], v[200:203], v[28:31]
	v_mfma_f32_16x16x32_bf16 v[24:27], v[142:145], v[200:203], v[24:27]
	v_mfma_f32_16x16x32_bf16 v[12:15], v[134:137], v[210:213], v[12:15]
	v_mfma_f32_16x16x32_bf16 v[8:11], v[142:145], v[210:213], v[8:11]
	s_setprio 0
	s_setprio 1
	v_mfma_f32_16x16x32_bf16 v[52:55], v[162:165], v[178:181], v[52:55]
	v_mfma_f32_16x16x32_bf16 v[48:51], v[170:173], v[178:181], v[48:51]
	v_mfma_f32_16x16x32_bf16 v[36:39], v[162:165], v[186:189], v[36:39]
	v_mfma_f32_16x16x32_bf16 v[32:35], v[170:173], v[186:189], v[32:35]
	v_mfma_f32_16x16x32_bf16 v[20:23], v[162:165], v[194:197], v[20:23]
	v_mfma_f32_16x16x32_bf16 v[16:19], v[170:173], v[194:197], v[16:19]
	v_mfma_f32_16x16x32_bf16 v[4:7], v[162:165], v[206:209], v[4:7]
	v_mfma_f32_16x16x32_bf16 v[0:3], v[170:173], v[206:209], v[0:3]
	v_mfma_f32_16x16x32_bf16 v[52:55], v[166:169], v[182:185], v[52:55]
	v_mfma_f32_16x16x32_bf16 v[48:51], v[174:177], v[182:185], v[48:51]
	v_mfma_f32_16x16x32_bf16 v[36:39], v[166:169], v[190:193], v[36:39]
	v_mfma_f32_16x16x32_bf16 v[32:35], v[174:177], v[190:193], v[32:35]
	v_mfma_f32_16x16x32_bf16 v[20:23], v[166:169], v[200:203], v[20:23]
	v_mfma_f32_16x16x32_bf16 v[16:19], v[174:177], v[200:203], v[16:19]
	v_mfma_f32_16x16x32_bf16 v[4:7], v[166:169], v[210:213], v[4:7]
	v_mfma_f32_16x16x32_bf16 v[0:3], v[174:177], v[210:213], v[0:3]
	s_setprio 0
	s_barrier
	s_add_i32 s28, 0, 0x18000
	s_add_i32 s30, 0, 0x1c000
	v_add_u32_e32 v142, s28, v157
	v_add_u32_e32 v161, s30, v157
	ds_read_b128 v[130:133], v142
	ds_read_b128 v[134:137], v142 offset:1024
	ds_read_b128 v[138:141], v142 offset:2048
	ds_read_b128 v[142:145], v142 offset:3072
	ds_read_b128 v[162:165], v161
	ds_read_b128 v[166:169], v161 offset:1024
	ds_read_b128 v[170:173], v161 offset:2048
	ds_read_b128 v[174:177], v161 offset:3072
	s_add_u32 s52, s68, 0x160000
	s_addc_u32 s53, s69, 0
	s_mov_b32 m0, s70
	v_lshl_add_u64 v[228:229], s[52:53], 0, v[146:147]
	ds_read_b128 v[178:181], v160 offset:32768
	ds_read_b128 v[182:185], v160 offset:33792
	ds_read_b128 v[186:189], v160 offset:34816
	ds_read_b128 v[190:193], v160 offset:35840
	ds_read_b128 v[194:197], v160 offset:36864
	ds_read_b128 v[200:203], v160 offset:37888
	ds_read_b128 v[206:209], v160 offset:38912
	ds_read_b128 v[210:213], v160 offset:39936
	global_load_lds_dwordx4 v[228:229], off
	v_lshl_add_u64 v[228:229], s[52:53], 0, v[148:149]
	s_mov_b32 m0, s71
	s_nop 0
	global_load_lds_dwordx4 v[228:229], off
	s_waitcnt vmcnt(8)
	s_waitcnt lgkmcnt(0)
	s_barrier
	s_setprio 1
	v_mfma_f32_16x16x32_bf16 v[126:129], v[130:133], v[178:181], v[126:129]
	v_mfma_f32_16x16x32_bf16 v[122:125], v[138:141], v[178:181], v[122:125]
	v_mfma_f32_16x16x32_bf16 v[110:113], v[130:133], v[186:189], v[110:113]
	v_mfma_f32_16x16x32_bf16 v[106:109], v[138:141], v[186:189], v[106:109]
	v_mfma_f32_16x16x32_bf16 v[92:95], v[130:133], v[194:197], v[92:95]
	v_mfma_f32_16x16x32_bf16 v[88:91], v[138:141], v[194:197], v[88:91]
	v_mfma_f32_16x16x32_bf16 v[76:79], v[130:133], v[206:209], v[76:79]
	v_mfma_f32_16x16x32_bf16 v[72:75], v[138:141], v[206:209], v[72:75]
	v_mfma_f32_16x16x32_bf16 v[126:129], v[134:137], v[182:185], v[126:129]
	v_mfma_f32_16x16x32_bf16 v[122:125], v[142:145], v[182:185], v[122:125]
	v_mfma_f32_16x16x32_bf16 v[110:113], v[134:137], v[190:193], v[110:113]
	v_mfma_f32_16x16x32_bf16 v[106:109], v[142:145], v[190:193], v[106:109]
	v_mfma_f32_16x16x32_bf16 v[92:95], v[134:137], v[200:203], v[92:95]
	v_mfma_f32_16x16x32_bf16 v[88:91], v[142:145], v[200:203], v[88:91]
	v_mfma_f32_16x16x32_bf16 v[76:79], v[134:137], v[210:213], v[76:79]
	v_mfma_f32_16x16x32_bf16 v[72:75], v[142:145], v[210:213], v[72:75]
	s_setprio 0
	s_setprio 1
	v_mfma_f32_16x16x32_bf16 v[118:121], v[162:165], v[178:181], v[118:121]
	v_mfma_f32_16x16x32_bf16 v[114:117], v[170:173], v[178:181], v[114:117]
	v_mfma_f32_16x16x32_bf16 v[102:105], v[162:165], v[186:189], v[102:105]
	v_mfma_f32_16x16x32_bf16 v[98:101], v[170:173], v[186:189], v[98:101]
	v_mfma_f32_16x16x32_bf16 v[84:87], v[162:165], v[194:197], v[84:87]
	v_mfma_f32_16x16x32_bf16 v[80:83], v[170:173], v[194:197], v[80:83]
	v_mfma_f32_16x16x32_bf16 v[68:71], v[162:165], v[206:209], v[68:71]
	v_mfma_f32_16x16x32_bf16 v[64:67], v[170:173], v[206:209], v[64:67]
	v_mfma_f32_16x16x32_bf16 v[118:121], v[166:169], v[182:185], v[118:121]
	v_mfma_f32_16x16x32_bf16 v[114:117], v[174:177], v[182:185], v[114:117]
	v_mfma_f32_16x16x32_bf16 v[102:105], v[166:169], v[190:193], v[102:105]
	v_mfma_f32_16x16x32_bf16 v[98:101], v[174:177], v[190:193], v[98:101]
	v_mfma_f32_16x16x32_bf16 v[84:87], v[166:169], v[200:203], v[84:87]
	v_mfma_f32_16x16x32_bf16 v[80:83], v[174:177], v[200:203], v[80:83]
	v_mfma_f32_16x16x32_bf16 v[68:71], v[166:169], v[210:213], v[68:71]
	v_mfma_f32_16x16x32_bf16 v[64:67], v[174:177], v[210:213], v[64:67]
	s_setprio 0
	s_barrier
; #define PG8_STAGE(bufoff, gbase, voff) do { _Pragma("unroll") for (int _i = 0; _i < 2; ++_i) \
;         __builtin_amdgcn_global_load_lds((const unsigned*)((const char*)(gbase) + (voff)[_i]), (PG8_LAS unsigned*)(lds + (bufoff) + ldsw + _i * 8192), 16, 0, 0); } while (0)
; #define PG8_LDA(dst, b, h) do { _Pragma("unroll") for (int m = 0; m < 4; ++m) _Pragma("unroll") for (int k = 0; k < 2; ++k) dst[m][k] = *(const PG8_LAS bf16x8*)(lds + PG8_SA(b, h) + aoff + m * 2048 + k * 1024); } while (0)
; #define PG8_WAIT_V(n) asm volatile("s_waitcnt vmcnt(" #n ")" ::: "memory")
; #define PG8_WAIT_L(n) asm volatile("s_waitcnt lgkmcnt(" #n ")" ::: "memory")
; #define PG8_BAR __builtin_amdgcn_s_barrier()
; template <class Epi, class Sched, bool ALIGN_EPI = true, bool SP2 = true>
; __device__ __forceinline__ void gemm_phase(PG8_LAS unsigned char* lds, const Gemm g, const Sched& S, const Epi& E, const int tid) {
;     ...
;         for (int t = 0; t < nt; t += 2) {
;             const bool last = (t == nt - 2);
;             const char* a1 = cA + (size_t)(t + 1) * kstep;
;             const char* a2 = last ? nA : cA + (size_t)(t + 2) * kstep; const char* b2 = last ? nB : cB + (size_t)(t + 2) * kstep;
;             const char* a3 = a2 + kstep; const char* b3 = b2 + kstep;
;             if (last && has_next) S.a_ready(nxt);
;             if constexpr (SP2) {
;             PG8_LDB(B0, 0, 0); PG8_LDB(B1, 0, 1); PG8_SCHED; PG8_LDA(At, 0, 0); PG8_STAGE(PG8_SA(1, 1), a1 + hstepA, voffA);
;             PG8_WAIT_V(8); PG8_WAIT_L(0); PG8_BAR; PG8_MMA(0, 0, At, B0); PG8_MMA(0, 1, At, B1); PG8_BAR; PG8_SCHED;
;             PG8_LDA(At, 0, 1); PG8_STAGE(PG8_SB(0, 0), b2, voffB); PG8_STAGE(PG8_SB(0, 1), b2 + hstepB, voffB); PG8_STAGE(PG8_SA(0, 0), a2, voffA);
;             PG8_WAIT_V(8); PG8_WAIT_L(0); PG8_BAR; PG8_MMA(1, 0, At, B0); PG8_MMA(1, 1, At, B1); PG8_BAR; PG8_SCHED;
;             PG8_LDB(B0, 1, 0); PG8_LDB(B1, 1, 1); PG8_SCHED; PG8_LDA(At, 1, 0); PG8_STAGE(PG8_SA(0, 1), a2 + hstepA, voffA);
;             PG8_WAIT_V(8); PG8_WAIT_L(0); PG8_BAR; PG8_MMA(0, 0, At, B0); PG8_MMA(0, 1, At, B1); PG8_BAR; PG8_SCHED;
;             PG8_LDA(At, 1, 1); PG8_STAGE(PG8_SB(1, 0), b3, voffB); PG8_STAGE(PG8_SB(1, 1), b3 + hstepB, voffB); PG8_STAGE(PG8_SA(1, 0), a3, voffA);
;             PG8_WAIT_V(8); PG8_WAIT_L(0); PG8_BAR; PG8_MMA(1, 0, At, B0); PG8_MMA(1, 1, At, B1); PG8_BAR; PG8_SCHED;
	s_add_i32 s28, s28, s19
	v_lshl_add_u64 v[154:155], v[154:155], 0, s[4:5]
	s_mov_b32 m0, s28
	ds_read_b128 v[178:181], v160 offset:49152
	ds_read_b128 v[182:185], v160 offset:50176
	ds_read_b128 v[186:189], v160 offset:51200
	ds_read_b128 v[190:193], v160 offset:52224
	ds_read_b128 v[194:197], v160 offset:53248
	ds_read_b128 v[200:203], v160 offset:54272
	ds_read_b128 v[206:209], v160 offset:55296
	ds_read_b128 v[210:213], v160 offset:56320
	global_load_lds_dwordx4 v[154:155], off
	s_add_i32 m0, s28, 0x2000
	s_add_u32 s52, s66, 0x160080
	v_lshl_add_u64 v[154:155], v[222:223], 0, s[4:5]
	s_addc_u32 s53, s67, 0
	s_add_i32 s28, s30, s19
	global_load_lds_dwordx4 v[154:155], off
	v_lshl_add_u64 v[154:155], s[52:53], 0, v[146:147]
	s_mov_b32 m0, s28
	s_nop 0
	global_load_lds_dwordx4 v[154:155], off
	v_lshl_add_u64 v[154:155], s[52:53], 0, v[148:149]
	s_add_i32 m0, s28, 0x2000
	s_nop 0
	global_load_lds_dwordx4 v[154:155], off
	v_lshl_add_u64 v[154:155], v[224:225], 0, s[4:5]
	s_mov_b32 m0, s83
	s_nop 0
	global_load_lds_dwordx4 v[154:155], off
	v_lshl_add_u64 v[154:155], v[226:227], 0, s[4:5]
	s_mov_b32 m0, s85
	s_nop 0
	global_load_lds_dwordx4 v[154:155], off
	s_waitcnt vmcnt(8)
	s_waitcnt lgkmcnt(0)
	s_barrier
	s_setprio 1
	v_mfma_f32_16x16x32_bf16 v[60:63], v[130:133], v[178:181], v[60:63]
	v_mfma_f32_16x16x32_bf16 v[56:59], v[138:141], v[178:181], v[56:59]
	v_mfma_f32_16x16x32_bf16 v[44:47], v[130:133], v[186:189], v[44:47]
	v_mfma_f32_16x16x32_bf16 v[40:43], v[138:141], v[186:189], v[40:43]
	v_mfma_f32_16x16x32_bf16 v[28:31], v[130:133], v[194:197], v[28:31]
	v_mfma_f32_16x16x32_bf16 v[24:27], v[138:141], v[194:197], v[24:27]
	v_mfma_f32_16x16x32_bf16 v[12:15], v[130:133], v[206:209], v[12:15]
	v_mfma_f32_16x16x32_bf16 v[8:11], v[138:141], v[206:209], v[8:11]
	v_mfma_f32_16x16x32_bf16 v[60:63], v[134:137], v[182:185], v[60:63]
	v_mfma_f32_16x16x32_bf16 v[56:59], v[142:145], v[182:185], v[56:59]
	v_mfma_f32_16x16x32_bf16 v[44:47], v[134:137], v[190:193], v[44:47]
	v_mfma_f32_16x16x32_bf16 v[40:43], v[142:145], v[190:193], v[40:43]
	v_mfma_f32_16x16x32_bf16 v[28:31], v[134:137], v[200:203], v[28:31]
	v_mfma_f32_16x16x32_bf16 v[24:27], v[142:145], v[200:203], v[24:27]
	v_mfma_f32_16x16x32_bf16 v[12:15], v[134:137], v[210:213], v[12:15]
	v_mfma_f32_16x16x32_bf16 v[8:11], v[142:145], v[210:213], v[8:11]
	s_setprio 0
	s_setprio 1
	v_mfma_f32_16x16x32_bf16 v[52:55], v[162:165], v[178:181], v[52:55]
	v_mfma_f32_16x16x32_bf16 v[48:51], v[170:173], v[178:181], v[48:51]
	v_mfma_f32_16x16x32_bf16 v[36:39], v[162:165], v[186:189], v[36:39]
	v_mfma_f32_16x16x32_bf16 v[32:35], v[170:173], v[186:189], v[32:35]
	v_mfma_f32_16x16x32_bf16 v[20:23], v[162:165], v[194:197], v[20:23]
	v_mfma_f32_16x16x32_bf16 v[16:19], v[170:173], v[194:197], v[16:19]
	v_mfma_f32_16x16x32_bf16 v[4:7], v[162:165], v[206:209], v[4:7]
	v_mfma_f32_16x16x32_bf16 v[0:3], v[170:173], v[206:209], v[0:3]
	v_mfma_f32_16x16x32_bf16 v[52:55], v[166:169], v[182:185], v[52:55]
	v_mfma_f32_16x16x32_bf16 v[48:51], v[174:177], v[182:185], v[48:51]
	v_mfma_f32_16x16x32_bf16 v[36:39], v[166:169], v[190:193], v[36:39]
	v_mfma_f32_16x16x32_bf16 v[32:35], v[174:177], v[190:193], v[32:35]
	v_mfma_f32_16x16x32_bf16 v[20:23], v[166:169], v[200:203], v[20:23]
	v_mfma_f32_16x16x32_bf16 v[16:19], v[174:177], v[200:203], v[16:19]
	v_mfma_f32_16x16x32_bf16 v[4:7], v[166:169], v[210:213], v[4:7]
	v_mfma_f32_16x16x32_bf16 v[0:3], v[174:177], v[210:213], v[0:3]
	s_setprio 0
	s_barrier
	s_add_u32 s26, s26, 0x100
	s_addc_u32 s27, s27, 0
	s_cmp_ge_i32 s29, s24
	s_mov_b64 s[62:63], s[64:65]
	s_mov_b32 s28, s29
	s_cbranch_scc0 .LBB0_1482
	s_and_b64 vcc, exec, s[56:57]
	s_cbranch_vccz .LBB0_1485

; #define PG8_STAGE(bufoff, gbase, voff) do { _Pragma("unroll") for (int _i = 0; _i < 2; ++_i) \
;         __builtin_amdgcn_global_load_lds((const unsigned*)((const char*)(gbase) + (voff)[_i]), (PG8_LAS unsigned*)(lds + (bufoff) + ldsw + _i * 8192), 16, 0, 0); } while (0)
; #define PG8_LDA(dst, b, h) do { _Pragma("unroll") for (int m = 0; m < 4; ++m) _Pragma("unroll") for (int k = 0; k < 2; ++k) dst[m][k] = *(const PG8_LAS bf16x8*)(lds + PG8_SA(b, h) + aoff + m * 2048 + k * 1024); } while (0)
; #define PG8_WAIT_V(n) asm volatile("s_waitcnt vmcnt(" #n ")" ::: "memory")
; #define PG8_WAIT_L(n) asm volatile("s_waitcnt lgkmcnt(" #n ")" ::: "memory")
; #define PG8_BAR __builtin_amdgcn_s_barrier()
; template <class Epi, class Sched, bool ALIGN_EPI = true, bool SP2 = true>
; __device__ __forceinline__ void gemm_phase(PG8_LAS unsigned char* lds, const Gemm g, const Sched& S, const Epi& E, const int tid) {
;     ...
;         for (int t = 0; t < nt; t += 2) {
;             const bool last = (t == nt - 2);
;             const char* a1 = cA + (size_t)(t + 1) * kstep;
;             const char* a2 = last ? nA : cA + (size_t)(t + 2) * kstep; const char* b2 = last ? nB : cB + (size_t)(t + 2) * kstep;
;             const char* a3 = a2 + kstep; const char* b3 = b2 + kstep;
;             if (last && has_next) S.a_ready(nxt);
;             if constexpr (SP2) {
;             PG8_LDB(B0, 0, 0); PG8_LDB(B1, 0, 1); PG8_SCHED; PG8_LDA(At, 0, 0); PG8_STAGE(PG8_SA(1, 1), a1 + hstepA, voffA);
;             PG8_WAIT_V(8); PG8_WAIT_L(0); PG8_BAR; PG8_MMA(0, 0, At, B0); PG8_MMA(0, 1, At, B1); PG8_BAR; PG8_SCHED;
;             PG8_LDA(At, 0, 1); PG8_STAGE(PG8_SB(0, 0), b2, voffB); PG8_STAGE(PG8_SB(0, 1), b2 + hstepB, voffB); PG8_STAGE(PG8_SA(0, 0), a2, voffA);
;             PG8_WAIT_V(8); PG8_WAIT_L(0); PG8_BAR; PG8_MMA(1, 0, At, B0); PG8_MMA(1, 1, At, B1); PG8_BAR; PG8_SCHED;
;             PG8_LDB(B0, 1, 0); PG8_LDB(B1, 1, 1); PG8_SCHED; PG8_LDA(At, 1, 0); PG8_STAGE(PG8_SA(0, 1), a2 + hstepA, voffA);
;             PG8_WAIT_V(8); PG8_WAIT_L(0); PG8_BAR; PG8_MMA(0, 0, At, B0); PG8_MMA(0, 1, At, B1); PG8_BAR; PG8_SCHED;
;             PG8_LDA(At, 1, 1); PG8_STAGE(PG8_SB(1, 0), b3, voffB); PG8_STAGE(PG8_SB(1, 1), b3 + hstepB, voffB); PG8_STAGE(PG8_SA(1, 0), a3, voffA);
;             PG8_WAIT_V(8); PG8_WAIT_L(0); PG8_BAR; PG8_MMA(1, 0, At, B0); PG8_MMA(1, 1, At, B1); PG8_BAR; PG8_SCHED;
.LBB0_1523:
	s_add_i32 vcc_lo, s72, 2
	s_add_u32 s70, s82, 0x100
	s_addc_u32 s71, s83, 0
	s_add_i32 s30, 0, 0x10000
	s_cmp_eq_u32 s29, s72
	s_cselect_b32 s81, s63, s71
	s_cselect_b32 s80, s62, s70
	v_add_u32_e32 v96, s30, v141
	s_cselect_b32 s73, s65, s59
	s_cselect_b32 s72, s64, s57
	s_add_i32 s31, 0, 0x14000
	ds_read_b128 v[146:149], v96
	ds_read_b128 v[150:153], v96 offset:1024
	ds_read_b128 v[154:157], v96 offset:2048
	ds_read_b128 v[158:161], v96 offset:3072
	v_add_u32_e32 v96, s31, v141
	ds_read_b128 v[162:165], v96
	ds_read_b128 v[166:169], v96 offset:1024
	ds_read_b128 v[170:173], v96 offset:2048
	ds_read_b128 v[174:177], v96 offset:3072
	v_lshl_add_u64 v[98:99], s[82:83], 0, v[136:137]
	s_add_i32 m0, s23, 0xc000
	ds_read_b128 v[178:181], v145
	ds_read_b128 v[182:185], v145 offset:1024
	ds_read_b128 v[186:189], v145 offset:2048
	ds_read_b128 v[190:193], v145 offset:3072
	ds_read_b128 v[194:197], v145 offset:4096
	ds_read_b128 v[200:203], v145 offset:5120
	ds_read_b128 v[206:209], v145 offset:6144
	ds_read_b128 v[210:213], v145 offset:7168
	global_load_lds_dwordx4 v[98:99], off
	v_lshl_add_u64 v[98:99], s[82:83], 0, v[138:139]
	s_add_i32 m0, s23, 0xe000
	s_nop 0
	global_load_lds_dwordx4 v[98:99], off
	s_waitcnt vmcnt(8)
	s_waitcnt lgkmcnt(0)
	s_barrier
	s_setprio 1
	v_mfma_f32_16x16x32_bf16 v[52:55], v[146:149], v[178:181], v[52:55]
	v_mfma_f32_16x16x32_bf16 v[52:55], v[150:153], v[182:185], v[52:55]
	v_mfma_f32_16x16x32_bf16 v[56:59], v[154:157], v[178:181], v[56:59]
	v_mfma_f32_16x16x32_bf16 v[56:59], v[158:161], v[182:185], v[56:59]
	v_mfma_f32_16x16x32_bf16 v[104:107], v[146:149], v[186:189], v[104:107]
	v_mfma_f32_16x16x32_bf16 v[104:107], v[150:153], v[190:193], v[104:107]
	v_mfma_f32_16x16x32_bf16 v[84:87], v[154:157], v[186:189], v[84:87]
	v_mfma_f32_16x16x32_bf16 v[84:87], v[158:161], v[190:193], v[84:87]
	v_mfma_f32_16x16x32_bf16 v[110:113], v[146:149], v[194:197], v[110:113]
	v_mfma_f32_16x16x32_bf16 v[110:113], v[150:153], v[200:203], v[110:113]
	v_mfma_f32_16x16x32_bf16 v[98:101], v[154:157], v[194:197], v[100:103]
	v_mfma_f32_16x16x32_bf16 v[88:91], v[146:149], v[206:209], v[88:91]
	v_mfma_f32_16x16x32_bf16 v[88:91], v[150:153], v[210:213], v[88:91]
	v_mfma_f32_16x16x32_bf16 v[80:83], v[154:157], v[206:209], v[80:83]
	v_mfma_f32_16x16x32_bf16 v[80:83], v[158:161], v[210:213], v[80:83]
	v_mfma_f32_16x16x32_bf16 v[98:101], v[158:161], v[200:203], v[98:101]
	s_setprio 0
	s_setprio 1
	v_mfma_f32_16x16x32_bf16 v[48:51], v[162:165], v[178:181], v[48:51]
	v_mfma_f32_16x16x32_bf16 v[48:51], v[166:169], v[182:185], v[48:51]
	v_mfma_f32_16x16x32_bf16 v[44:47], v[170:173], v[178:181], v[44:47]
	v_mfma_f32_16x16x32_bf16 v[44:47], v[174:177], v[182:185], v[44:47]
	v_mfma_f32_16x16x32_bf16 v[76:79], v[162:165], v[186:189], v[76:79]
	v_mfma_f32_16x16x32_bf16 v[76:79], v[166:169], v[190:193], v[76:79]
	v_mfma_f32_16x16x32_bf16 v[68:71], v[170:173], v[186:189], v[68:71]
	v_mfma_f32_16x16x32_bf16 v[68:71], v[174:177], v[190:193], v[68:71]
	v_mfma_f32_16x16x32_bf16 v[130:133], v[162:165], v[194:197], v[130:133]
	v_mfma_f32_16x16x32_bf16 v[130:133], v[166:169], v[200:203], v[130:133]
	v_mfma_f32_16x16x32_bf16 v[92:95], v[170:173], v[194:197], v[92:95]
	v_mfma_f32_16x16x32_bf16 v[92:95], v[174:177], v[200:203], v[92:95]
	v_mfma_f32_16x16x32_bf16 v[72:75], v[162:165], v[206:209], v[72:75]
	v_mfma_f32_16x16x32_bf16 v[64:67], v[170:173], v[206:209], v[64:67]
	s_setprio 2
	s_barrier
	v_mfma_f32_16x16x32_bf16 v[72:75], v[166:169], v[210:213], v[72:75]
	v_mfma_f32_16x16x32_bf16 v[64:67], v[174:177], v[210:213], v[64:67]
	s_setprio 0
	s_add_i32 s30, s30, s22
	v_lshl_add_u64 v[224:225], s[72:73], 0, v[108:109]
	s_mov_b32 m0, s30
	ds_read_b128 v[178:181], v145 offset:16384
	ds_read_b128 v[182:185], v145 offset:17408
	ds_read_b128 v[186:189], v145 offset:18432
	ds_read_b128 v[190:193], v145 offset:19456
	ds_read_b128 v[194:197], v145 offset:20480
	ds_read_b128 v[200:203], v145 offset:21504
	ds_read_b128 v[206:209], v145 offset:22528
	ds_read_b128 v[210:213], v145 offset:23552
	global_load_lds_dwordx4 v[224:225], off
	s_add_i32 m0, s30, 0x2000
	s_add_u32 s82, s72, 0x160000
	v_lshl_add_u64 v[226:227], s[72:73], 0, v[134:135]
	s_addc_u32 s83, s73, 0
	s_add_i32 s30, s31, s22
	global_load_lds_dwordx4 v[226:227], off
	v_lshl_add_u64 v[102:103], s[82:83], 0, v[108:109]
	s_mov_b32 m0, s30
	v_lshl_add_u64 v[228:229], s[80:81], 0, v[108:109]
	global_load_lds_dwordx4 v[102:103], off
	v_lshl_add_u64 v[102:103], s[82:83], 0, v[134:135]
	s_add_i32 m0, s30, 0x2000
	v_lshl_add_u64 v[230:231], s[80:81], 0, v[134:135]
	global_load_lds_dwordx4 v[102:103], off
	s_mov_b32 m0, s23
	s_nop 0
	global_load_lds_dwordx4 v[228:229], off
	s_mov_b32 m0, s24
	s_nop 0
	global_load_lds_dwordx4 v[230:231], off
	s_waitcnt vmcnt(8)
	s_waitcnt lgkmcnt(0)
	s_barrier
; #define PG8_STAGE(bufoff, gbase, voff) do { _Pragma("unroll") for (int _i = 0; _i < 2; ++_i) \
;         __builtin_amdgcn_global_load_lds((const unsigned*)((const char*)(gbase) + (voff)[_i]), (PG8_LAS unsigned*)(lds + (bufoff) + ldsw + _i * 8192), 16, 0, 0); } while (0)
; #define PG8_LDA(dst, b, h) do { _Pragma("unroll") for (int m = 0; m < 4; ++m) _Pragma("unroll") for (int k = 0; k < 2; ++k) dst[m][k] = *(const PG8_LAS bf16x8*)(lds + PG8_SA(b, h) + aoff + m * 2048 + k * 1024); } while (0)
; #define PG8_LDB(dst, b, h) do { _Pragma("unroll") for (int n = 0; n < 2; ++n) _Pragma("unroll") for (int k = 0; k < 2; ++k) dst[n][k] = *(const PG8_LAS bf16x8*)(lds + PG8_SB(b, h) + boff + n * 2048 + k * 1024); } while (0)
; #define PG8_MMA(ai, bj, At, Bt) do { __builtin_amdgcn_s_setprio(1); _Pragma("unroll") for (int m = 0; m < 4; ++m) _Pragma("unroll") for (int n = 0; n < 2; ++n) _Pragma("unroll") for (int k = 0; k < 2; ++k) \
;         acc[ai][bj][m][n] = __builtin_amdgcn_mfma_f32_16x16x32_bf16(Bt[n][k], At[m][k], acc[ai][bj][m][n], 0, 0, 0); __builtin_amdgcn_s_setprio(0); } while (0)
; template <class Epi, class Sched, bool ALIGN_EPI = true, bool SP2 = true>
; __device__ __forceinline__ void gemm_phase(PG8_LAS unsigned char* lds, const Gemm g, const Sched& S, const Epi& E, const int tid) {
;     ...
;             if constexpr (SP2) {
;             PG8_LDB(B0, 0, 0); PG8_LDB(B1, 0, 1); PG8_SCHED; PG8_LDA(At, 0, 0); PG8_STAGE(PG8_SA(1, 1), a1 + hstepA, voffA);
;             PG8_WAIT_V(8); PG8_WAIT_L(0); PG8_BAR; PG8_MMA(0, 0, At, B0); PG8_MMA(0, 1, At, B1); PG8_BAR; PG8_SCHED;
;             PG8_LDA(At, 0, 1); PG8_STAGE(PG8_SB(0, 0), b2, voffB); PG8_STAGE(PG8_SB(0, 1), b2 + hstepB, voffB); PG8_STAGE(PG8_SA(0, 0), a2, voffA);
;             PG8_WAIT_V(8); PG8_WAIT_L(0); PG8_BAR; PG8_MMA(1, 0, At, B0); PG8_MMA(1, 1, At, B1); PG8_BAR; PG8_SCHED;
;             PG8_LDB(B0, 1, 0); PG8_LDB(B1, 1, 1); PG8_SCHED; PG8_LDA(At, 1, 0); PG8_STAGE(PG8_SA(0, 1), a2 + hstepA, voffA);
;             PG8_WAIT_V(8); PG8_WAIT_L(0); PG8_BAR; PG8_MMA(0, 0, At, B0); PG8_MMA(0, 1, At, B1); PG8_BAR; PG8_SCHED;
;             PG8_LDA(At, 1, 1); PG8_STAGE(PG8_SB(1, 0), b3, voffB); PG8_STAGE(PG8_SB(1, 1), b3 + hstepB, voffB); PG8_STAGE(PG8_SA(1, 0), a3, voffA);
;             PG8_WAIT_V(8); PG8_WAIT_L(0); PG8_BAR; PG8_MMA(1, 0, At, B0); PG8_MMA(1, 1, At, B1); PG8_BAR; PG8_SCHED;
	s_setprio 1
	v_mfma_f32_16x16x32_bf16 v[126:129], v[146:149], v[178:181], v[126:129]
	v_mfma_f32_16x16x32_bf16 v[126:129], v[150:153], v[182:185], v[126:129]
	v_mfma_f32_16x16x32_bf16 v[122:125], v[154:157], v[178:181], v[122:125]
	v_mfma_f32_16x16x32_bf16 v[122:125], v[158:161], v[182:185], v[122:125]
	v_mfma_f32_16x16x32_bf16 v[60:63], v[146:149], v[186:189], v[60:63]
	v_mfma_f32_16x16x32_bf16 v[60:63], v[150:153], v[190:193], v[60:63]
	v_mfma_f32_16x16x32_bf16 v[40:43], v[154:157], v[186:189], v[40:43]
	v_mfma_f32_16x16x32_bf16 v[40:43], v[158:161], v[190:193], v[40:43]
	v_mfma_f32_16x16x32_bf16 v[28:31], v[146:149], v[194:197], v[28:31]
	v_mfma_f32_16x16x32_bf16 v[28:31], v[150:153], v[200:203], v[28:31]
	v_mfma_f32_16x16x32_bf16 v[24:27], v[154:157], v[194:197], v[24:27]
	v_mfma_f32_16x16x32_bf16 v[24:27], v[158:161], v[200:203], v[24:27]
	v_mfma_f32_16x16x32_bf16 v[12:15], v[146:149], v[206:209], v[12:15]
	v_mfma_f32_16x16x32_bf16 v[12:15], v[150:153], v[210:213], v[12:15]
	v_mfma_f32_16x16x32_bf16 v[8:11], v[154:157], v[206:209], v[8:11]
	v_mfma_f32_16x16x32_bf16 v[8:11], v[158:161], v[210:213], v[8:11]
	s_setprio 0
	s_setprio 1
	v_mfma_f32_16x16x32_bf16 v[118:121], v[162:165], v[178:181], v[118:121]
	v_mfma_f32_16x16x32_bf16 v[118:121], v[166:169], v[182:185], v[118:121]
	v_mfma_f32_16x16x32_bf16 v[114:117], v[170:173], v[178:181], v[114:117]
	v_mfma_f32_16x16x32_bf16 v[114:117], v[174:177], v[182:185], v[114:117]
	v_mfma_f32_16x16x32_bf16 v[36:39], v[162:165], v[186:189], v[36:39]
	v_mfma_f32_16x16x32_bf16 v[36:39], v[166:169], v[190:193], v[36:39]
	v_mfma_f32_16x16x32_bf16 v[32:35], v[170:173], v[186:189], v[32:35]
	v_mfma_f32_16x16x32_bf16 v[32:35], v[174:177], v[190:193], v[32:35]
	v_mfma_f32_16x16x32_bf16 v[20:23], v[162:165], v[194:197], v[20:23]
	v_mfma_f32_16x16x32_bf16 v[20:23], v[166:169], v[200:203], v[20:23]
	v_mfma_f32_16x16x32_bf16 v[16:19], v[170:173], v[194:197], v[16:19]
	v_mfma_f32_16x16x32_bf16 v[16:19], v[174:177], v[200:203], v[16:19]
	v_mfma_f32_16x16x32_bf16 v[4:7], v[162:165], v[206:209], v[4:7]
	v_mfma_f32_16x16x32_bf16 v[0:3], v[170:173], v[206:209], v[0:3]
	s_setprio 2
	s_barrier
	v_mfma_f32_16x16x32_bf16 v[4:7], v[166:169], v[210:213], v[4:7]
	v_mfma_f32_16x16x32_bf16 v[0:3], v[174:177], v[210:213], v[0:3]
	s_setprio 0
	s_add_i32 s30, 0, 0x18000
	v_add_u32_e32 v96, s30, v141
	s_add_i32 s31, 0, 0x1c000
	ds_read_b128 v[146:149], v96
	ds_read_b128 v[150:153], v96 offset:1024
	ds_read_b128 v[154:157], v96 offset:2048
	ds_read_b128 v[158:161], v96 offset:3072
	v_add_u32_e32 v96, s31, v141
	ds_read_b128 v[162:165], v96
	ds_read_b128 v[166:169], v96 offset:1024
	ds_read_b128 v[170:173], v96 offset:2048
	ds_read_b128 v[174:177], v96 offset:3072
	s_add_u32 s80, s80, 0x160000
	s_addc_u32 s81, s81, 0
	s_mov_b32 m0, s25
	v_lshl_add_u64 v[102:103], s[80:81], 0, v[108:109]
	ds_read_b128 v[178:181], v145 offset:32768
	ds_read_b128 v[182:185], v145 offset:33792
	ds_read_b128 v[186:189], v145 offset:34816
	ds_read_b128 v[190:193], v145 offset:35840
	ds_read_b128 v[194:197], v145 offset:36864
	ds_read_b128 v[200:203], v145 offset:37888
	ds_read_b128 v[206:209], v145 offset:38912
	ds_read_b128 v[210:213], v145 offset:39936
	global_load_lds_dwordx4 v[102:103], off
	v_lshl_add_u64 v[102:103], s[80:81], 0, v[134:135]
	s_mov_b32 m0, s49
	s_nop 0
	global_load_lds_dwordx4 v[102:103], off
	s_waitcnt vmcnt(8)
	s_waitcnt lgkmcnt(0)
	s_barrier
	s_setprio 1
	v_mfma_f32_16x16x32_bf16 v[52:55], v[146:149], v[178:181], v[52:55]
	v_mfma_f32_16x16x32_bf16 v[52:55], v[150:153], v[182:185], v[52:55]
	v_mfma_f32_16x16x32_bf16 v[56:59], v[154:157], v[178:181], v[56:59]
	v_mfma_f32_16x16x32_bf16 v[56:59], v[158:161], v[182:185], v[56:59]
	v_mfma_f32_16x16x32_bf16 v[102:105], v[146:149], v[186:189], v[104:107]
	v_mfma_f32_16x16x32_bf16 v[84:87], v[154:157], v[186:189], v[84:87]
	v_mfma_f32_16x16x32_bf16 v[84:87], v[158:161], v[190:193], v[84:87]
	v_mfma_f32_16x16x32_bf16 v[110:113], v[146:149], v[194:197], v[110:113]
	v_mfma_f32_16x16x32_bf16 v[110:113], v[150:153], v[200:203], v[110:113]
	v_mfma_f32_16x16x32_bf16 v[98:101], v[154:157], v[194:197], v[98:101]
	v_mfma_f32_16x16x32_bf16 v[88:91], v[146:149], v[206:209], v[88:91]
	v_mfma_f32_16x16x32_bf16 v[88:91], v[150:153], v[210:213], v[88:91]
	v_mfma_f32_16x16x32_bf16 v[80:83], v[154:157], v[206:209], v[80:83]
	v_mfma_f32_16x16x32_bf16 v[80:83], v[158:161], v[210:213], v[80:83]
	v_mfma_f32_16x16x32_bf16 v[104:107], v[150:153], v[190:193], v[102:105]
	v_mfma_f32_16x16x32_bf16 v[100:103], v[158:161], v[200:203], v[98:101]
	s_setprio 0
	s_setprio 1
	v_mfma_f32_16x16x32_bf16 v[48:51], v[162:165], v[178:181], v[48:51]
	v_mfma_f32_16x16x32_bf16 v[48:51], v[166:169], v[182:185], v[48:51]
	v_mfma_f32_16x16x32_bf16 v[44:47], v[170:173], v[178:181], v[44:47]
	v_mfma_f32_16x16x32_bf16 v[44:47], v[174:177], v[182:185], v[44:47]
	v_mfma_f32_16x16x32_bf16 v[76:79], v[162:165], v[186:189], v[76:79]
	v_mfma_f32_16x16x32_bf16 v[76:79], v[166:169], v[190:193], v[76:79]
	v_mfma_f32_16x16x32_bf16 v[68:71], v[170:173], v[186:189], v[68:71]
	v_mfma_f32_16x16x32_bf16 v[68:71], v[174:177], v[190:193], v[68:71]
	v_mfma_f32_16x16x32_bf16 v[130:133], v[162:165], v[194:197], v[130:133]
	v_mfma_f32_16x16x32_bf16 v[130:133], v[166:169], v[200:203], v[130:133]
	v_mfma_f32_16x16x32_bf16 v[92:95], v[170:173], v[194:197], v[92:95]
	v_mfma_f32_16x16x32_bf16 v[92:95], v[174:177], v[200:203], v[92:95]
	v_mfma_f32_16x16x32_bf16 v[72:75], v[162:165], v[206:209], v[72:75]
	v_mfma_f32_16x16x32_bf16 v[64:67], v[170:173], v[206:209], v[64:67]
	s_setprio 2
	s_barrier
; #define PG8_STAGE(bufoff, gbase, voff) do { _Pragma("unroll") for (int _i = 0; _i < 2; ++_i) \
;         __builtin_amdgcn_global_load_lds((const unsigned*)((const char*)(gbase) + (voff)[_i]), (PG8_LAS unsigned*)(lds + (bufoff) + ldsw + _i * 8192), 16, 0, 0); } while (0)
; #define PG8_LDA(dst, b, h) do { _Pragma("unroll") for (int m = 0; m < 4; ++m) _Pragma("unroll") for (int k = 0; k < 2; ++k) dst[m][k] = *(const PG8_LAS bf16x8*)(lds + PG8_SA(b, h) + aoff + m * 2048 + k * 1024); } while (0)
; #define PG8_WAIT_V(n) asm volatile("s_waitcnt vmcnt(" #n ")" ::: "memory")
; #define PG8_WAIT_L(n) asm volatile("s_waitcnt lgkmcnt(" #n ")" ::: "memory")
; #define PG8_BAR __builtin_amdgcn_s_barrier()
; template <class Epi, class Sched, bool ALIGN_EPI = true, bool SP2 = true>
; __device__ __forceinline__ void gemm_phase(PG8_LAS unsigned char* lds, const Gemm g, const Sched& S, const Epi& E, const int tid) {
;     ...
;         for (int t = 0; t < nt; t += 2) {
;             const bool last = (t == nt - 2);
;             const char* a1 = cA + (size_t)(t + 1) * kstep;
;             const char* a2 = last ? nA : cA + (size_t)(t + 2) * kstep; const char* b2 = last ? nB : cB + (size_t)(t + 2) * kstep;
;             const char* a3 = a2 + kstep; const char* b3 = b2 + kstep;
;             if (last && has_next) S.a_ready(nxt);
;             if constexpr (SP2) {
;             PG8_LDB(B0, 0, 0); PG8_LDB(B1, 0, 1); PG8_SCHED; PG8_LDA(At, 0, 0); PG8_STAGE(PG8_SA(1, 1), a1 + hstepA, voffA);
;             PG8_WAIT_V(8); PG8_WAIT_L(0); PG8_BAR; PG8_MMA(0, 0, At, B0); PG8_MMA(0, 1, At, B1); PG8_BAR; PG8_SCHED;
;             PG8_LDA(At, 0, 1); PG8_STAGE(PG8_SB(0, 0), b2, voffB); PG8_STAGE(PG8_SB(0, 1), b2 + hstepB, voffB); PG8_STAGE(PG8_SA(0, 0), a2, voffA);
;             PG8_WAIT_V(8); PG8_WAIT_L(0); PG8_BAR; PG8_MMA(1, 0, At, B0); PG8_MMA(1, 1, At, B1); PG8_BAR; PG8_SCHED;
;             PG8_LDB(B0, 1, 0); PG8_LDB(B1, 1, 1); PG8_SCHED; PG8_LDA(At, 1, 0); PG8_STAGE(PG8_SA(0, 1), a2 + hstepA, voffA);
;             PG8_WAIT_V(8); PG8_WAIT_L(0); PG8_BAR; PG8_MMA(0, 0, At, B0); PG8_MMA(0, 1, At, B1); PG8_BAR; PG8_SCHED;
;             PG8_LDA(At, 1, 1); PG8_STAGE(PG8_SB(1, 0), b3, voffB); PG8_STAGE(PG8_SB(1, 1), b3 + hstepB, voffB); PG8_STAGE(PG8_SA(1, 0), a3, voffA);
;             PG8_WAIT_V(8); PG8_WAIT_L(0); PG8_BAR; PG8_MMA(1, 0, At, B0); PG8_MMA(1, 1, At, B1); PG8_BAR; PG8_SCHED;
	v_mfma_f32_16x16x32_bf16 v[72:75], v[166:169], v[210:213], v[72:75]
	v_mfma_f32_16x16x32_bf16 v[64:67], v[174:177], v[210:213], v[64:67]
	s_setprio 0
	s_add_i32 s30, s30, s22
	v_lshl_add_u64 v[98:99], v[224:225], 0, s[4:5]
	s_mov_b32 m0, s30
	ds_read_b128 v[178:181], v145 offset:49152
	ds_read_b128 v[182:185], v145 offset:50176
	ds_read_b128 v[186:189], v145 offset:51200
	ds_read_b128 v[190:193], v145 offset:52224
	ds_read_b128 v[194:197], v145 offset:53248
	ds_read_b128 v[200:203], v145 offset:54272
	ds_read_b128 v[206:209], v145 offset:55296
	ds_read_b128 v[210:213], v145 offset:56320
	global_load_lds_dwordx4 v[98:99], off
	s_add_i32 m0, s30, 0x2000
	s_add_u32 s72, s72, 0x160080
	v_lshl_add_u64 v[98:99], v[226:227], 0, s[4:5]
	s_addc_u32 s73, s73, 0
	s_add_i32 s30, s31, s22
	global_load_lds_dwordx4 v[98:99], off
	v_lshl_add_u64 v[98:99], s[72:73], 0, v[108:109]
	s_mov_b32 m0, s30
	s_nop 0
	global_load_lds_dwordx4 v[98:99], off
	v_lshl_add_u64 v[98:99], s[72:73], 0, v[134:135]
	s_add_i32 m0, s30, 0x2000
	s_nop 0
	global_load_lds_dwordx4 v[98:99], off
	v_lshl_add_u64 v[98:99], v[228:229], 0, s[4:5]
	s_mov_b32 m0, s91
	s_nop 0
	global_load_lds_dwordx4 v[98:99], off
	v_lshl_add_u64 v[98:99], v[230:231], 0, s[4:5]
	s_mov_b32 m0, s86
	s_nop 0
	global_load_lds_dwordx4 v[98:99], off
	s_waitcnt vmcnt(8)
	s_waitcnt lgkmcnt(0)
	s_barrier
	s_setprio 1
	v_mfma_f32_16x16x32_bf16 v[126:129], v[146:149], v[178:181], v[126:129]
	v_mfma_f32_16x16x32_bf16 v[126:129], v[150:153], v[182:185], v[126:129]
	v_mfma_f32_16x16x32_bf16 v[122:125], v[154:157], v[178:181], v[122:125]
	v_mfma_f32_16x16x32_bf16 v[122:125], v[158:161], v[182:185], v[122:125]
	v_mfma_f32_16x16x32_bf16 v[60:63], v[146:149], v[186:189], v[60:63]
	v_mfma_f32_16x16x32_bf16 v[60:63], v[150:153], v[190:193], v[60:63]
	v_mfma_f32_16x16x32_bf16 v[40:43], v[154:157], v[186:189], v[40:43]
	v_mfma_f32_16x16x32_bf16 v[40:43], v[158:161], v[190:193], v[40:43]
	v_mfma_f32_16x16x32_bf16 v[28:31], v[146:149], v[194:197], v[28:31]
	v_mfma_f32_16x16x32_bf16 v[28:31], v[150:153], v[200:203], v[28:31]
	v_mfma_f32_16x16x32_bf16 v[24:27], v[154:157], v[194:197], v[24:27]
	v_mfma_f32_16x16x32_bf16 v[24:27], v[158:161], v[200:203], v[24:27]
	v_mfma_f32_16x16x32_bf16 v[12:15], v[146:149], v[206:209], v[12:15]
	v_mfma_f32_16x16x32_bf16 v[12:15], v[150:153], v[210:213], v[12:15]
	v_mfma_f32_16x16x32_bf16 v[8:11], v[154:157], v[206:209], v[8:11]
	v_mfma_f32_16x16x32_bf16 v[8:11], v[158:161], v[210:213], v[8:11]
	s_setprio 0
	s_setprio 1
	v_mfma_f32_16x16x32_bf16 v[118:121], v[162:165], v[178:181], v[118:121]
	v_mfma_f32_16x16x32_bf16 v[118:121], v[166:169], v[182:185], v[118:121]
	v_mfma_f32_16x16x32_bf16 v[114:117], v[170:173], v[178:181], v[114:117]
	v_mfma_f32_16x16x32_bf16 v[114:117], v[174:177], v[182:185], v[114:117]
	v_mfma_f32_16x16x32_bf16 v[36:39], v[162:165], v[186:189], v[36:39]
	v_mfma_f32_16x16x32_bf16 v[36:39], v[166:169], v[190:193], v[36:39]
	v_mfma_f32_16x16x32_bf16 v[32:35], v[170:173], v[186:189], v[32:35]
	v_mfma_f32_16x16x32_bf16 v[32:35], v[174:177], v[190:193], v[32:35]
	v_mfma_f32_16x16x32_bf16 v[20:23], v[162:165], v[194:197], v[20:23]
	v_mfma_f32_16x16x32_bf16 v[20:23], v[166:169], v[200:203], v[20:23]
	v_mfma_f32_16x16x32_bf16 v[16:19], v[170:173], v[194:197], v[16:19]
	v_mfma_f32_16x16x32_bf16 v[16:19], v[174:177], v[200:203], v[16:19]
	v_mfma_f32_16x16x32_bf16 v[4:7], v[162:165], v[206:209], v[4:7]
	v_mfma_f32_16x16x32_bf16 v[0:3], v[170:173], v[206:209], v[0:3]
	s_setprio 2
	s_barrier
	v_mfma_f32_16x16x32_bf16 v[4:7], v[166:169], v[210:213], v[4:7]
	v_mfma_f32_16x16x32_bf16 v[0:3], v[174:177], v[210:213], v[0:3]
	s_setprio 0
	s_add_u32 s57, s57, 0x100
	s_addc_u32 s59, s59, 0
	s_cmp_ge_i32 vcc_lo, s53
	s_mov_b64 s[82:83], s[70:71]
	s_mov_b32 s72, vcc_lo
	s_cbranch_scc0 .LBB0_1523
